# GEMM main loops: duplicate lgkmcnt(0) waits dropped and M0 writes hoisted above the address add so the s_nop pads disappear
# speedup vs baseline: 1.0334x; 1.0086x over previous
; #define PG8_STAGE(bufoff, gbase, voff) do { _Pragma("unroll") for (int _i = 0; _i < 2; ++_i) \
;         __builtin_amdgcn_global_load_lds((const unsigned*)((const char*)(gbase) + (voff)[_i]), (LAS unsigned*)(lds + (bufoff) + ldsw + _i * 8192), 16, 0, 0); } while (0)
; #define PG8_LDA(dst, b, h) do { _Pragma("unroll") for (int m = 0; m < 4; ++m) _Pragma("unroll") for (int k = 0; k < 2; ++k) dst[m][k] = *(const LAS bf16x8*)(lds + PG8_SA(b, h) + aoff + m * 2048 + k * 1024); } while (0)
; #define PG8_LDB(dst, b, h) do { _Pragma("unroll") for (int n = 0; n < 2; ++n) _Pragma("unroll") for (int k = 0; k < 2; ++k) dst[n][k] = *(const LAS bf16x8*)(lds + PG8_SB(b, h) + boff + n * 2048 + k * 1024); } while (0)
; #define PG8_MMA(ai, bj, At, Bt) do { __builtin_amdgcn_s_setprio(1); _Pragma("unroll") for (int m = 0; m < 4; ++m) _Pragma("unroll") for (int n = 0; n < 2; ++n) _Pragma("unroll") for (int k = 0; k < 2; ++k) \
;         acc[ai][bj][m][n] = __builtin_amdgcn_mfma_f32_16x16x32_bf16(Bt[n][k], At[m][k], acc[ai][bj][m][n], 0, 0, 0); __builtin_amdgcn_s_setprio(0); } while (0)
; #define PG8_WAIT_L(n) asm volatile("s_waitcnt lgkmcnt(" #n ")" ::: "memory")
; #define PG8_BAR __builtin_amdgcn_s_barrier()
; #define PG8_SCHED __builtin_amdgcn_sched_barrier(0)
; template <class Epi>
; __device__ __forceinline__ void gemm_phase(LAS unsigned char* lds, const Gemm g, const Epi& E) {
;     ...
;         for (int t = 0; t < nt; t += 2) {
;             const bool last = (t == nt - 2);
;             const char* a1 = cA + (size_t)(t + 1) * kstep;
;             const char* a2 = last ? nA : cA + (size_t)(t + 2) * kstep; const char* b2 = last ? nB : cB + (size_t)(t + 2) * kstep;
;             const char* a3 = a2 + kstep; const char* b3 = b2 + kstep;
;             PG8_LDB(B0, 0, 0); PG8_SCHED; PG8_LDA(At, 0, 0); PG8_STAGE(PG8_SA(1, 1), a1 + hstep, voffA);
;             PG8_WAIT_L(8); PG8_BAR; PG8_WAIT_L(0); PG8_MMA(0, 0, At, B0); PG8_BAR; PG8_SCHED;
;             PG8_LDB(B1, 0, 1); PG8_STAGE(PG8_SB(0, 0), b2, voffB);
;             PG8_BAR; PG8_WAIT_L(0); PG8_MMA(0, 1, At, B1); PG8_BAR;
;             PG8_LDA(At, 0, 1); PG8_STAGE(PG8_SA(0, 0), a2, voffA);
;             PG8_BAR; PG8_WAIT_L(0); PG8_MMA(1, 0, At, B0); PG8_BAR; PG8_SCHED;
;             PG8_STAGE(PG8_SB(0, 1), b2 + hstep, voffB);
.LBB0_30:
	s_add_u32 s28, s26, 0xfff80080
	s_addc_u32 s29, s27, -1
	s_add_i32 s34, 0, 0x10000
	v_add_u32_e32 v143, s34, v141
	ds_read_b128 v[144:147], v143
	ds_read_b128 v[148:151], v143 offset:1024
	ds_read_b128 v[152:155], v143 offset:2048
	ds_read_b128 v[156:159], v143 offset:3072
	s_cmp_eq_u32 s89, 28
	s_cselect_b32 s37, s45, s29
	s_cselect_b32 s36, s78, s28
	s_cselect_b32 s29, s43, s83
	s_cselect_b32 s28, s79, s82
	v_lshl_add_u64 v[192:193], s[26:27], 0, v[136:137]
	s_add_i32 m0, s39, 0xc000
	ds_read_b128 v[160:163], v142
	ds_read_b128 v[164:167], v142 offset:1024
	ds_read_b128 v[168:171], v142 offset:2048
	ds_read_b128 v[172:175], v142 offset:3072
	ds_read_b128 v[176:179], v142 offset:4096
	ds_read_b128 v[180:183], v142 offset:5120
	ds_read_b128 v[184:187], v142 offset:6144
	ds_read_b128 v[188:191], v142 offset:7168
	global_load_lds_dwordx4 v[192:193], off
	s_add_i32 m0, s39, 0xe000
	v_lshl_add_u64 v[192:193], s[26:27], 0, v[138:139]
	global_load_lds_dwordx4 v[192:193], off
	s_waitcnt lgkmcnt(8)
	s_barrier
	s_waitcnt lgkmcnt(0)
	s_setprio 1
	v_mfma_f32_16x16x32_bf16 v[124:127], v[144:147], v[160:163], v[124:127]
	v_mfma_f32_16x16x32_bf16 v[116:119], v[152:155], v[160:163], v[116:119]
	v_mfma_f32_16x16x32_bf16 v[108:111], v[144:147], v[168:171], v[108:111]
	v_mfma_f32_16x16x32_bf16 v[100:103], v[152:155], v[168:171], v[100:103]
	v_mfma_f32_16x16x32_bf16 v[92:95], v[144:147], v[176:179], v[92:95]
	v_mfma_f32_16x16x32_bf16 v[84:87], v[152:155], v[176:179], v[84:87]
	v_mfma_f32_16x16x32_bf16 v[76:79], v[144:147], v[184:187], v[76:79]
	v_mfma_f32_16x16x32_bf16 v[68:71], v[152:155], v[184:187], v[68:71]
	v_mfma_f32_16x16x32_bf16 v[124:127], v[148:151], v[164:167], v[124:127]
	v_mfma_f32_16x16x32_bf16 v[116:119], v[156:159], v[164:167], v[116:119]
	v_mfma_f32_16x16x32_bf16 v[108:111], v[148:151], v[172:175], v[108:111]
	v_mfma_f32_16x16x32_bf16 v[100:103], v[156:159], v[172:175], v[100:103]
	v_mfma_f32_16x16x32_bf16 v[92:95], v[148:151], v[180:183], v[92:95]
	v_mfma_f32_16x16x32_bf16 v[84:87], v[156:159], v[180:183], v[84:87]
	v_mfma_f32_16x16x32_bf16 v[76:79], v[148:151], v[188:191], v[76:79]
	v_mfma_f32_16x16x32_bf16 v[68:71], v[156:159], v[188:191], v[68:71]
	s_setprio 0
	s_barrier
	s_add_i32 s46, 0, 0x14000
	s_add_i32 s34, s34, s31
	v_add_u32_e32 v143, s46, v141
	v_lshl_add_u64 v[220:221], s[28:29], 0, v[132:133]
	s_mov_b32 m0, s34
	ds_read_b128 v[192:195], v143
	ds_read_b128 v[196:199], v143 offset:1024
	ds_read_b128 v[200:203], v143 offset:2048
	ds_read_b128 v[204:207], v143 offset:3072
	global_load_lds_dwordx4 v[220:221], off
	s_add_i32 m0, s34, 0x2000
	v_lshl_add_u64 v[228:229], s[28:29], 0, v[128:129]
	global_load_lds_dwordx4 v[228:229], off
	s_barrier
	s_waitcnt lgkmcnt(0)
	s_setprio 1
	v_mfma_f32_16x16x32_bf16 v[120:123], v[192:195], v[160:163], v[120:123]
	v_mfma_f32_16x16x32_bf16 v[112:115], v[200:203], v[160:163], v[112:115]
	v_mfma_f32_16x16x32_bf16 v[104:107], v[192:195], v[168:171], v[104:107]
	v_mfma_f32_16x16x32_bf16 v[96:99], v[200:203], v[168:171], v[96:99]
	v_mfma_f32_16x16x32_bf16 v[88:91], v[192:195], v[176:179], v[88:91]
	v_mfma_f32_16x16x32_bf16 v[80:83], v[200:203], v[176:179], v[80:83]
	v_mfma_f32_16x16x32_bf16 v[72:75], v[192:195], v[184:187], v[72:75]
	v_mfma_f32_16x16x32_bf16 v[64:67], v[200:203], v[184:187], v[64:67]
	v_mfma_f32_16x16x32_bf16 v[120:123], v[196:199], v[164:167], v[120:123]
	v_mfma_f32_16x16x32_bf16 v[112:115], v[204:207], v[164:167], v[112:115]
	v_mfma_f32_16x16x32_bf16 v[104:107], v[196:199], v[172:175], v[104:107]
	v_mfma_f32_16x16x32_bf16 v[96:99], v[204:207], v[172:175], v[96:99]
	v_mfma_f32_16x16x32_bf16 v[88:91], v[196:199], v[180:183], v[88:91]
	v_mfma_f32_16x16x32_bf16 v[80:83], v[204:207], v[180:183], v[80:83]
	v_mfma_f32_16x16x32_bf16 v[72:75], v[196:199], v[188:191], v[72:75]
	v_mfma_f32_16x16x32_bf16 v[64:67], v[204:207], v[188:191], v[64:67]
	s_setprio 0
	s_mov_b32 m0, s39
	v_lshl_add_u64 v[230:231], s[36:37], 0, v[134:135]
	s_barrier
	ds_read_b128 v[160:163], v142 offset:16384
	ds_read_b128 v[164:167], v142 offset:17408
	ds_read_b128 v[168:171], v142 offset:18432
	ds_read_b128 v[172:175], v142 offset:19456
	ds_read_b128 v[176:179], v142 offset:20480
	ds_read_b128 v[180:183], v142 offset:21504
	ds_read_b128 v[184:187], v142 offset:22528
	ds_read_b128 v[188:191], v142 offset:23552
	global_load_lds_dwordx4 v[230:231], off
	s_mov_b32 m0, s68
	v_lshl_add_u64 v[232:233], s[36:37], 0, v[130:131]
	global_load_lds_dwordx4 v[232:233], off
	s_barrier
	s_waitcnt lgkmcnt(0)
	s_setprio 1
	v_mfma_f32_16x16x32_bf16 v[60:63], v[144:147], v[160:163], v[60:63]
	v_mfma_f32_16x16x32_bf16 v[52:55], v[152:155], v[160:163], v[52:55]
	v_mfma_f32_16x16x32_bf16 v[44:47], v[144:147], v[168:171], v[44:47]
	v_mfma_f32_16x16x32_bf16 v[36:39], v[152:155], v[168:171], v[36:39]
	v_mfma_f32_16x16x32_bf16 v[28:31], v[144:147], v[176:179], v[28:31]
	v_mfma_f32_16x16x32_bf16 v[20:23], v[152:155], v[176:179], v[20:23]
	v_mfma_f32_16x16x32_bf16 v[12:15], v[144:147], v[184:187], v[12:15]
	v_mfma_f32_16x16x32_bf16 v[4:7], v[152:155], v[184:187], v[4:7]
	v_mfma_f32_16x16x32_bf16 v[60:63], v[148:151], v[164:167], v[60:63]
	v_mfma_f32_16x16x32_bf16 v[52:55], v[156:159], v[164:167], v[52:55]
	v_mfma_f32_16x16x32_bf16 v[44:47], v[148:151], v[172:175], v[44:47]
	v_mfma_f32_16x16x32_bf16 v[36:39], v[156:159], v[172:175], v[36:39]
	v_mfma_f32_16x16x32_bf16 v[28:31], v[148:151], v[180:183], v[28:31]
	v_mfma_f32_16x16x32_bf16 v[20:23], v[156:159], v[180:183], v[20:23]
	v_mfma_f32_16x16x32_bf16 v[12:15], v[148:151], v[188:191], v[12:15]
	v_mfma_f32_16x16x32_bf16 v[4:7], v[156:159], v[188:191], v[4:7]
	s_setprio 0
	s_barrier
; #define PG8_STAGE(bufoff, gbase, voff) do { _Pragma("unroll") for (int _i = 0; _i < 2; ++_i) \
;         __builtin_amdgcn_global_load_lds((const unsigned*)((const char*)(gbase) + (voff)[_i]), (LAS unsigned*)(lds + (bufoff) + ldsw + _i * 8192), 16, 0, 0); } while (0)
; #define PG8_LDA(dst, b, h) do { _Pragma("unroll") for (int m = 0; m < 4; ++m) _Pragma("unroll") for (int k = 0; k < 2; ++k) dst[m][k] = *(const LAS bf16x8*)(lds + PG8_SA(b, h) + aoff + m * 2048 + k * 1024); } while (0)
; #define PG8_LDB(dst, b, h) do { _Pragma("unroll") for (int n = 0; n < 2; ++n) _Pragma("unroll") for (int k = 0; k < 2; ++k) dst[n][k] = *(const LAS bf16x8*)(lds + PG8_SB(b, h) + boff + n * 2048 + k * 1024); } while (0)
; #define PG8_MMA(ai, bj, At, Bt) do { __builtin_amdgcn_s_setprio(1); _Pragma("unroll") for (int m = 0; m < 4; ++m) _Pragma("unroll") for (int n = 0; n < 2; ++n) _Pragma("unroll") for (int k = 0; k < 2; ++k) \
;         acc[ai][bj][m][n] = __builtin_amdgcn_mfma_f32_16x16x32_bf16(Bt[n][k], At[m][k], acc[ai][bj][m][n], 0, 0, 0); __builtin_amdgcn_s_setprio(0); } while (0)
; #define PG8_WAIT_V(n) asm volatile("s_waitcnt vmcnt(" #n ")" ::: "memory")
; #define PG8_WAIT_L(n) asm volatile("s_waitcnt lgkmcnt(" #n ")" ::: "memory")
; #define PG8_BAR __builtin_amdgcn_s_barrier()
; #define PG8_SCHED __builtin_amdgcn_sched_barrier(0)
; template <class Epi>
; __device__ __forceinline__ void gemm_phase(LAS unsigned char* lds, const Gemm g, const Epi& E) {
;     ...
;             PG8_STAGE(PG8_SB(0, 1), b2 + hstep, voffB);
;             PG8_WAIT_V(6); PG8_BAR; PG8_MMA(1, 1, At, B1); PG8_BAR;
;             PG8_LDB(B0, 1, 0); PG8_SCHED; PG8_LDA(At, 1, 0); PG8_STAGE(PG8_SA(0, 1), a2 + hstep, voffA);
;             PG8_WAIT_L(8); PG8_BAR; PG8_WAIT_L(0); PG8_MMA(0, 0, At, B0); PG8_BAR; PG8_SCHED;
;             PG8_LDB(B1, 1, 1); PG8_STAGE(PG8_SB(1, 0), b3, voffB);
;             PG8_BAR; PG8_WAIT_L(0); PG8_MMA(0, 1, At, B1); PG8_BAR;
;             PG8_LDA(At, 1, 1); PG8_STAGE(PG8_SA(1, 0), a3, voffA);
;             PG8_BAR; PG8_WAIT_L(0); PG8_MMA(1, 0, At, B0); PG8_BAR; PG8_SCHED;
;             PG8_STAGE(PG8_SB(1, 1), b3 + hstep, voffB);
	s_add_u32 s34, s28, 0x80000
	s_addc_u32 s35, s29, 0
	s_add_i32 s46, s46, s31
	s_mov_b32 m0, s46
	v_lshl_add_u64 v[144:145], s[34:35], 0, v[132:133]
	global_load_lds_dwordx4 v[144:145], off
	s_add_i32 m0, s46, 0x2000
	v_lshl_add_u64 v[144:145], s[34:35], 0, v[128:129]
	global_load_lds_dwordx4 v[144:145], off
	s_waitcnt vmcnt(6)
	s_barrier
	s_setprio 1
	v_mfma_f32_16x16x32_bf16 v[56:59], v[192:195], v[160:163], v[56:59]
	v_mfma_f32_16x16x32_bf16 v[48:51], v[200:203], v[160:163], v[48:51]
	v_mfma_f32_16x16x32_bf16 v[40:43], v[192:195], v[168:171], v[40:43]
	v_mfma_f32_16x16x32_bf16 v[32:35], v[200:203], v[168:171], v[32:35]
	v_mfma_f32_16x16x32_bf16 v[24:27], v[192:195], v[176:179], v[24:27]
	v_mfma_f32_16x16x32_bf16 v[16:19], v[200:203], v[176:179], v[16:19]
	v_mfma_f32_16x16x32_bf16 v[8:11], v[192:195], v[184:187], v[8:11]
	v_mfma_f32_16x16x32_bf16 v[0:3], v[200:203], v[184:187], v[0:3]
	v_mfma_f32_16x16x32_bf16 v[56:59], v[196:199], v[164:167], v[56:59]
	v_mfma_f32_16x16x32_bf16 v[48:51], v[204:207], v[164:167], v[48:51]
	v_mfma_f32_16x16x32_bf16 v[40:43], v[196:199], v[172:175], v[40:43]
	v_mfma_f32_16x16x32_bf16 v[32:35], v[204:207], v[172:175], v[32:35]
	v_mfma_f32_16x16x32_bf16 v[24:27], v[196:199], v[180:183], v[24:27]
	v_mfma_f32_16x16x32_bf16 v[16:19], v[204:207], v[180:183], v[16:19]
	v_mfma_f32_16x16x32_bf16 v[8:11], v[196:199], v[188:191], v[8:11]
	v_mfma_f32_16x16x32_bf16 v[0:3], v[204:207], v[188:191], v[0:3]
	s_setprio 0
	s_add_i32 s46, 0, 0x18000
	v_add_u32_e32 v143, s46, v141
	s_barrier
	ds_read_b128 v[144:147], v143
	ds_read_b128 v[148:151], v143 offset:1024
	ds_read_b128 v[152:155], v143 offset:2048
	ds_read_b128 v[156:159], v143 offset:3072
	s_add_u32 s34, s36, 0x80000
	s_addc_u32 s35, s37, 0
	s_mov_b32 m0, s69
	v_lshl_add_u64 v[192:193], s[34:35], 0, v[134:135]
	ds_read_b128 v[160:163], v142 offset:32768
	ds_read_b128 v[164:167], v142 offset:33792
	ds_read_b128 v[168:171], v142 offset:34816
	ds_read_b128 v[172:175], v142 offset:35840
	ds_read_b128 v[176:179], v142 offset:36864
	ds_read_b128 v[180:183], v142 offset:37888
	ds_read_b128 v[184:187], v142 offset:38912
	ds_read_b128 v[188:191], v142 offset:39936
	global_load_lds_dwordx4 v[192:193], off
	s_mov_b32 m0, s70
	v_lshl_add_u64 v[192:193], s[34:35], 0, v[130:131]
	global_load_lds_dwordx4 v[192:193], off
	s_waitcnt lgkmcnt(8)
	s_barrier
	s_waitcnt lgkmcnt(0)
	s_setprio 1
	v_mfma_f32_16x16x32_bf16 v[124:127], v[144:147], v[160:163], v[124:127]
	v_mfma_f32_16x16x32_bf16 v[116:119], v[152:155], v[160:163], v[116:119]
	v_mfma_f32_16x16x32_bf16 v[108:111], v[144:147], v[168:171], v[108:111]
	v_mfma_f32_16x16x32_bf16 v[100:103], v[152:155], v[168:171], v[100:103]
	v_mfma_f32_16x16x32_bf16 v[92:95], v[144:147], v[176:179], v[92:95]
	v_mfma_f32_16x16x32_bf16 v[84:87], v[152:155], v[176:179], v[84:87]
	v_mfma_f32_16x16x32_bf16 v[76:79], v[144:147], v[184:187], v[76:79]
	v_mfma_f32_16x16x32_bf16 v[68:71], v[152:155], v[184:187], v[68:71]
	v_mfma_f32_16x16x32_bf16 v[124:127], v[148:151], v[164:167], v[124:127]
	v_mfma_f32_16x16x32_bf16 v[116:119], v[156:159], v[164:167], v[116:119]
	v_mfma_f32_16x16x32_bf16 v[108:111], v[148:151], v[172:175], v[108:111]
	v_mfma_f32_16x16x32_bf16 v[100:103], v[156:159], v[172:175], v[100:103]
	v_mfma_f32_16x16x32_bf16 v[92:95], v[148:151], v[180:183], v[92:95]
	v_mfma_f32_16x16x32_bf16 v[84:87], v[156:159], v[180:183], v[84:87]
	v_mfma_f32_16x16x32_bf16 v[76:79], v[148:151], v[188:191], v[76:79]
	v_mfma_f32_16x16x32_bf16 v[68:71], v[156:159], v[188:191], v[68:71]
	s_setprio 0
	s_barrier
	s_add_i32 s34, 0, 0x1c000
	s_add_i32 s35, s46, s31
	v_add_u32_e32 v143, s34, v141
	v_lshl_add_u64 v[220:221], v[220:221], 0, s[20:21]
	s_mov_b32 m0, s35
	ds_read_b128 v[192:195], v143
	ds_read_b128 v[196:199], v143 offset:1024
	ds_read_b128 v[200:203], v143 offset:2048
	ds_read_b128 v[204:207], v143 offset:3072
	global_load_lds_dwordx4 v[220:221], off
	s_add_i32 m0, s35, 0x2000
	v_lshl_add_u64 v[220:221], v[228:229], 0, s[20:21]
	global_load_lds_dwordx4 v[220:221], off
	s_barrier
	s_waitcnt lgkmcnt(0)
	s_setprio 1
	v_mfma_f32_16x16x32_bf16 v[120:123], v[192:195], v[160:163], v[120:123]
	v_mfma_f32_16x16x32_bf16 v[112:115], v[200:203], v[160:163], v[112:115]
	v_mfma_f32_16x16x32_bf16 v[104:107], v[192:195], v[168:171], v[104:107]
	v_mfma_f32_16x16x32_bf16 v[96:99], v[200:203], v[168:171], v[96:99]
	v_mfma_f32_16x16x32_bf16 v[88:91], v[192:195], v[176:179], v[88:91]
	v_mfma_f32_16x16x32_bf16 v[80:83], v[200:203], v[176:179], v[80:83]
	v_mfma_f32_16x16x32_bf16 v[72:75], v[192:195], v[184:187], v[72:75]
	v_mfma_f32_16x16x32_bf16 v[64:67], v[200:203], v[184:187], v[64:67]
	v_mfma_f32_16x16x32_bf16 v[120:123], v[196:199], v[164:167], v[120:123]
	v_mfma_f32_16x16x32_bf16 v[112:115], v[204:207], v[164:167], v[112:115]
	v_mfma_f32_16x16x32_bf16 v[104:107], v[196:199], v[172:175], v[104:107]
	v_mfma_f32_16x16x32_bf16 v[96:99], v[204:207], v[172:175], v[96:99]
	v_mfma_f32_16x16x32_bf16 v[88:91], v[196:199], v[180:183], v[88:91]
	v_mfma_f32_16x16x32_bf16 v[80:83], v[204:207], v[180:183], v[80:83]
	v_mfma_f32_16x16x32_bf16 v[72:75], v[196:199], v[188:191], v[72:75]
	v_mfma_f32_16x16x32_bf16 v[64:67], v[204:207], v[188:191], v[64:67]
	s_setprio 0
	s_mov_b32 m0, s2
	v_lshl_add_u64 v[220:221], v[230:231], 0, s[20:21]
	s_barrier
	ds_read_b128 v[160:163], v142 offset:49152
	ds_read_b128 v[164:167], v142 offset:50176
	ds_read_b128 v[168:171], v142 offset:51200
	ds_read_b128 v[172:175], v142 offset:52224
	ds_read_b128 v[176:179], v142 offset:53248
	ds_read_b128 v[180:183], v142 offset:54272
	ds_read_b128 v[184:187], v142 offset:55296
	ds_read_b128 v[188:191], v142 offset:56320
	global_load_lds_dwordx4 v[220:221], off
	s_mov_b32 m0, s71
	v_lshl_add_u64 v[220:221], v[232:233], 0, s[20:21]
	global_load_lds_dwordx4 v[220:221], off
	s_barrier
; __device__ __forceinline__ u32x4 pack8u(f32x4 a, f32x4 b) { u32x4 w = {cvt_pk_bf16(a[0], a[1]), cvt_pk_bf16(a[2], a[3]), cvt_pk_bf16(b[0], b[1]), cvt_pk_bf16(b[2], b[3])}; return w; }
; __device__ __forceinline__ float siluf_(float x) { return x * __builtin_amdgcn_rcpf(1.0f + __expf(-x)); }
; #define PG8_MMA(ai, bj, At, Bt) do { __builtin_amdgcn_s_setprio(1); _Pragma("unroll") for (int m = 0; m < 4; ++m) _Pragma("unroll") for (int n = 0; n < 2; ++n) _Pragma("unroll") for (int k = 0; k < 2; ++k) \
;         acc[ai][bj][m][n] = __builtin_amdgcn_mfma_f32_16x16x32_bf16(Bt[n][k], At[m][k], acc[ai][bj][m][n], 0, 0, 0); __builtin_amdgcn_s_setprio(0); } while (0)
; #define PG8_WAIT_V(n) asm volatile("s_waitcnt vmcnt(" #n ")" ::: "memory")
; #define PG8_BAR __builtin_amdgcn_s_barrier()
; template <class Epi>
; __device__ __forceinline__ void gemm_phase(LAS unsigned char* lds, const Gemm g, const Epi& E) {
;     ...
;             PG8_WAIT_V(6); PG8_BAR; PG8_MMA(1, 1, At, B1); PG8_BAR;
;     __device__ __forceinline__ void operator()(const AccT& acc, const Unit& u, int wr, int wc, int fr, int fq) const {
; #pragma unroll
;         for (int ai = 0; ai < 2; ++ai)
; #pragma unroll
;             for (int m = 0; m < 4; ++m) {
;                 const int row = u.pm * 256 + ai * 128 + wr * 64 + m * 16 + fr;
;                 f32x4 o0, o1;
; #pragma unroll
;                 for (int j = 0; j < 4; ++j) { o0[j] = siluf_(acc[ai][0][m][0][j]) * acc[ai][1][m][0][j]; o1[j] = siluf_(acc[ai][0][m][1][j]) * acc[ai][1][m][1][j]; }
;                 *(u32x4*)(ACT + (size_t)row * DFF + u.pn * 128 + wc * 32 + fq * 8) = pack8u(o0, o1);
;             }
	s_waitcnt lgkmcnt(0)
	s_setprio 1
	v_mfma_f32_16x16x32_bf16 v[60:63], v[144:147], v[160:163], v[60:63]
	v_mfma_f32_16x16x32_bf16 v[52:55], v[152:155], v[160:163], v[52:55]
	v_mfma_f32_16x16x32_bf16 v[44:47], v[144:147], v[168:171], v[44:47]
	v_mfma_f32_16x16x32_bf16 v[36:39], v[152:155], v[168:171], v[36:39]
	v_mfma_f32_16x16x32_bf16 v[28:31], v[144:147], v[176:179], v[28:31]
	v_mfma_f32_16x16x32_bf16 v[20:23], v[152:155], v[176:179], v[20:23]
	v_mfma_f32_16x16x32_bf16 v[12:15], v[144:147], v[184:187], v[12:15]
	v_mfma_f32_16x16x32_bf16 v[4:7], v[152:155], v[184:187], v[4:7]
	v_mfma_f32_16x16x32_bf16 v[60:63], v[148:151], v[164:167], v[60:63]
	v_mfma_f32_16x16x32_bf16 v[52:55], v[156:159], v[164:167], v[52:55]
	v_mfma_f32_16x16x32_bf16 v[44:47], v[148:151], v[172:175], v[44:47]
	v_mfma_f32_16x16x32_bf16 v[36:39], v[156:159], v[172:175], v[36:39]
	v_mfma_f32_16x16x32_bf16 v[28:31], v[148:151], v[180:183], v[28:31]
	v_mfma_f32_16x16x32_bf16 v[20:23], v[156:159], v[180:183], v[20:23]
	v_mfma_f32_16x16x32_bf16 v[12:15], v[148:151], v[188:191], v[12:15]
	v_mfma_f32_16x16x32_bf16 v[4:7], v[156:159], v[188:191], v[4:7]
	s_setprio 0
	s_barrier
	s_add_u32 s28, s28, 0x80080
	s_addc_u32 s29, s29, 0
	s_add_i32 s34, s34, s31
	s_mov_b32 m0, s34
	v_lshl_add_u64 v[144:145], s[28:29], 0, v[132:133]
	global_load_lds_dwordx4 v[144:145], off
	s_add_i32 m0, s34, 0x2000
	v_lshl_add_u64 v[144:145], s[28:29], 0, v[128:129]
	global_load_lds_dwordx4 v[144:145], off
	s_waitcnt vmcnt(6)
	s_barrier
	s_setprio 1
	v_mfma_f32_16x16x32_bf16 v[56:59], v[192:195], v[160:163], v[56:59]
	v_mfma_f32_16x16x32_bf16 v[48:51], v[200:203], v[160:163], v[48:51]
	v_mfma_f32_16x16x32_bf16 v[40:43], v[192:195], v[168:171], v[40:43]
	v_mfma_f32_16x16x32_bf16 v[32:35], v[200:203], v[168:171], v[32:35]
	v_mfma_f32_16x16x32_bf16 v[24:27], v[192:195], v[176:179], v[24:27]
	v_mfma_f32_16x16x32_bf16 v[16:19], v[200:203], v[176:179], v[16:19]
	v_mfma_f32_16x16x32_bf16 v[8:11], v[192:195], v[184:187], v[8:11]
	v_mfma_f32_16x16x32_bf16 v[0:3], v[200:203], v[184:187], v[0:3]
	v_mfma_f32_16x16x32_bf16 v[56:59], v[196:199], v[164:167], v[56:59]
	v_mfma_f32_16x16x32_bf16 v[48:51], v[204:207], v[164:167], v[48:51]
	v_mfma_f32_16x16x32_bf16 v[40:43], v[196:199], v[172:175], v[40:43]
	v_mfma_f32_16x16x32_bf16 v[32:35], v[204:207], v[172:175], v[32:35]
	v_mfma_f32_16x16x32_bf16 v[24:27], v[196:199], v[180:183], v[24:27]
	v_mfma_f32_16x16x32_bf16 v[16:19], v[204:207], v[180:183], v[16:19]
	v_mfma_f32_16x16x32_bf16 v[8:11], v[196:199], v[188:191], v[8:11]
	v_mfma_f32_16x16x32_bf16 v[0:3], v[204:207], v[188:191], v[0:3]
	s_setprio 0
	s_add_i32 s89, s89, 2
	s_add_u32 s26, s26, 0x100
	s_addc_u32 s27, s27, 0
	s_add_u32 s82, s82, 0x100
	s_addc_u32 s83, s83, 0
	s_cmp_gt_u32 s89, 29
	s_barrier
	s_cbranch_scc0 .LBB0_30
	v_mul_f32_e32 v145, 0xbfb8aa3b, v116
	v_exp_f32_e32 v145, v145
	v_mul_f32_e32 v144, 0xbfb8aa3b, v124
	v_exp_f32_e32 v144, v144
	v_readlane_b32 s28, v252, 37
	v_add_f32_e32 v145, 1.0, v145
	v_rcp_f32_e32 v146, v145
	v_mul_f32_e32 v145, 0xbfb8aa3b, v125
	v_exp_f32_e32 v145, v145
	v_add_f32_e32 v144, 1.0, v144
	v_rcp_f32_e32 v144, v144
	s_lshl_b32 s26, s76, 7
	v_add_f32_e32 v145, 1.0, v145
	v_rcp_f32_e32 v145, v145
	v_readlane_b32 s29, v252, 38
	v_lshl_add_u32 v143, s88, 8, v140
	s_ashr_i32 s27, s26, 31
	v_pk_mul_f32 v[124:125], v[124:125], v[144:145]
	s_movk_i32 s34, 0x2c00
	v_pk_mul_f32 v[120:121], v[124:125], v[120:121]
	v_mul_f32_e32 v124, 0xbfb8aa3b, v117
	v_exp_f32_e32 v124, v124
	s_lshl_b64 s[88:89], s[26:27], 1
	s_and_b64 vcc, exec, s[40:41]
	s_mov_b32 s76, s42
	v_add_f32_e32 v124, 1.0, v124
	v_rcp_f32_e32 v147, v124
	s_nop 0
	v_pk_mul_f32 v[116:117], v[116:117], v[146:147]
	s_nop 0
	v_pk_mul_f32 v[112:113], v[116:117], v[112:113]
	v_mul_f32_e32 v117, 0xbfb8aa3b, v118
	v_exp_f32_e32 v117, v117
	v_mul_f32_e32 v116, 0xbfb8aa3b, v126
	v_exp_f32_e32 v116, v116
	v_add_f32_e32 v117, 1.0, v117
	v_rcp_f32_e32 v124, v117
	v_mul_f32_e32 v117, 0xbfb8aa3b, v127
	v_exp_f32_e32 v117, v117
	v_add_f32_e32 v116, 1.0, v116
	v_rcp_f32_e32 v116, v116
	v_add_f32_e32 v117, 1.0, v117
	v_rcp_f32_e32 v117, v117
	s_nop 0
	v_pk_mul_f32 v[116:117], v[126:127], v[116:117]
	s_nop 0
	v_pk_mul_f32 v[116:117], v[116:117], v[122:123]
	v_mul_f32_e32 v122, 0xbfb8aa3b, v119
	v_exp_f32_e32 v122, v122
	s_nop 0
	v_add_f32_e32 v122, 1.0, v122
	v_rcp_f32_e32 v125, v122
	s_nop 0
	v_pk_mul_f32 v[118:119], v[118:119], v[124:125]
	s_nop 0
	v_pk_mul_f32 v[118:119], v[118:119], v[114:115]
	v_cvt_pk_bf16_f32 v115, v116, v117
	v_cvt_pk_bf16_f32 v116, v112, v113
	v_mov_b64_e32 v[112:113], s[28:29]
	v_cvt_pk_bf16_f32 v117, v118, v119
	v_mad_i64_i32 v[118:119], s[28:29], v143, s34, v[112:113]
	v_lshl_add_u64 v[118:119], v[118:119], 0, s[88:89]
	s_mov_b64 s[28:29], s[90:91]
	v_lshl_add_u64 v[118:119], v[118:119], 0, s[28:29]
	v_cvt_pk_bf16_f32 v114, v120, v121
	v_lshl_add_u64 v[118:119], v[118:119], 0, v[208:209]
	global_store_dwordx4 v[118:119], v[114:117], off
	s_nop 1
	v_mul_f32_e32 v115, 0xbfb8aa3b, v100
	v_exp_f32_e32 v115, v115
	v_mul_f32_e32 v114, 0xbfb8aa3b, v108
	v_exp_f32_e32 v114, v114
	v_add_f32_e32 v115, 1.0, v115
	v_rcp_f32_e32 v116, v115
	v_mul_f32_e32 v115, 0xbfb8aa3b, v109
	v_exp_f32_e32 v115, v115
	v_add_f32_e32 v114, 1.0, v114
	v_rcp_f32_e32 v114, v114
	v_add_f32_e32 v115, 1.0, v115
	v_rcp_f32_e32 v115, v115
	s_nop 0
	v_pk_mul_f32 v[108:109], v[108:109], v[114:115]
	s_nop 0
	v_pk_mul_f32 v[104:105], v[108:109], v[104:105]
	v_mul_f32_e32 v108, 0xbfb8aa3b, v101
	v_exp_f32_e32 v108, v108
	s_nop 0
	v_add_f32_e32 v108, 1.0, v108
	v_rcp_f32_e32 v117, v108
	s_nop 0
	v_pk_mul_f32 v[100:101], v[100:101], v[116:117]
	s_nop 0
; __device__ __forceinline__ u32x4 pack8u(f32x4 a, f32x4 b) { u32x4 w = {cvt_pk_bf16(a[0], a[1]), cvt_pk_bf16(a[2], a[3]), cvt_pk_bf16(b[0], b[1]), cvt_pk_bf16(b[2], b[3])}; return w; }
; __device__ __forceinline__ float siluf_(float x) { return x * __builtin_amdgcn_rcpf(1.0f + __expf(-x)); }
;     __device__ __forceinline__ void operator()(const AccT& acc, const Unit& u, int wr, int wc, int fr, int fq) const {
; #pragma unroll
;         for (int ai = 0; ai < 2; ++ai)
; #pragma unroll
;             for (int m = 0; m < 4; ++m) {
;                 const int row = u.pm * 256 + ai * 128 + wr * 64 + m * 16 + fr;
;                 f32x4 o0, o1;
; #pragma unroll
;                 for (int j = 0; j < 4; ++j) { o0[j] = siluf_(acc[ai][0][m][0][j]) * acc[ai][1][m][0][j]; o1[j] = siluf_(acc[ai][0][m][1][j]) * acc[ai][1][m][1][j]; }
;                 *(u32x4*)(ACT + (size_t)row * DFF + u.pn * 128 + wc * 32 + fq * 8) = pack8u(o0, o1);
;             }
	v_pk_mul_f32 v[100:101], v[100:101], v[96:97]
	v_mul_f32_e32 v97, 0xbfb8aa3b, v102
	v_exp_f32_e32 v97, v97
	v_mul_f32_e32 v96, 0xbfb8aa3b, v110
	v_exp_f32_e32 v96, v96
	v_add_f32_e32 v97, 1.0, v97
	v_rcp_f32_e32 v108, v97
	v_mul_f32_e32 v97, 0xbfb8aa3b, v111
	v_exp_f32_e32 v97, v97
	v_add_f32_e32 v96, 1.0, v96
	v_rcp_f32_e32 v96, v96
	v_add_f32_e32 v97, 1.0, v97
	v_rcp_f32_e32 v97, v97
	s_nop 0
	v_pk_mul_f32 v[96:97], v[110:111], v[96:97]
	s_nop 0
	v_pk_mul_f32 v[106:107], v[96:97], v[106:107]
	v_mul_f32_e32 v96, 0xbfb8aa3b, v103
	v_exp_f32_e32 v96, v96
	s_nop 0
	v_add_f32_e32 v96, 1.0, v96
	v_rcp_f32_e32 v109, v96
	s_nop 0
	v_pk_mul_f32 v[96:97], v[102:103], v[108:109]
	v_or_b32_e32 v108, 16, v143
	v_pk_mul_f32 v[102:103], v[96:97], v[98:99]
	v_cvt_pk_bf16_f32 v98, v100, v101
	v_mad_i64_i32 v[100:101], s[26:27], v108, s34, v[112:113]
	v_lshl_add_u64 v[100:101], v[100:101], 0, s[88:89]
	v_lshl_add_u64 v[100:101], v[100:101], 0, s[28:29]
	v_cvt_pk_bf16_f32 v96, v104, v105
	v_cvt_pk_bf16_f32 v97, v106, v107
	v_cvt_pk_bf16_f32 v99, v102, v103
	v_lshl_add_u64 v[100:101], v[100:101], 0, v[208:209]
	global_store_dwordx4 v[100:101], v[96:99], off
	s_nop 1
	v_mul_f32_e32 v97, 0xbfb8aa3b, v84
	v_exp_f32_e32 v97, v97
	v_mul_f32_e32 v96, 0xbfb8aa3b, v92
	v_exp_f32_e32 v96, v96
	v_add_f32_e32 v97, 1.0, v97
	v_rcp_f32_e32 v98, v97
	v_mul_f32_e32 v97, 0xbfb8aa3b, v93
	v_exp_f32_e32 v97, v97
	v_add_f32_e32 v96, 1.0, v96
	v_rcp_f32_e32 v96, v96
	v_add_f32_e32 v97, 1.0, v97
	v_rcp_f32_e32 v97, v97
	s_nop 0
	v_pk_mul_f32 v[92:93], v[92:93], v[96:97]
	s_nop 0
	v_pk_mul_f32 v[88:89], v[92:93], v[88:89]
	v_mul_f32_e32 v92, 0xbfb8aa3b, v85
	v_exp_f32_e32 v92, v92
	s_nop 0
	v_add_f32_e32 v92, 1.0, v92
	v_rcp_f32_e32 v99, v92
	s_nop 0
	v_pk_mul_f32 v[84:85], v[84:85], v[98:99]
	s_nop 0
	v_pk_mul_f32 v[84:85], v[84:85], v[80:81]
	v_mul_f32_e32 v81, 0xbfb8aa3b, v86
	v_exp_f32_e32 v81, v81
	v_mul_f32_e32 v80, 0xbfb8aa3b, v94
	v_exp_f32_e32 v80, v80
	v_add_f32_e32 v81, 1.0, v81
	v_rcp_f32_e32 v92, v81
	v_mul_f32_e32 v81, 0xbfb8aa3b, v95
	v_exp_f32_e32 v81, v81
	v_add_f32_e32 v80, 1.0, v80
	v_rcp_f32_e32 v80, v80
	v_add_f32_e32 v81, 1.0, v81
	v_rcp_f32_e32 v81, v81
	s_nop 0
	v_pk_mul_f32 v[80:81], v[94:95], v[80:81]
	s_nop 0
	v_pk_mul_f32 v[90:91], v[80:81], v[90:91]
	v_mul_f32_e32 v80, 0xbfb8aa3b, v87
	v_exp_f32_e32 v80, v80
	s_nop 0
	v_add_f32_e32 v80, 1.0, v80
	v_rcp_f32_e32 v93, v80
	s_nop 0
	v_pk_mul_f32 v[80:81], v[86:87], v[92:93]
	v_or_b32_e32 v92, 32, v143
	v_pk_mul_f32 v[86:87], v[80:81], v[82:83]
	v_cvt_pk_bf16_f32 v82, v84, v85
	v_mad_i64_i32 v[84:85], s[26:27], v92, s34, v[112:113]
	v_lshl_add_u64 v[84:85], v[84:85], 0, s[88:89]
	v_lshl_add_u64 v[84:85], v[84:85], 0, s[28:29]
	v_cvt_pk_bf16_f32 v80, v88, v89
	v_cvt_pk_bf16_f32 v81, v90, v91
	v_cvt_pk_bf16_f32 v83, v86, v87
	v_lshl_add_u64 v[84:85], v[84:85], 0, v[208:209]
	global_store_dwordx4 v[84:85], v[80:83], off
	s_nop 1
	v_mul_f32_e32 v81, 0xbfb8aa3b, v68
	v_exp_f32_e32 v81, v81
	v_mul_f32_e32 v80, 0xbfb8aa3b, v76
	v_exp_f32_e32 v80, v80
	v_add_f32_e32 v81, 1.0, v81
	v_rcp_f32_e32 v82, v81
	v_mul_f32_e32 v81, 0xbfb8aa3b, v77
	v_exp_f32_e32 v81, v81
	v_add_f32_e32 v80, 1.0, v80
	v_rcp_f32_e32 v80, v80
	v_add_f32_e32 v81, 1.0, v81
	v_rcp_f32_e32 v81, v81
	s_nop 0
	v_pk_mul_f32 v[76:77], v[76:77], v[80:81]
	s_nop 0
	v_pk_mul_f32 v[72:73], v[76:77], v[72:73]
	v_mul_f32_e32 v76, 0xbfb8aa3b, v69
	v_exp_f32_e32 v76, v76
	s_nop 0
	v_add_f32_e32 v76, 1.0, v76
	v_rcp_f32_e32 v83, v76
	s_nop 0
	v_pk_mul_f32 v[68:69], v[68:69], v[82:83]
	s_nop 0
	v_pk_mul_f32 v[68:69], v[68:69], v[64:65]
	v_mul_f32_e32 v65, 0xbfb8aa3b, v70
	v_exp_f32_e32 v65, v65
	v_mul_f32_e32 v64, 0xbfb8aa3b, v78
	v_exp_f32_e32 v64, v64
	v_add_f32_e32 v65, 1.0, v65
	v_rcp_f32_e32 v76, v65
	v_mul_f32_e32 v65, 0xbfb8aa3b, v79
	v_exp_f32_e32 v65, v65
	v_add_f32_e32 v64, 1.0, v64
	v_rcp_f32_e32 v64, v64
	v_add_f32_e32 v65, 1.0, v65
	v_rcp_f32_e32 v65, v65
	s_nop 0
	v_pk_mul_f32 v[64:65], v[78:79], v[64:65]
	s_nop 0
	v_pk_mul_f32 v[74:75], v[64:65], v[74:75]
	v_mul_f32_e32 v64, 0xbfb8aa3b, v71
	v_exp_f32_e32 v64, v64
	s_nop 0
	v_add_f32_e32 v64, 1.0, v64
	v_rcp_f32_e32 v77, v64
	s_nop 0
	v_pk_mul_f32 v[64:65], v[70:71], v[76:77]
	v_or_b32_e32 v76, 48, v143
	v_pk_mul_f32 v[70:71], v[64:65], v[66:67]
	v_cvt_pk_bf16_f32 v66, v68, v69
	v_mad_i64_i32 v[68:69], s[26:27], v76, s34, v[112:113]
	v_lshl_add_u64 v[68:69], v[68:69], 0, s[88:89]
	v_lshl_add_u64 v[68:69], v[68:69], 0, s[28:29]
	v_cvt_pk_bf16_f32 v64, v72, v73
	v_cvt_pk_bf16_f32 v65, v74, v75
	v_cvt_pk_bf16_f32 v67, v70, v71
	v_lshl_add_u64 v[68:69], v[68:69], 0, v[208:209]
	global_store_dwordx4 v[68:69], v[64:67], off
	v_add_u32_e32 v68, 0x80, v143
	s_nop 0
	v_mul_f32_e32 v65, 0xbfb8aa3b, v52
	v_exp_f32_e32 v65, v65
	v_mul_f32_e32 v64, 0xbfb8aa3b, v60
	v_exp_f32_e32 v64, v64
	v_add_f32_e32 v65, 1.0, v65
	v_rcp_f32_e32 v66, v65
	v_mul_f32_e32 v65, 0xbfb8aa3b, v61
	v_exp_f32_e32 v65, v65
	v_add_f32_e32 v64, 1.0, v64
	v_rcp_f32_e32 v64, v64
	v_add_f32_e32 v65, 1.0, v65
	v_rcp_f32_e32 v65, v65
	s_nop 0
	v_pk_mul_f32 v[60:61], v[60:61], v[64:65]
	s_nop 0
	v_pk_mul_f32 v[56:57], v[60:61], v[56:57]
	v_mul_f32_e32 v60, 0xbfb8aa3b, v53
	v_exp_f32_e32 v60, v60
	s_nop 0
	v_add_f32_e32 v60, 1.0, v60
	v_rcp_f32_e32 v67, v60
	s_nop 0
	v_pk_mul_f32 v[52:53], v[52:53], v[66:67]
	s_nop 0
	v_pk_mul_f32 v[52:53], v[52:53], v[48:49]
	v_mul_f32_e32 v49, 0xbfb8aa3b, v54
	v_exp_f32_e32 v49, v49
	v_mul_f32_e32 v48, 0xbfb8aa3b, v62
	v_exp_f32_e32 v48, v48
	v_add_f32_e32 v49, 1.0, v49
	v_rcp_f32_e32 v60, v49
	v_mul_f32_e32 v49, 0xbfb8aa3b, v63
	v_exp_f32_e32 v49, v49
	v_add_f32_e32 v48, 1.0, v48
	v_rcp_f32_e32 v48, v48
; __device__ __forceinline__ u32x4 pack8u(f32x4 a, f32x4 b) { u32x4 w = {cvt_pk_bf16(a[0], a[1]), cvt_pk_bf16(a[2], a[3]), cvt_pk_bf16(b[0], b[1]), cvt_pk_bf16(b[2], b[3])}; return w; }
; __device__ __forceinline__ float siluf_(float x) { return x * __builtin_amdgcn_rcpf(1.0f + __expf(-x)); }
; #define PG8_WAIT_V(n) asm volatile("s_waitcnt vmcnt(" #n ")" ::: "memory")
; #define PG8_BAR __builtin_amdgcn_s_barrier()
; template <class Epi>
; __device__ __forceinline__ void gemm_phase(LAS unsigned char* lds, const Gemm g, const Epi& E) {
;     ...
;         E(acc, cur, wr, wc, fr, fq);
;         if (!has_next) break;
; #pragma unroll
;         for (int a = 0; a < 2; ++a)
; #pragma unroll
;             for (int b = 0; b < 2; ++b)
; #pragma unroll
;                 for (int m = 0; m < 4; ++m)
; #pragma unroll
;                     for (int n = 0; n < 2; ++n) acc[a][b][m][n] = (f32x4){0.f, 0.f, 0.f, 0.f};
;         cur = nxt; cA = nA; cB = nB; ++ui;
;     }
;     PG8_WAIT_V(0);
;     if (wr == 0) PG8_BAR;
;     PG8_BAR;
;     __device__ __forceinline__ void operator()(const AccT& acc, const Unit& u, int wr, int wc, int fr, int fq) const {
; #pragma unroll
;         for (int ai = 0; ai < 2; ++ai)
; #pragma unroll
;             for (int m = 0; m < 4; ++m) {
;                 const int row = u.pm * 256 + ai * 128 + wr * 64 + m * 16 + fr;
;                 f32x4 o0, o1;
; #pragma unroll
;                 for (int j = 0; j < 4; ++j) { o0[j] = siluf_(acc[ai][0][m][0][j]) * acc[ai][1][m][0][j]; o1[j] = siluf_(acc[ai][0][m][1][j]) * acc[ai][1][m][1][j]; }
;                 *(u32x4*)(ACT + (size_t)row * DFF + u.pn * 128 + wc * 32 + fq * 8) = pack8u(o0, o1);
;             }
	v_add_f32_e32 v49, 1.0, v49
	v_rcp_f32_e32 v49, v49
	s_nop 0
	v_pk_mul_f32 v[48:49], v[62:63], v[48:49]
	s_nop 0
	v_pk_mul_f32 v[58:59], v[48:49], v[58:59]
	v_mul_f32_e32 v48, 0xbfb8aa3b, v55
	v_exp_f32_e32 v48, v48
	s_nop 0
	v_add_f32_e32 v48, 1.0, v48
	v_rcp_f32_e32 v61, v48
	s_nop 0
	v_pk_mul_f32 v[48:49], v[54:55], v[60:61]
	s_nop 0
	v_pk_mul_f32 v[54:55], v[48:49], v[50:51]
	v_cvt_pk_bf16_f32 v50, v52, v53
	v_mad_i64_i32 v[52:53], s[26:27], v68, s34, v[112:113]
	v_lshl_add_u64 v[52:53], v[52:53], 0, s[88:89]
	v_lshl_add_u64 v[52:53], v[52:53], 0, s[28:29]
	v_cvt_pk_bf16_f32 v48, v56, v57
	v_cvt_pk_bf16_f32 v49, v58, v59
	v_cvt_pk_bf16_f32 v51, v54, v55
	v_lshl_add_u64 v[52:53], v[52:53], 0, v[208:209]
	global_store_dwordx4 v[52:53], v[48:51], off
	s_nop 1
	v_mul_f32_e32 v49, 0xbfb8aa3b, v36
	v_exp_f32_e32 v49, v49
	v_mul_f32_e32 v48, 0xbfb8aa3b, v44
	v_exp_f32_e32 v48, v48
	v_add_f32_e32 v49, 1.0, v49
	v_rcp_f32_e32 v50, v49
	v_mul_f32_e32 v49, 0xbfb8aa3b, v45
	v_exp_f32_e32 v49, v49
	v_add_f32_e32 v48, 1.0, v48
	v_rcp_f32_e32 v48, v48
	v_add_f32_e32 v49, 1.0, v49
	v_rcp_f32_e32 v49, v49
	s_nop 0
	v_pk_mul_f32 v[44:45], v[44:45], v[48:49]
	s_nop 0
	v_pk_mul_f32 v[40:41], v[44:45], v[40:41]
	v_mul_f32_e32 v44, 0xbfb8aa3b, v37
	v_exp_f32_e32 v44, v44
	s_nop 0
	v_add_f32_e32 v44, 1.0, v44
	v_rcp_f32_e32 v51, v44
	s_nop 0
	v_pk_mul_f32 v[36:37], v[36:37], v[50:51]
	s_nop 0
	v_pk_mul_f32 v[36:37], v[36:37], v[32:33]
	v_mul_f32_e32 v33, 0xbfb8aa3b, v38
	v_exp_f32_e32 v33, v33
	v_mul_f32_e32 v32, 0xbfb8aa3b, v46
	v_exp_f32_e32 v32, v32
	v_add_f32_e32 v33, 1.0, v33
	v_rcp_f32_e32 v44, v33
	v_mul_f32_e32 v33, 0xbfb8aa3b, v47
	v_exp_f32_e32 v33, v33
	v_add_f32_e32 v32, 1.0, v32
	v_rcp_f32_e32 v32, v32
	v_add_f32_e32 v33, 1.0, v33
	v_rcp_f32_e32 v33, v33
	s_nop 0
	v_pk_mul_f32 v[32:33], v[46:47], v[32:33]
	s_nop 0
	v_pk_mul_f32 v[42:43], v[32:33], v[42:43]
	v_mul_f32_e32 v32, 0xbfb8aa3b, v39
	v_exp_f32_e32 v32, v32
	s_nop 0
	v_add_f32_e32 v32, 1.0, v32
	v_rcp_f32_e32 v45, v32
	s_nop 0
	v_pk_mul_f32 v[32:33], v[38:39], v[44:45]
	v_add_u32_e32 v44, 0x90, v143
	v_pk_mul_f32 v[38:39], v[32:33], v[34:35]
	v_cvt_pk_bf16_f32 v34, v36, v37
	v_mad_i64_i32 v[36:37], s[26:27], v44, s34, v[112:113]
	v_lshl_add_u64 v[36:37], v[36:37], 0, s[88:89]
	v_lshl_add_u64 v[36:37], v[36:37], 0, s[28:29]
	v_cvt_pk_bf16_f32 v32, v40, v41
	v_cvt_pk_bf16_f32 v33, v42, v43
	v_cvt_pk_bf16_f32 v35, v38, v39
	v_lshl_add_u64 v[36:37], v[36:37], 0, v[208:209]
	global_store_dwordx4 v[36:37], v[32:35], off
	s_nop 1
	v_mul_f32_e32 v33, 0xbfb8aa3b, v20
	v_exp_f32_e32 v33, v33
	v_mul_f32_e32 v32, 0xbfb8aa3b, v28
	v_exp_f32_e32 v32, v32
	v_add_f32_e32 v33, 1.0, v33
	v_rcp_f32_e32 v34, v33
	v_mul_f32_e32 v33, 0xbfb8aa3b, v29
	v_exp_f32_e32 v33, v33
	v_add_f32_e32 v32, 1.0, v32
	v_rcp_f32_e32 v32, v32
	v_add_f32_e32 v33, 1.0, v33
	v_rcp_f32_e32 v33, v33
	s_nop 0
	v_pk_mul_f32 v[28:29], v[28:29], v[32:33]
	s_nop 0
	v_pk_mul_f32 v[24:25], v[28:29], v[24:25]
	v_mul_f32_e32 v28, 0xbfb8aa3b, v21
	v_exp_f32_e32 v28, v28
	s_nop 0
	v_add_f32_e32 v28, 1.0, v28
	v_rcp_f32_e32 v35, v28
	s_nop 0
	v_pk_mul_f32 v[20:21], v[20:21], v[34:35]
	s_nop 0
	v_pk_mul_f32 v[20:21], v[20:21], v[16:17]
	v_mul_f32_e32 v17, 0xbfb8aa3b, v22
	v_exp_f32_e32 v17, v17
	v_mul_f32_e32 v16, 0xbfb8aa3b, v30
	v_exp_f32_e32 v16, v16
	v_add_f32_e32 v17, 1.0, v17
	v_rcp_f32_e32 v28, v17
	v_mul_f32_e32 v17, 0xbfb8aa3b, v31
	v_exp_f32_e32 v17, v17
	v_add_f32_e32 v16, 1.0, v16
	v_rcp_f32_e32 v16, v16
	v_add_f32_e32 v17, 1.0, v17
	v_rcp_f32_e32 v17, v17
	s_nop 0
	v_pk_mul_f32 v[16:17], v[30:31], v[16:17]
	s_nop 0
	v_pk_mul_f32 v[26:27], v[16:17], v[26:27]
	v_mul_f32_e32 v16, 0xbfb8aa3b, v23
	v_exp_f32_e32 v16, v16
	s_nop 0
	v_add_f32_e32 v16, 1.0, v16
	v_rcp_f32_e32 v29, v16
	s_nop 0
	v_pk_mul_f32 v[16:17], v[22:23], v[28:29]
	v_add_u32_e32 v28, 0xa0, v143
	v_pk_mul_f32 v[22:23], v[16:17], v[18:19]
	v_cvt_pk_bf16_f32 v18, v20, v21
	v_mad_i64_i32 v[20:21], s[26:27], v28, s34, v[112:113]
	v_lshl_add_u64 v[20:21], v[20:21], 0, s[88:89]
	v_lshl_add_u64 v[20:21], v[20:21], 0, s[28:29]
	v_cvt_pk_bf16_f32 v16, v24, v25
	v_cvt_pk_bf16_f32 v17, v26, v27
	v_cvt_pk_bf16_f32 v19, v22, v23
	v_lshl_add_u64 v[20:21], v[20:21], 0, v[208:209]
	global_store_dwordx4 v[20:21], v[16:19], off
	s_nop 1
	v_mul_f32_e32 v17, 0xbfb8aa3b, v4
	v_exp_f32_e32 v17, v17
	v_mul_f32_e32 v16, 0xbfb8aa3b, v12
	v_exp_f32_e32 v16, v16
	v_add_f32_e32 v17, 1.0, v17
	v_rcp_f32_e32 v18, v17
	v_mul_f32_e32 v17, 0xbfb8aa3b, v13
	v_exp_f32_e32 v17, v17
	v_add_f32_e32 v16, 1.0, v16
	v_rcp_f32_e32 v16, v16
	v_add_f32_e32 v17, 1.0, v17
	v_rcp_f32_e32 v17, v17
	s_nop 0
	v_pk_mul_f32 v[12:13], v[12:13], v[16:17]
	s_nop 0
	v_pk_mul_f32 v[8:9], v[12:13], v[8:9]
	v_mul_f32_e32 v12, 0xbfb8aa3b, v5
	v_exp_f32_e32 v12, v12
	s_nop 0
	v_add_f32_e32 v12, 1.0, v12
	v_rcp_f32_e32 v19, v12
	s_nop 0
	v_pk_mul_f32 v[4:5], v[4:5], v[18:19]
	s_nop 0
	v_pk_mul_f32 v[4:5], v[4:5], v[0:1]
	v_mul_f32_e32 v1, 0xbfb8aa3b, v6
	v_exp_f32_e32 v1, v1
	v_mul_f32_e32 v0, 0xbfb8aa3b, v14
	v_exp_f32_e32 v0, v0
	v_add_f32_e32 v1, 1.0, v1
	v_rcp_f32_e32 v12, v1
	v_mul_f32_e32 v1, 0xbfb8aa3b, v15
	v_exp_f32_e32 v1, v1
	v_add_f32_e32 v0, 1.0, v0
	v_rcp_f32_e32 v0, v0
	v_add_f32_e32 v1, 1.0, v1
	v_rcp_f32_e32 v1, v1
	s_nop 0
	v_pk_mul_f32 v[0:1], v[14:15], v[0:1]
	s_nop 0
	v_pk_mul_f32 v[10:11], v[0:1], v[10:11]
	v_mul_f32_e32 v0, 0xbfb8aa3b, v7
	v_exp_f32_e32 v0, v0
	s_nop 0
	v_add_f32_e32 v0, 1.0, v0
	v_rcp_f32_e32 v13, v0
	s_nop 0
	v_pk_mul_f32 v[0:1], v[6:7], v[12:13]
	v_add_u32_e32 v12, 0xb0, v143
	v_pk_mul_f32 v[6:7], v[0:1], v[2:3]
	v_cvt_pk_bf16_f32 v2, v4, v5
	v_mad_i64_i32 v[4:5], s[26:27], v12, s34, v[112:113]
	v_lshl_add_u64 v[4:5], v[4:5], 0, s[88:89]
	v_lshl_add_u64 v[4:5], v[4:5], 0, s[28:29]
	v_cvt_pk_bf16_f32 v0, v8, v9
	v_cvt_pk_bf16_f32 v1, v10, v11
	v_cvt_pk_bf16_f32 v3, v6, v7
	v_lshl_add_u64 v[4:5], v[4:5], 0, v[208:209]
	s_mov_b32 s88, s44
	s_mov_b64 s[28:29], s[64:65]
	s_mov_b64 s[26:27], s[48:49]
	global_store_dwordx4 v[4:5], v[0:3], off
	s_cbranch_vccz .LBB0_27
	s_waitcnt vmcnt(0)
	s_cmpk_gt_u32 s30, 0xff
	s_mov_b32 s89, 0xc000
	s_mov_b64 s[34:35], 0
	s_cbranch_scc1 .LBB0_34
	s_barrier

; #define PG8_STAGE(bufoff, gbase, voff) do { _Pragma("unroll") for (int _i = 0; _i < 2; ++_i) \
;         __builtin_amdgcn_global_load_lds((const unsigned*)((const char*)(gbase) + (voff)[_i]), (LAS unsigned*)(lds + (bufoff) + ldsw + _i * 8192), 16, 0, 0); } while (0)
; #define PG8_LDA(dst, b, h) do { _Pragma("unroll") for (int m = 0; m < 4; ++m) _Pragma("unroll") for (int k = 0; k < 2; ++k) dst[m][k] = *(const LAS bf16x8*)(lds + PG8_SA(b, h) + aoff + m * 2048 + k * 1024); } while (0)
; #define PG8_LDB(dst, b, h) do { _Pragma("unroll") for (int n = 0; n < 2; ++n) _Pragma("unroll") for (int k = 0; k < 2; ++k) dst[n][k] = *(const LAS bf16x8*)(lds + PG8_SB(b, h) + boff + n * 2048 + k * 1024); } while (0)
; #define PG8_MMA(ai, bj, At, Bt) do { __builtin_amdgcn_s_setprio(1); _Pragma("unroll") for (int m = 0; m < 4; ++m) _Pragma("unroll") for (int n = 0; n < 2; ++n) _Pragma("unroll") for (int k = 0; k < 2; ++k) \
;         acc[ai][bj][m][n] = __builtin_amdgcn_mfma_f32_16x16x32_bf16(Bt[n][k], At[m][k], acc[ai][bj][m][n], 0, 0, 0); __builtin_amdgcn_s_setprio(0); } while (0)
; #define PG8_WAIT_L(n) asm volatile("s_waitcnt lgkmcnt(" #n ")" ::: "memory")
; #define PG8_BAR __builtin_amdgcn_s_barrier()
; #define PG8_SCHED __builtin_amdgcn_sched_barrier(0)
; template <class Epi>
; __device__ __forceinline__ void gemm_phase(LAS unsigned char* lds, const Gemm g, const Epi& E) {
;     ...
;         for (int t = 0; t < nt; t += 2) {
;             const bool last = (t == nt - 2);
;             const char* a1 = cA + (size_t)(t + 1) * kstep;
;             const char* a2 = last ? nA : cA + (size_t)(t + 2) * kstep; const char* b2 = last ? nB : cB + (size_t)(t + 2) * kstep;
;             const char* a3 = a2 + kstep; const char* b3 = b2 + kstep;
;             PG8_LDB(B0, 0, 0); PG8_SCHED; PG8_LDA(At, 0, 0); PG8_STAGE(PG8_SA(1, 1), a1 + hstep, voffA);
;             PG8_WAIT_L(8); PG8_BAR; PG8_WAIT_L(0); PG8_MMA(0, 0, At, B0); PG8_BAR; PG8_SCHED;
;             PG8_LDB(B1, 0, 1); PG8_STAGE(PG8_SB(0, 0), b2, voffB);
;             PG8_BAR; PG8_WAIT_L(0); PG8_MMA(0, 1, At, B1); PG8_BAR;
;             PG8_LDA(At, 0, 1); PG8_STAGE(PG8_SA(0, 0), a2, voffA);
;             PG8_BAR; PG8_WAIT_L(0); PG8_MMA(1, 0, At, B0); PG8_BAR; PG8_SCHED;
;             PG8_STAGE(PG8_SB(0, 1), b2 + hstep, voffB);
.LBB0_120:
	s_add_u32 s28, s26, 0xfff80080
	s_addc_u32 s29, s27, -1
	s_add_i32 s34, 0, 0x10000
	v_add_u32_e32 v92, s34, v174
	ds_read_b128 v[72:75], v92
	ds_read_b128 v[76:79], v92 offset:1024
	ds_read_b128 v[84:87], v92 offset:2048
	ds_read_b128 v[92:95], v92 offset:3072
	s_cmp_eq_u32 vcc_lo, 28
	s_cselect_b32 s37, s38, s29
	s_cselect_b32 s36, s39, s28
	s_cselect_b32 s29, s43, s97
	s_cselect_b32 s28, s49, s65
	v_lshl_add_u64 v[172:173], s[26:27], 0, v[160:161]
	s_add_i32 m0, s68, 0xc000
	ds_read_b128 v[144:147], v175
	ds_read_b128 v[148:151], v175 offset:1024
	ds_read_b128 v[164:167], v175 offset:2048
	ds_read_b128 v[168:171], v175 offset:3072
	ds_read_b128 v[178:181], v175 offset:4096
	ds_read_b128 v[182:185], v175 offset:5120
	ds_read_b128 v[186:189], v175 offset:6144
	ds_read_b128 v[190:193], v175 offset:7168
	global_load_lds_dwordx4 v[172:173], off
	s_add_i32 m0, s68, 0xe000
	v_lshl_add_u64 v[172:173], s[26:27], 0, v[162:163]
	global_load_lds_dwordx4 v[172:173], off
	s_waitcnt lgkmcnt(8)
	s_barrier
	s_waitcnt lgkmcnt(0)
	s_setprio 1
	v_mfma_f32_16x16x32_bf16 v[140:143], v[72:75], v[144:147], v[140:143]
	v_mfma_f32_16x16x32_bf16 v[136:139], v[84:87], v[144:147], v[136:139]
	v_mfma_f32_16x16x32_bf16 v[124:127], v[72:75], v[164:167], v[124:127]
	v_mfma_f32_16x16x32_bf16 v[120:123], v[84:87], v[164:167], v[120:123]
	v_mfma_f32_16x16x32_bf16 v[108:111], v[72:75], v[178:181], v[108:111]
	v_mfma_f32_16x16x32_bf16 v[104:107], v[84:87], v[178:181], v[104:107]
	v_mfma_f32_16x16x32_bf16 v[88:91], v[72:75], v[186:189], v[88:91]
	v_mfma_f32_16x16x32_bf16 v[80:83], v[84:87], v[186:189], v[80:83]
	v_mfma_f32_16x16x32_bf16 v[140:143], v[76:79], v[148:151], v[140:143]
	v_mfma_f32_16x16x32_bf16 v[136:139], v[92:95], v[148:151], v[136:139]
	v_mfma_f32_16x16x32_bf16 v[124:127], v[76:79], v[168:171], v[124:127]
	v_mfma_f32_16x16x32_bf16 v[120:123], v[92:95], v[168:171], v[120:123]
	v_mfma_f32_16x16x32_bf16 v[108:111], v[76:79], v[182:185], v[108:111]
	v_mfma_f32_16x16x32_bf16 v[104:107], v[92:95], v[182:185], v[104:107]
	v_mfma_f32_16x16x32_bf16 v[88:91], v[76:79], v[190:193], v[88:91]
	v_mfma_f32_16x16x32_bf16 v[80:83], v[92:95], v[190:193], v[80:83]
	s_setprio 0
	s_barrier
	s_add_i32 s46, 0, 0x14000
	v_add_u32_e32 v172, s46, v174
	s_add_i32 s34, s34, s31
	ds_read_b128 v[194:197], v172
	ds_read_b128 v[198:201], v172 offset:1024
	ds_read_b128 v[202:205], v172 offset:2048
	ds_read_b128 v[228:231], v172 offset:3072
	v_lshl_add_u64 v[172:173], s[28:29], 0, v[208:209]
	s_mov_b32 m0, s34
	v_lshl_add_u64 v[206:207], s[28:29], 0, v[156:157]
	global_load_lds_dwordx4 v[172:173], off
	s_add_i32 m0, s34, 0x2000
	s_nop 0
	global_load_lds_dwordx4 v[206:207], off
	s_barrier
	s_waitcnt lgkmcnt(0)
	s_setprio 1
	v_mfma_f32_16x16x32_bf16 v[132:135], v[194:197], v[144:147], v[132:135]
	v_mfma_f32_16x16x32_bf16 v[128:131], v[202:205], v[144:147], v[128:131]
	v_mfma_f32_16x16x32_bf16 v[116:119], v[194:197], v[164:167], v[116:119]
	v_mfma_f32_16x16x32_bf16 v[112:115], v[202:205], v[164:167], v[112:115]
	v_mfma_f32_16x16x32_bf16 v[100:103], v[194:197], v[178:181], v[100:103]
	v_mfma_f32_16x16x32_bf16 v[96:99], v[202:205], v[178:181], v[96:99]
	v_mfma_f32_16x16x32_bf16 v[68:71], v[194:197], v[186:189], v[68:71]
	v_mfma_f32_16x16x32_bf16 v[64:67], v[202:205], v[186:189], v[64:67]
	v_mfma_f32_16x16x32_bf16 v[132:135], v[198:201], v[148:151], v[132:135]
	v_mfma_f32_16x16x32_bf16 v[128:131], v[228:231], v[148:151], v[128:131]
	v_mfma_f32_16x16x32_bf16 v[116:119], v[198:201], v[168:171], v[116:119]
	v_mfma_f32_16x16x32_bf16 v[112:115], v[228:231], v[168:171], v[112:115]
	v_mfma_f32_16x16x32_bf16 v[100:103], v[198:201], v[182:185], v[100:103]
	v_mfma_f32_16x16x32_bf16 v[96:99], v[228:231], v[182:185], v[96:99]
	v_mfma_f32_16x16x32_bf16 v[68:71], v[198:201], v[190:193], v[68:71]
	v_mfma_f32_16x16x32_bf16 v[64:67], v[228:231], v[190:193], v[64:67]
	s_setprio 0
	s_mov_b32 m0, s68
	v_lshl_add_u64 v[220:221], s[36:37], 0, v[152:153]
	s_barrier
	ds_read_b128 v[144:147], v175 offset:16384
	ds_read_b128 v[148:151], v175 offset:17408
	ds_read_b128 v[164:167], v175 offset:18432
	ds_read_b128 v[168:171], v175 offset:19456
	ds_read_b128 v[178:181], v175 offset:20480
	ds_read_b128 v[182:185], v175 offset:21504
	ds_read_b128 v[186:189], v175 offset:22528
	ds_read_b128 v[190:193], v175 offset:23552
	global_load_lds_dwordx4 v[220:221], off
	s_mov_b32 m0, s69
	v_lshl_add_u64 v[232:233], s[36:37], 0, v[154:155]
	global_load_lds_dwordx4 v[232:233], off
	s_barrier
	s_waitcnt lgkmcnt(0)
	s_setprio 1
	v_mfma_f32_16x16x32_bf16 v[60:63], v[72:75], v[144:147], v[60:63]
	v_mfma_f32_16x16x32_bf16 v[56:59], v[84:87], v[144:147], v[56:59]
	v_mfma_f32_16x16x32_bf16 v[44:47], v[72:75], v[164:167], v[44:47]
	v_mfma_f32_16x16x32_bf16 v[40:43], v[84:87], v[164:167], v[40:43]
	v_mfma_f32_16x16x32_bf16 v[28:31], v[72:75], v[178:181], v[28:31]
	v_mfma_f32_16x16x32_bf16 v[24:27], v[84:87], v[178:181], v[24:27]
	v_mfma_f32_16x16x32_bf16 v[12:15], v[72:75], v[186:189], v[12:15]
	v_mfma_f32_16x16x32_bf16 v[8:11], v[84:87], v[186:189], v[8:11]
	v_mfma_f32_16x16x32_bf16 v[60:63], v[76:79], v[148:151], v[60:63]
	v_mfma_f32_16x16x32_bf16 v[56:59], v[92:95], v[148:151], v[56:59]
	v_mfma_f32_16x16x32_bf16 v[44:47], v[76:79], v[168:171], v[44:47]
	v_mfma_f32_16x16x32_bf16 v[40:43], v[92:95], v[168:171], v[40:43]
	v_mfma_f32_16x16x32_bf16 v[28:31], v[76:79], v[182:185], v[28:31]
	v_mfma_f32_16x16x32_bf16 v[24:27], v[92:95], v[182:185], v[24:27]
	v_mfma_f32_16x16x32_bf16 v[12:15], v[76:79], v[190:193], v[12:15]
	v_mfma_f32_16x16x32_bf16 v[8:11], v[92:95], v[190:193], v[8:11]
	s_setprio 0
	s_barrier
; #define PG8_STAGE(bufoff, gbase, voff) do { _Pragma("unroll") for (int _i = 0; _i < 2; ++_i) \
;         __builtin_amdgcn_global_load_lds((const unsigned*)((const char*)(gbase) + (voff)[_i]), (LAS unsigned*)(lds + (bufoff) + ldsw + _i * 8192), 16, 0, 0); } while (0)
; #define PG8_LDA(dst, b, h) do { _Pragma("unroll") for (int m = 0; m < 4; ++m) _Pragma("unroll") for (int k = 0; k < 2; ++k) dst[m][k] = *(const LAS bf16x8*)(lds + PG8_SA(b, h) + aoff + m * 2048 + k * 1024); } while (0)
; #define PG8_LDB(dst, b, h) do { _Pragma("unroll") for (int n = 0; n < 2; ++n) _Pragma("unroll") for (int k = 0; k < 2; ++k) dst[n][k] = *(const LAS bf16x8*)(lds + PG8_SB(b, h) + boff + n * 2048 + k * 1024); } while (0)
; #define PG8_MMA(ai, bj, At, Bt) do { __builtin_amdgcn_s_setprio(1); _Pragma("unroll") for (int m = 0; m < 4; ++m) _Pragma("unroll") for (int n = 0; n < 2; ++n) _Pragma("unroll") for (int k = 0; k < 2; ++k) \
;         acc[ai][bj][m][n] = __builtin_amdgcn_mfma_f32_16x16x32_bf16(Bt[n][k], At[m][k], acc[ai][bj][m][n], 0, 0, 0); __builtin_amdgcn_s_setprio(0); } while (0)
; #define PG8_WAIT_V(n) asm volatile("s_waitcnt vmcnt(" #n ")" ::: "memory")
; #define PG8_WAIT_L(n) asm volatile("s_waitcnt lgkmcnt(" #n ")" ::: "memory")
; #define PG8_BAR __builtin_amdgcn_s_barrier()
; #define PG8_SCHED __builtin_amdgcn_sched_barrier(0)
; template <class Epi>
; __device__ __forceinline__ void gemm_phase(LAS unsigned char* lds, const Gemm g, const Epi& E) {
;     ...
;             PG8_STAGE(PG8_SB(0, 1), b2 + hstep, voffB);
;             PG8_WAIT_V(6); PG8_BAR; PG8_MMA(1, 1, At, B1); PG8_BAR;
;             PG8_LDB(B0, 1, 0); PG8_SCHED; PG8_LDA(At, 1, 0); PG8_STAGE(PG8_SA(0, 1), a2 + hstep, voffA);
;             PG8_WAIT_L(8); PG8_BAR; PG8_WAIT_L(0); PG8_MMA(0, 0, At, B0); PG8_BAR; PG8_SCHED;
;             PG8_LDB(B1, 1, 1); PG8_STAGE(PG8_SB(1, 0), b3, voffB);
;             PG8_BAR; PG8_WAIT_L(0); PG8_MMA(0, 1, At, B1); PG8_BAR;
;             PG8_LDA(At, 1, 1); PG8_STAGE(PG8_SA(1, 0), a3, voffA);
;             PG8_BAR; PG8_WAIT_L(0); PG8_MMA(1, 0, At, B0); PG8_BAR; PG8_SCHED;
;             PG8_STAGE(PG8_SB(1, 1), b3 + hstep, voffB);
	s_add_u32 s34, s28, 0x80000
	s_addc_u32 s35, s29, 0
	s_add_i32 s46, s46, s31
	s_mov_b32 m0, s46
	v_lshl_add_u64 v[72:73], s[34:35], 0, v[208:209]
	global_load_lds_dwordx4 v[72:73], off
	s_add_i32 m0, s46, 0x2000
	v_lshl_add_u64 v[72:73], s[34:35], 0, v[156:157]
	global_load_lds_dwordx4 v[72:73], off
	s_waitcnt vmcnt(6)
	s_barrier
	s_setprio 1
	v_mfma_f32_16x16x32_bf16 v[52:55], v[194:197], v[144:147], v[52:55]
	v_mfma_f32_16x16x32_bf16 v[48:51], v[202:205], v[144:147], v[48:51]
	v_mfma_f32_16x16x32_bf16 v[36:39], v[194:197], v[164:167], v[36:39]
	v_mfma_f32_16x16x32_bf16 v[32:35], v[202:205], v[164:167], v[32:35]
	v_mfma_f32_16x16x32_bf16 v[20:23], v[194:197], v[178:181], v[20:23]
	v_mfma_f32_16x16x32_bf16 v[16:19], v[202:205], v[178:181], v[16:19]
	v_mfma_f32_16x16x32_bf16 v[4:7], v[194:197], v[186:189], v[4:7]
	v_mfma_f32_16x16x32_bf16 v[0:3], v[202:205], v[186:189], v[0:3]
	v_mfma_f32_16x16x32_bf16 v[52:55], v[198:201], v[148:151], v[52:55]
	v_mfma_f32_16x16x32_bf16 v[48:51], v[228:231], v[148:151], v[48:51]
	v_mfma_f32_16x16x32_bf16 v[36:39], v[198:201], v[168:171], v[36:39]
	v_mfma_f32_16x16x32_bf16 v[32:35], v[228:231], v[168:171], v[32:35]
	v_mfma_f32_16x16x32_bf16 v[20:23], v[198:201], v[182:185], v[20:23]
	v_mfma_f32_16x16x32_bf16 v[16:19], v[228:231], v[182:185], v[16:19]
	v_mfma_f32_16x16x32_bf16 v[4:7], v[198:201], v[190:193], v[4:7]
	v_mfma_f32_16x16x32_bf16 v[0:3], v[228:231], v[190:193], v[0:3]
	s_setprio 0
	s_add_i32 s46, 0, 0x18000
	v_add_u32_e32 v92, s46, v174
	s_barrier
	ds_read_b128 v[72:75], v92
	ds_read_b128 v[76:79], v92 offset:1024
	ds_read_b128 v[84:87], v92 offset:2048
	ds_read_b128 v[92:95], v92 offset:3072
	s_add_u32 s34, s36, 0x80000
	s_addc_u32 s35, s37, 0
	s_mov_b32 m0, s70
	v_lshl_add_u64 v[194:195], s[34:35], 0, v[152:153]
	ds_read_b128 v[144:147], v175 offset:32768
	ds_read_b128 v[148:151], v175 offset:33792
	ds_read_b128 v[164:167], v175 offset:34816
	ds_read_b128 v[168:171], v175 offset:35840
	ds_read_b128 v[178:181], v175 offset:36864
	ds_read_b128 v[182:185], v175 offset:37888
	ds_read_b128 v[186:189], v175 offset:38912
	ds_read_b128 v[190:193], v175 offset:39936
	global_load_lds_dwordx4 v[194:195], off
	s_mov_b32 m0, s71
	v_lshl_add_u64 v[194:195], s[34:35], 0, v[154:155]
	global_load_lds_dwordx4 v[194:195], off
	s_waitcnt lgkmcnt(8)
	s_barrier
	s_waitcnt lgkmcnt(0)
	s_setprio 1
	v_mfma_f32_16x16x32_bf16 v[140:143], v[72:75], v[144:147], v[140:143]
	v_mfma_f32_16x16x32_bf16 v[136:139], v[84:87], v[144:147], v[136:139]
	v_mfma_f32_16x16x32_bf16 v[124:127], v[72:75], v[164:167], v[124:127]
	v_mfma_f32_16x16x32_bf16 v[120:123], v[84:87], v[164:167], v[120:123]
	v_mfma_f32_16x16x32_bf16 v[108:111], v[72:75], v[178:181], v[108:111]
	v_mfma_f32_16x16x32_bf16 v[104:107], v[84:87], v[178:181], v[104:107]
	v_mfma_f32_16x16x32_bf16 v[88:91], v[72:75], v[186:189], v[88:91]
	v_mfma_f32_16x16x32_bf16 v[80:83], v[84:87], v[186:189], v[80:83]
	v_mfma_f32_16x16x32_bf16 v[140:143], v[76:79], v[148:151], v[140:143]
	v_mfma_f32_16x16x32_bf16 v[136:139], v[92:95], v[148:151], v[136:139]
	v_mfma_f32_16x16x32_bf16 v[124:127], v[76:79], v[168:171], v[124:127]
	v_mfma_f32_16x16x32_bf16 v[120:123], v[92:95], v[168:171], v[120:123]
	v_mfma_f32_16x16x32_bf16 v[108:111], v[76:79], v[182:185], v[108:111]
	v_mfma_f32_16x16x32_bf16 v[104:107], v[92:95], v[182:185], v[104:107]
	v_mfma_f32_16x16x32_bf16 v[88:91], v[76:79], v[190:193], v[88:91]
	v_mfma_f32_16x16x32_bf16 v[80:83], v[92:95], v[190:193], v[80:83]
	s_setprio 0
	s_barrier
	s_add_i32 s34, 0, 0x1c000
	s_add_i32 s35, s46, s31
	v_add_u32_e32 v177, s34, v174
	v_lshl_add_u64 v[172:173], v[172:173], 0, s[20:21]
	s_mov_b32 m0, s35
	ds_read_b128 v[194:197], v177
	ds_read_b128 v[198:201], v177 offset:1024
	ds_read_b128 v[202:205], v177 offset:2048
	ds_read_b128 v[228:231], v177 offset:3072
	global_load_lds_dwordx4 v[172:173], off
	s_add_i32 m0, s35, 0x2000
	v_lshl_add_u64 v[172:173], v[206:207], 0, s[20:21]
	global_load_lds_dwordx4 v[172:173], off
	s_barrier
	s_waitcnt lgkmcnt(0)
	s_setprio 1
	v_mfma_f32_16x16x32_bf16 v[132:135], v[194:197], v[144:147], v[132:135]
	v_mfma_f32_16x16x32_bf16 v[128:131], v[202:205], v[144:147], v[128:131]
	v_mfma_f32_16x16x32_bf16 v[116:119], v[194:197], v[164:167], v[116:119]
	v_mfma_f32_16x16x32_bf16 v[112:115], v[202:205], v[164:167], v[112:115]
	v_mfma_f32_16x16x32_bf16 v[100:103], v[194:197], v[178:181], v[100:103]
	v_mfma_f32_16x16x32_bf16 v[96:99], v[202:205], v[178:181], v[96:99]
	v_mfma_f32_16x16x32_bf16 v[68:71], v[194:197], v[186:189], v[68:71]
	v_mfma_f32_16x16x32_bf16 v[64:67], v[202:205], v[186:189], v[64:67]
	v_mfma_f32_16x16x32_bf16 v[132:135], v[198:201], v[148:151], v[132:135]
	v_mfma_f32_16x16x32_bf16 v[128:131], v[228:231], v[148:151], v[128:131]
	v_mfma_f32_16x16x32_bf16 v[116:119], v[198:201], v[168:171], v[116:119]
	v_mfma_f32_16x16x32_bf16 v[112:115], v[228:231], v[168:171], v[112:115]
	v_mfma_f32_16x16x32_bf16 v[100:103], v[198:201], v[182:185], v[100:103]
	v_mfma_f32_16x16x32_bf16 v[96:99], v[228:231], v[182:185], v[96:99]
	v_mfma_f32_16x16x32_bf16 v[68:71], v[198:201], v[190:193], v[68:71]
	v_mfma_f32_16x16x32_bf16 v[64:67], v[228:231], v[190:193], v[64:67]
	s_setprio 0
	s_mov_b32 m0, s78
	v_lshl_add_u64 v[172:173], v[220:221], 0, s[20:21]
	s_barrier
	ds_read_b128 v[144:147], v175 offset:49152
	ds_read_b128 v[148:151], v175 offset:50176
	ds_read_b128 v[164:167], v175 offset:51200
	ds_read_b128 v[168:171], v175 offset:52224
	ds_read_b128 v[178:181], v175 offset:53248
	ds_read_b128 v[182:185], v175 offset:54272
	ds_read_b128 v[186:189], v175 offset:55296
	ds_read_b128 v[190:193], v175 offset:56320
	global_load_lds_dwordx4 v[172:173], off
	s_mov_b32 m0, s79
	v_lshl_add_u64 v[172:173], v[232:233], 0, s[20:21]
	global_load_lds_dwordx4 v[172:173], off
	s_barrier
; __device__ __forceinline__ float bflo(unsigned w) { return __uint_as_float(w << 16); }
; __device__ __forceinline__ float bfhi(unsigned w) { return __uint_as_float(w & 0xffff0000u); }
; __device__ __forceinline__ u32x4 pack8u(f32x4 a, f32x4 b) { u32x4 w = {cvt_pk_bf16(a[0], a[1]), cvt_pk_bf16(a[2], a[3]), cvt_pk_bf16(b[0], b[1]), cvt_pk_bf16(b[2], b[3])}; return w; }
; #define PG8_MMA(ai, bj, At, Bt) do { __builtin_amdgcn_s_setprio(1); _Pragma("unroll") for (int m = 0; m < 4; ++m) _Pragma("unroll") for (int n = 0; n < 2; ++n) _Pragma("unroll") for (int k = 0; k < 2; ++k) \
;         acc[ai][bj][m][n] = __builtin_amdgcn_mfma_f32_16x16x32_bf16(Bt[n][k], At[m][k], acc[ai][bj][m][n], 0, 0, 0); __builtin_amdgcn_s_setprio(0); } while (0)
; #define PG8_WAIT_V(n) asm volatile("s_waitcnt vmcnt(" #n ")" ::: "memory")
; #define PG8_BAR __builtin_amdgcn_s_barrier()
; template <class Epi>
; __device__ __forceinline__ void gemm_phase(LAS unsigned char* lds, const Gemm g, const Epi& E) {
;     ...
;             PG8_WAIT_V(6); PG8_BAR; PG8_MMA(1, 1, At, B1); PG8_BAR;
;     __device__ __forceinline__ void operator()(const AccT& acc, const Unit& u, int wr, int wc, int fr, int fq) const {
;         const int b = (u.pm * 256) / SEQ;
;         f32x4 gt[2][2];
; #pragma unroll
;         for (int bj = 0; bj < 2; ++bj)
; #pragma unroll
;             for (int n = 0; n < 2; ++n) gt[bj][n] = *(const f32x4*)(GT + (size_t)b * 6 * D + u.pn * 256 + bj * 128 + wc * 32 + fq * 8 + 4 * n);
; #pragma unroll
;         for (int ai = 0; ai < 2; ++ai)
; #pragma unroll
;             for (int m = 0; m < 4; ++m) {
;                 const int row = u.pm * 256 + ai * 128 + wr * 64 + m * 16 + fr;
; #pragma unroll
;                 for (int bj = 0; bj < 2; ++bj) {
;                     const size_t off = (size_t)row * D + u.pn * 256 + bj * 128 + wc * 32 + fq * 8;
;                     f32x4 x0, x1;
;                     if (XINF) { x0 = *(const f32x4*)(XINF + off); x1 = *(const f32x4*)(XINF + off + 4); }
;                     else { const u32x4 w = *(const u32x4*)(XIN16 + off); x0 = (f32x4){bflo(w[0]), bfhi(w[0]), bflo(w[1]), bfhi(w[1])}; x1 = (f32x4){bflo(w[2]), bfhi(w[2]), bflo(w[3]), bfhi(w[3])}; }
;                     *(u32x4*)(XOUT + off) = pack8u(x0 + gt[bj][0] * acc[ai][bj][m][0], x1 + gt[bj][1] * acc[ai][bj][m][1]);
;                 }
;             }
	s_waitcnt lgkmcnt(0)
	s_setprio 1
	v_mfma_f32_16x16x32_bf16 v[60:63], v[72:75], v[144:147], v[60:63]
	v_mfma_f32_16x16x32_bf16 v[56:59], v[84:87], v[144:147], v[56:59]
	v_mfma_f32_16x16x32_bf16 v[44:47], v[72:75], v[164:167], v[44:47]
	v_mfma_f32_16x16x32_bf16 v[40:43], v[84:87], v[164:167], v[40:43]
	v_mfma_f32_16x16x32_bf16 v[28:31], v[72:75], v[178:181], v[28:31]
	v_mfma_f32_16x16x32_bf16 v[24:27], v[84:87], v[178:181], v[24:27]
	v_mfma_f32_16x16x32_bf16 v[12:15], v[72:75], v[186:189], v[12:15]
	v_mfma_f32_16x16x32_bf16 v[8:11], v[84:87], v[186:189], v[8:11]
	v_mfma_f32_16x16x32_bf16 v[60:63], v[76:79], v[148:151], v[60:63]
	v_mfma_f32_16x16x32_bf16 v[56:59], v[92:95], v[148:151], v[56:59]
	v_mfma_f32_16x16x32_bf16 v[44:47], v[76:79], v[168:171], v[44:47]
	v_mfma_f32_16x16x32_bf16 v[40:43], v[92:95], v[168:171], v[40:43]
	v_mfma_f32_16x16x32_bf16 v[28:31], v[76:79], v[182:185], v[28:31]
	v_mfma_f32_16x16x32_bf16 v[24:27], v[92:95], v[182:185], v[24:27]
	v_mfma_f32_16x16x32_bf16 v[12:15], v[76:79], v[190:193], v[12:15]
	v_mfma_f32_16x16x32_bf16 v[8:11], v[92:95], v[190:193], v[8:11]
	s_setprio 0
	s_barrier
	s_add_u32 s28, s28, 0x80080
	s_addc_u32 s29, s29, 0
	s_add_i32 s34, s34, s31
	s_mov_b32 m0, s34
	v_lshl_add_u64 v[72:73], s[28:29], 0, v[208:209]
	global_load_lds_dwordx4 v[72:73], off
	s_add_i32 m0, s34, 0x2000
	v_lshl_add_u64 v[72:73], s[28:29], 0, v[156:157]
	global_load_lds_dwordx4 v[72:73], off
	s_waitcnt vmcnt(6)
	s_barrier
	s_setprio 1
	v_mfma_f32_16x16x32_bf16 v[52:55], v[194:197], v[144:147], v[52:55]
	v_mfma_f32_16x16x32_bf16 v[48:51], v[202:205], v[144:147], v[48:51]
	v_mfma_f32_16x16x32_bf16 v[36:39], v[194:197], v[164:167], v[36:39]
	v_mfma_f32_16x16x32_bf16 v[32:35], v[202:205], v[164:167], v[32:35]
	v_mfma_f32_16x16x32_bf16 v[20:23], v[194:197], v[178:181], v[20:23]
	v_mfma_f32_16x16x32_bf16 v[16:19], v[202:205], v[178:181], v[16:19]
	v_mfma_f32_16x16x32_bf16 v[4:7], v[194:197], v[186:189], v[4:7]
	v_mfma_f32_16x16x32_bf16 v[0:3], v[202:205], v[186:189], v[0:3]
	v_mfma_f32_16x16x32_bf16 v[52:55], v[198:201], v[148:151], v[52:55]
	v_mfma_f32_16x16x32_bf16 v[48:51], v[228:231], v[148:151], v[48:51]
	v_mfma_f32_16x16x32_bf16 v[36:39], v[198:201], v[168:171], v[36:39]
	v_mfma_f32_16x16x32_bf16 v[32:35], v[228:231], v[168:171], v[32:35]
	v_mfma_f32_16x16x32_bf16 v[20:23], v[198:201], v[182:185], v[20:23]
	v_mfma_f32_16x16x32_bf16 v[16:19], v[228:231], v[182:185], v[16:19]
	v_mfma_f32_16x16x32_bf16 v[4:7], v[198:201], v[190:193], v[4:7]
	v_mfma_f32_16x16x32_bf16 v[0:3], v[228:231], v[190:193], v[0:3]
	s_setprio 0
	s_add_i32 vcc_lo, vcc_lo, 2
	s_add_u32 s26, s26, 0x100
	s_addc_u32 s27, s27, 0
	s_add_u32 s65, s65, 0x100
	s_addc_u32 s97, s97, 0
	s_cmp_gt_u32 vcc_lo, 29
	s_barrier
	s_cbranch_scc0 .LBB0_120
	s_ashr_i32 s26, s42, 31
	s_lshr_b32 s26, s26, 29
	s_add_i32 s26, s42, s26
	s_ashr_i32 s26, s26, 3
	s_mul_i32 s26, s26, 6
	s_ashr_i32 s27, s26, 31
	s_lshl_b64 s[26:27], s[26:27], 13
	s_add_u32 s34, s74, s26
	s_addc_u32 s35, s76, s27
	s_lshl_b32 s26, s96, 8
	s_ashr_i32 s27, s26, 31
	s_lshl_b64 s[28:29], s[26:27], 2
	s_add_u32 s28, s34, s28
	s_addc_u32 s29, s35, s29
	s_add_u32 s28, s28, s83
	s_addc_u32 s29, s29, 0
	global_load_dwordx4 v[84:87], v176, s[28:29] offset:16
	global_load_dwordx4 v[92:95], v176, s[28:29]
	global_load_dwordx4 v[72:75], v176, s[28:29] offset:528
	global_load_dwordx4 v[76:79], v176, s[28:29] offset:512
	v_readlane_b32 s34, v255, 22
	v_readlane_b32 s35, v255, 23
	v_lshl_add_u32 v166, s42, 8, v159
	v_or_b32_e32 v167, s26, v158
	v_lshlrev_b32_e32 v164, 2, v167
	v_lshl_add_u32 v164, v166, 13, v164
	v_lshlrev_b32_e32 v165, 1, v167
	v_lshl_add_u32 v165, v166, 12, v165
	s_and_b64 vcc, exec, s[44:45]
	s_cbranch_vccnz .Lepr1_f32
	v_add_u32_e32 v166, 0x0, v165
	global_load_dwordx4 v[168:171], v166, s[34:35] offset:0
	v_add_u32_e32 v166, 0x0, v165
	global_load_dwordx4 v[178:181], v166, s[34:35] offset:256
	v_add_u32_e32 v166, 0x10000, v165
	global_load_dwordx4 v[182:185], v166, s[34:35] offset:0
	v_add_u32_e32 v166, 0x10000, v165
	global_load_dwordx4 v[186:189], v166, s[34:35] offset:256
	v_add_u32_e32 v166, 0x20000, v165
	global_load_dwordx4 v[190:193], v166, s[34:35] offset:0
	v_add_u32_e32 v166, 0x20000, v165
	global_load_dwordx4 v[194:197], v166, s[34:35] offset:256
	v_add_u32_e32 v166, 0x30000, v165
	global_load_dwordx4 v[198:201], v166, s[34:35] offset:0
	v_add_u32_e32 v166, 0x30000, v165
	global_load_dwordx4 v[202:205], v166, s[34:35] offset:256
	v_add_u32_e32 v166, 0x80000, v165
	global_load_dwordx4 v[228:231], v166, s[34:35] offset:0
	s_waitcnt vmcnt(8)
	v_lshlrev_b32_e32 v144, 16, v168
	v_and_b32_e32 v145, 0xffff0000, v168
	v_lshlrev_b32_e32 v146, 16, v169
	v_and_b32_e32 v147, 0xffff0000, v169
	v_lshlrev_b32_e32 v148, 16, v170
	v_and_b32_e32 v149, 0xffff0000, v170
	v_lshlrev_b32_e32 v150, 16, v171
	v_and_b32_e32 v151, 0xffff0000, v171
	v_pk_fma_f32 v[140:141], v[140:141], v[92:93], v[144:145]
	v_pk_fma_f32 v[142:143], v[142:143], v[94:95], v[146:147]
	v_pk_fma_f32 v[136:137], v[136:137], v[84:85], v[148:149]
	v_pk_fma_f32 v[138:139], v[138:139], v[86:87], v[150:151]
	v_cvt_pk_bf16_f32 v140, v140, v141
	v_cvt_pk_bf16_f32 v141, v142, v143
	v_cvt_pk_bf16_f32 v142, v136, v137
	v_cvt_pk_bf16_f32 v143, v138, v139
	v_add_u32_e32 v167, 0x0, v165
	global_store_dwordx4 v167, v[140:143], s[34:35] offset:0
	v_add_u32_e32 v166, 0x80000, v165
	global_load_dwordx4 v[168:171], v166, s[34:35] offset:256
	v_add_u32_e32 v166, 0x90000, v165
	global_load_dwordx4 v[136:139], v166, s[34:35] offset:0
	s_waitcnt vmcnt(10)
; __device__ __forceinline__ float bflo(unsigned w) { return __uint_as_float(w << 16); }
; __device__ __forceinline__ float bfhi(unsigned w) { return __uint_as_float(w & 0xffff0000u); }
; __device__ __forceinline__ u32x4 pack8u(f32x4 a, f32x4 b) { u32x4 w = {cvt_pk_bf16(a[0], a[1]), cvt_pk_bf16(a[2], a[3]), cvt_pk_bf16(b[0], b[1]), cvt_pk_bf16(b[2], b[3])}; return w; }
;     __device__ __forceinline__ void operator()(const AccT& acc, const Unit& u, int wr, int wc, int fr, int fq) const {
;     ...
; #pragma unroll
;         for (int ai = 0; ai < 2; ++ai)
; #pragma unroll
;             for (int m = 0; m < 4; ++m) {
;                 const int row = u.pm * 256 + ai * 128 + wr * 64 + m * 16 + fr;
; #pragma unroll
;                 for (int bj = 0; bj < 2; ++bj) {
;                     const size_t off = (size_t)row * D + u.pn * 256 + bj * 128 + wc * 32 + fq * 8;
;                     f32x4 x0, x1;
;                     if (XINF) { x0 = *(const f32x4*)(XINF + off); x1 = *(const f32x4*)(XINF + off + 4); }
;                     else { const u32x4 w = *(const u32x4*)(XIN16 + off); x0 = (f32x4){bflo(w[0]), bfhi(w[0]), bflo(w[1]), bfhi(w[1])}; x1 = (f32x4){bflo(w[2]), bfhi(w[2]), bflo(w[3]), bfhi(w[3])}; }
;                     *(u32x4*)(XOUT + off) = pack8u(x0 + gt[bj][0] * acc[ai][bj][m][0], x1 + gt[bj][1] * acc[ai][bj][m][1]);
;                 }
;             }
	v_lshlrev_b32_e32 v144, 16, v178
	v_and_b32_e32 v145, 0xffff0000, v178
	v_lshlrev_b32_e32 v146, 16, v179
	v_and_b32_e32 v147, 0xffff0000, v179
	v_lshlrev_b32_e32 v148, 16, v180
	v_and_b32_e32 v149, 0xffff0000, v180
	v_lshlrev_b32_e32 v150, 16, v181
	v_and_b32_e32 v151, 0xffff0000, v181
	v_pk_fma_f32 v[132:133], v[132:133], v[76:77], v[144:145]
	v_pk_fma_f32 v[134:135], v[134:135], v[78:79], v[146:147]
	v_pk_fma_f32 v[128:129], v[128:129], v[72:73], v[148:149]
	v_pk_fma_f32 v[130:131], v[130:131], v[74:75], v[150:151]
	v_cvt_pk_bf16_f32 v132, v132, v133
	v_cvt_pk_bf16_f32 v133, v134, v135
	v_cvt_pk_bf16_f32 v134, v128, v129
	v_cvt_pk_bf16_f32 v135, v130, v131
	v_add_u32_e32 v167, 0x0, v165
	global_store_dwordx4 v167, v[132:135], s[34:35] offset:256
	v_add_u32_e32 v166, 0x90000, v165
	global_load_dwordx4 v[178:181], v166, s[34:35] offset:256
	v_add_u32_e32 v166, 0xa0000, v165
	global_load_dwordx4 v[128:131], v166, s[34:35] offset:0
	s_waitcnt vmcnt(12)
	v_lshlrev_b32_e32 v144, 16, v182
	v_and_b32_e32 v145, 0xffff0000, v182
	v_lshlrev_b32_e32 v146, 16, v183
	v_and_b32_e32 v147, 0xffff0000, v183
	v_lshlrev_b32_e32 v148, 16, v184
	v_and_b32_e32 v149, 0xffff0000, v184
	v_lshlrev_b32_e32 v150, 16, v185
	v_and_b32_e32 v151, 0xffff0000, v185
	v_pk_fma_f32 v[124:125], v[124:125], v[92:93], v[144:145]
	v_pk_fma_f32 v[126:127], v[126:127], v[94:95], v[146:147]
	v_pk_fma_f32 v[120:121], v[120:121], v[84:85], v[148:149]
	v_pk_fma_f32 v[122:123], v[122:123], v[86:87], v[150:151]
	v_cvt_pk_bf16_f32 v124, v124, v125
	v_cvt_pk_bf16_f32 v125, v126, v127
	v_cvt_pk_bf16_f32 v126, v120, v121
	v_cvt_pk_bf16_f32 v127, v122, v123
	v_add_u32_e32 v167, 0x10000, v165
	global_store_dwordx4 v167, v[124:127], s[34:35] offset:0
	v_add_u32_e32 v166, 0xa0000, v165
	global_load_dwordx4 v[182:185], v166, s[34:35] offset:256
	v_add_u32_e32 v166, 0xb0000, v165
	global_load_dwordx4 v[120:123], v166, s[34:35] offset:0
	s_waitcnt vmcnt(14)
	v_lshlrev_b32_e32 v144, 16, v186
	v_and_b32_e32 v145, 0xffff0000, v186
	v_lshlrev_b32_e32 v146, 16, v187
	v_and_b32_e32 v147, 0xffff0000, v187
	v_lshlrev_b32_e32 v148, 16, v188
	v_and_b32_e32 v149, 0xffff0000, v188
	v_lshlrev_b32_e32 v150, 16, v189
	v_and_b32_e32 v151, 0xffff0000, v189
	v_pk_fma_f32 v[116:117], v[116:117], v[76:77], v[144:145]
	v_pk_fma_f32 v[118:119], v[118:119], v[78:79], v[146:147]
	v_pk_fma_f32 v[112:113], v[112:113], v[72:73], v[148:149]
	v_pk_fma_f32 v[114:115], v[114:115], v[74:75], v[150:151]
	v_cvt_pk_bf16_f32 v116, v116, v117
	v_cvt_pk_bf16_f32 v117, v118, v119
	v_cvt_pk_bf16_f32 v118, v112, v113
	v_cvt_pk_bf16_f32 v119, v114, v115
	v_add_u32_e32 v167, 0x10000, v165
	global_store_dwordx4 v167, v[116:119], s[34:35] offset:256
	v_add_u32_e32 v166, 0xb0000, v165
	global_load_dwordx4 v[186:189], v166, s[34:35] offset:256
	s_waitcnt vmcnt(15)
	v_lshlrev_b32_e32 v144, 16, v190
	v_and_b32_e32 v145, 0xffff0000, v190
	v_lshlrev_b32_e32 v146, 16, v191
	v_and_b32_e32 v147, 0xffff0000, v191
	v_lshlrev_b32_e32 v148, 16, v192
	v_and_b32_e32 v149, 0xffff0000, v192
	v_lshlrev_b32_e32 v150, 16, v193
	v_and_b32_e32 v151, 0xffff0000, v193
	v_pk_fma_f32 v[108:109], v[108:109], v[92:93], v[144:145]
	v_pk_fma_f32 v[110:111], v[110:111], v[94:95], v[146:147]
	v_pk_fma_f32 v[104:105], v[104:105], v[84:85], v[148:149]
	v_pk_fma_f32 v[106:107], v[106:107], v[86:87], v[150:151]
	v_cvt_pk_bf16_f32 v108, v108, v109
	v_cvt_pk_bf16_f32 v109, v110, v111
	v_cvt_pk_bf16_f32 v110, v104, v105
	v_cvt_pk_bf16_f32 v111, v106, v107
	v_add_u32_e32 v167, 0x20000, v165
	global_store_dwordx4 v167, v[108:111], s[34:35] offset:0
	s_waitcnt vmcnt(15)
	v_lshlrev_b32_e32 v144, 16, v194
	v_and_b32_e32 v145, 0xffff0000, v194
	v_lshlrev_b32_e32 v146, 16, v195
	v_and_b32_e32 v147, 0xffff0000, v195
	v_lshlrev_b32_e32 v148, 16, v196
	v_and_b32_e32 v149, 0xffff0000, v196
	v_lshlrev_b32_e32 v150, 16, v197
	v_and_b32_e32 v151, 0xffff0000, v197
	v_pk_fma_f32 v[100:101], v[100:101], v[76:77], v[144:145]
	v_pk_fma_f32 v[102:103], v[102:103], v[78:79], v[146:147]
	v_pk_fma_f32 v[96:97], v[96:97], v[72:73], v[148:149]
	v_pk_fma_f32 v[98:99], v[98:99], v[74:75], v[150:151]
	v_cvt_pk_bf16_f32 v100, v100, v101
	v_cvt_pk_bf16_f32 v101, v102, v103
	v_cvt_pk_bf16_f32 v102, v96, v97
	v_cvt_pk_bf16_f32 v103, v98, v99
	v_add_u32_e32 v167, 0x20000, v165
	global_store_dwordx4 v167, v[100:103], s[34:35] offset:256
	s_waitcnt vmcnt(15)
	v_lshlrev_b32_e32 v144, 16, v198
	v_and_b32_e32 v145, 0xffff0000, v198
	v_lshlrev_b32_e32 v146, 16, v199
	v_and_b32_e32 v147, 0xffff0000, v199
	v_lshlrev_b32_e32 v148, 16, v200
	v_and_b32_e32 v149, 0xffff0000, v200
	v_lshlrev_b32_e32 v150, 16, v201
	v_and_b32_e32 v151, 0xffff0000, v201
	v_pk_fma_f32 v[88:89], v[88:89], v[92:93], v[144:145]
	v_pk_fma_f32 v[90:91], v[90:91], v[94:95], v[146:147]
	v_pk_fma_f32 v[80:81], v[80:81], v[84:85], v[148:149]
	v_pk_fma_f32 v[82:83], v[82:83], v[86:87], v[150:151]
	v_cvt_pk_bf16_f32 v88, v88, v89
	v_cvt_pk_bf16_f32 v89, v90, v91
	v_cvt_pk_bf16_f32 v90, v80, v81
	v_cvt_pk_bf16_f32 v91, v82, v83
	v_add_u32_e32 v167, 0x30000, v165
	global_store_dwordx4 v167, v[88:91], s[34:35] offset:0
	s_waitcnt vmcnt(15)
	v_lshlrev_b32_e32 v144, 16, v202
	v_and_b32_e32 v145, 0xffff0000, v202
	v_lshlrev_b32_e32 v146, 16, v203
	v_and_b32_e32 v147, 0xffff0000, v203
	v_lshlrev_b32_e32 v148, 16, v204
	v_and_b32_e32 v149, 0xffff0000, v204
	v_lshlrev_b32_e32 v150, 16, v205
	v_and_b32_e32 v151, 0xffff0000, v205
	v_pk_fma_f32 v[68:69], v[68:69], v[76:77], v[144:145]
	v_pk_fma_f32 v[70:71], v[70:71], v[78:79], v[146:147]
	v_pk_fma_f32 v[64:65], v[64:65], v[72:73], v[148:149]
	v_pk_fma_f32 v[66:67], v[66:67], v[74:75], v[150:151]
	v_cvt_pk_bf16_f32 v68, v68, v69
	v_cvt_pk_bf16_f32 v69, v70, v71
	v_cvt_pk_bf16_f32 v70, v64, v65
	v_cvt_pk_bf16_f32 v71, v66, v67
	v_add_u32_e32 v167, 0x30000, v165
	global_store_dwordx4 v167, v[68:71], s[34:35] offset:256
	s_waitcnt vmcnt(15)
; __device__ __forceinline__ float bflo(unsigned w) { return __uint_as_float(w << 16); }
; __device__ __forceinline__ float bfhi(unsigned w) { return __uint_as_float(w & 0xffff0000u); }
; __device__ __forceinline__ u32x4 pack8u(f32x4 a, f32x4 b) { u32x4 w = {cvt_pk_bf16(a[0], a[1]), cvt_pk_bf16(a[2], a[3]), cvt_pk_bf16(b[0], b[1]), cvt_pk_bf16(b[2], b[3])}; return w; }
;     __device__ __forceinline__ void operator()(const AccT& acc, const Unit& u, int wr, int wc, int fr, int fq) const {
;     ...
; #pragma unroll
;         for (int ai = 0; ai < 2; ++ai)
; #pragma unroll
;             for (int m = 0; m < 4; ++m) {
;                 const int row = u.pm * 256 + ai * 128 + wr * 64 + m * 16 + fr;
; #pragma unroll
;                 for (int bj = 0; bj < 2; ++bj) {
;                     const size_t off = (size_t)row * D + u.pn * 256 + bj * 128 + wc * 32 + fq * 8;
;                     f32x4 x0, x1;
;                     if (XINF) { x0 = *(const f32x4*)(XINF + off); x1 = *(const f32x4*)(XINF + off + 4); }
;                     else { const u32x4 w = *(const u32x4*)(XIN16 + off); x0 = (f32x4){bflo(w[0]), bfhi(w[0]), bflo(w[1]), bfhi(w[1])}; x1 = (f32x4){bflo(w[2]), bfhi(w[2]), bflo(w[3]), bfhi(w[3])}; }
;                     *(u32x4*)(XOUT + off) = pack8u(x0 + gt[bj][0] * acc[ai][bj][m][0], x1 + gt[bj][1] * acc[ai][bj][m][1]);
;                 }
;             }
	v_lshlrev_b32_e32 v144, 16, v228
	v_and_b32_e32 v145, 0xffff0000, v228
	v_lshlrev_b32_e32 v146, 16, v229
	v_and_b32_e32 v147, 0xffff0000, v229
	v_lshlrev_b32_e32 v148, 16, v230
	v_and_b32_e32 v149, 0xffff0000, v230
	v_lshlrev_b32_e32 v150, 16, v231
	v_and_b32_e32 v151, 0xffff0000, v231
	v_pk_fma_f32 v[60:61], v[60:61], v[92:93], v[144:145]
	v_pk_fma_f32 v[62:63], v[62:63], v[94:95], v[146:147]
	v_pk_fma_f32 v[56:57], v[56:57], v[84:85], v[148:149]
	v_pk_fma_f32 v[58:59], v[58:59], v[86:87], v[150:151]
	v_cvt_pk_bf16_f32 v60, v60, v61
	v_cvt_pk_bf16_f32 v61, v62, v63
	v_cvt_pk_bf16_f32 v62, v56, v57
	v_cvt_pk_bf16_f32 v63, v58, v59
	v_add_u32_e32 v167, 0x80000, v165
	global_store_dwordx4 v167, v[60:63], s[34:35] offset:0
	s_waitcnt vmcnt(14)
	v_lshlrev_b32_e32 v144, 16, v168
	v_and_b32_e32 v145, 0xffff0000, v168
	v_lshlrev_b32_e32 v146, 16, v169
	v_and_b32_e32 v147, 0xffff0000, v169
	v_lshlrev_b32_e32 v148, 16, v170
	v_and_b32_e32 v149, 0xffff0000, v170
	v_lshlrev_b32_e32 v150, 16, v171
	v_and_b32_e32 v151, 0xffff0000, v171
	v_pk_fma_f32 v[52:53], v[52:53], v[76:77], v[144:145]
	v_pk_fma_f32 v[54:55], v[54:55], v[78:79], v[146:147]
	v_pk_fma_f32 v[48:49], v[48:49], v[72:73], v[148:149]
	v_pk_fma_f32 v[50:51], v[50:51], v[74:75], v[150:151]
	v_cvt_pk_bf16_f32 v52, v52, v53
	v_cvt_pk_bf16_f32 v53, v54, v55
	v_cvt_pk_bf16_f32 v54, v48, v49
	v_cvt_pk_bf16_f32 v55, v50, v51
	v_add_u32_e32 v167, 0x80000, v165
	global_store_dwordx4 v167, v[52:55], s[34:35] offset:256
	s_waitcnt vmcnt(14)
	v_lshlrev_b32_e32 v144, 16, v136
	v_and_b32_e32 v145, 0xffff0000, v136
	v_lshlrev_b32_e32 v146, 16, v137
	v_and_b32_e32 v147, 0xffff0000, v137
	v_lshlrev_b32_e32 v148, 16, v138
	v_and_b32_e32 v149, 0xffff0000, v138
	v_lshlrev_b32_e32 v150, 16, v139
	v_and_b32_e32 v151, 0xffff0000, v139
	v_pk_fma_f32 v[44:45], v[44:45], v[92:93], v[144:145]
	v_pk_fma_f32 v[46:47], v[46:47], v[94:95], v[146:147]
	v_pk_fma_f32 v[40:41], v[40:41], v[84:85], v[148:149]
	v_pk_fma_f32 v[42:43], v[42:43], v[86:87], v[150:151]
	v_cvt_pk_bf16_f32 v44, v44, v45
	v_cvt_pk_bf16_f32 v45, v46, v47
	v_cvt_pk_bf16_f32 v46, v40, v41
	v_cvt_pk_bf16_f32 v47, v42, v43
	v_add_u32_e32 v167, 0x90000, v165
	global_store_dwordx4 v167, v[44:47], s[34:35] offset:0
	s_waitcnt vmcnt(13)
	v_lshlrev_b32_e32 v144, 16, v178
	v_and_b32_e32 v145, 0xffff0000, v178
	v_lshlrev_b32_e32 v146, 16, v179
	v_and_b32_e32 v147, 0xffff0000, v179
	v_lshlrev_b32_e32 v148, 16, v180
	v_and_b32_e32 v149, 0xffff0000, v180
	v_lshlrev_b32_e32 v150, 16, v181
	v_and_b32_e32 v151, 0xffff0000, v181
	v_pk_fma_f32 v[36:37], v[36:37], v[76:77], v[144:145]
	v_pk_fma_f32 v[38:39], v[38:39], v[78:79], v[146:147]
	v_pk_fma_f32 v[32:33], v[32:33], v[72:73], v[148:149]
	v_pk_fma_f32 v[34:35], v[34:35], v[74:75], v[150:151]
	v_cvt_pk_bf16_f32 v36, v36, v37
	v_cvt_pk_bf16_f32 v37, v38, v39
	v_cvt_pk_bf16_f32 v38, v32, v33
	v_cvt_pk_bf16_f32 v39, v34, v35
	v_add_u32_e32 v167, 0x90000, v165
	global_store_dwordx4 v167, v[36:39], s[34:35] offset:256
	s_waitcnt vmcnt(13)
	v_lshlrev_b32_e32 v144, 16, v128
	v_and_b32_e32 v145, 0xffff0000, v128
	v_lshlrev_b32_e32 v146, 16, v129
	v_and_b32_e32 v147, 0xffff0000, v129
	v_lshlrev_b32_e32 v148, 16, v130
	v_and_b32_e32 v149, 0xffff0000, v130
	v_lshlrev_b32_e32 v150, 16, v131
	v_and_b32_e32 v151, 0xffff0000, v131
	v_pk_fma_f32 v[28:29], v[28:29], v[92:93], v[144:145]
	v_pk_fma_f32 v[30:31], v[30:31], v[94:95], v[146:147]
	v_pk_fma_f32 v[24:25], v[24:25], v[84:85], v[148:149]
	v_pk_fma_f32 v[26:27], v[26:27], v[86:87], v[150:151]
	v_cvt_pk_bf16_f32 v28, v28, v29
	v_cvt_pk_bf16_f32 v29, v30, v31
	v_cvt_pk_bf16_f32 v30, v24, v25
	v_cvt_pk_bf16_f32 v31, v26, v27
	v_add_u32_e32 v167, 0xa0000, v165
	global_store_dwordx4 v167, v[28:31], s[34:35] offset:0
	s_waitcnt vmcnt(12)
	v_lshlrev_b32_e32 v144, 16, v182
	v_and_b32_e32 v145, 0xffff0000, v182
	v_lshlrev_b32_e32 v146, 16, v183
	v_and_b32_e32 v147, 0xffff0000, v183
	v_lshlrev_b32_e32 v148, 16, v184
	v_and_b32_e32 v149, 0xffff0000, v184
	v_lshlrev_b32_e32 v150, 16, v185
	v_and_b32_e32 v151, 0xffff0000, v185
	v_pk_fma_f32 v[20:21], v[20:21], v[76:77], v[144:145]
	v_pk_fma_f32 v[22:23], v[22:23], v[78:79], v[146:147]
	v_pk_fma_f32 v[16:17], v[16:17], v[72:73], v[148:149]
	v_pk_fma_f32 v[18:19], v[18:19], v[74:75], v[150:151]
	v_cvt_pk_bf16_f32 v20, v20, v21
	v_cvt_pk_bf16_f32 v21, v22, v23
	v_cvt_pk_bf16_f32 v22, v16, v17
	v_cvt_pk_bf16_f32 v23, v18, v19
	v_add_u32_e32 v167, 0xa0000, v165
	global_store_dwordx4 v167, v[20:23], s[34:35] offset:256
	s_waitcnt vmcnt(12)
	v_lshlrev_b32_e32 v144, 16, v120
	v_and_b32_e32 v145, 0xffff0000, v120
	v_lshlrev_b32_e32 v146, 16, v121
	v_and_b32_e32 v147, 0xffff0000, v121
	v_lshlrev_b32_e32 v148, 16, v122
	v_and_b32_e32 v149, 0xffff0000, v122
	v_lshlrev_b32_e32 v150, 16, v123
	v_and_b32_e32 v151, 0xffff0000, v123
	v_pk_fma_f32 v[12:13], v[12:13], v[92:93], v[144:145]
	v_pk_fma_f32 v[14:15], v[14:15], v[94:95], v[146:147]
	v_pk_fma_f32 v[8:9], v[8:9], v[84:85], v[148:149]
	v_pk_fma_f32 v[10:11], v[10:11], v[86:87], v[150:151]
	v_cvt_pk_bf16_f32 v12, v12, v13
	v_cvt_pk_bf16_f32 v13, v14, v15
	v_cvt_pk_bf16_f32 v14, v8, v9
	v_cvt_pk_bf16_f32 v15, v10, v11
	v_add_u32_e32 v167, 0xb0000, v165
	global_store_dwordx4 v167, v[12:15], s[34:35] offset:0
	s_waitcnt vmcnt(11)
	v_lshlrev_b32_e32 v144, 16, v186
	v_and_b32_e32 v145, 0xffff0000, v186
	v_lshlrev_b32_e32 v146, 16, v187
	v_and_b32_e32 v147, 0xffff0000, v187
	v_lshlrev_b32_e32 v148, 16, v188
	v_and_b32_e32 v149, 0xffff0000, v188
	v_lshlrev_b32_e32 v150, 16, v189
	v_and_b32_e32 v151, 0xffff0000, v189
	v_pk_fma_f32 v[4:5], v[4:5], v[76:77], v[144:145]
	v_pk_fma_f32 v[6:7], v[6:7], v[78:79], v[146:147]
	v_pk_fma_f32 v[0:1], v[0:1], v[72:73], v[148:149]
	v_pk_fma_f32 v[2:3], v[2:3], v[74:75], v[150:151]
	v_cvt_pk_bf16_f32 v4, v4, v5
	v_cvt_pk_bf16_f32 v5, v6, v7
	v_cvt_pk_bf16_f32 v6, v0, v1
	v_cvt_pk_bf16_f32 v7, v2, v3
	v_add_u32_e32 v167, 0xb0000, v165
	global_store_dwordx4 v167, v[4:7], s[34:35] offset:256
	s_mov_b64 s[42:43], exec
	s_branch .Lepr1_latch

; #define PG8_STAGE(bufoff, gbase, voff) do { _Pragma("unroll") for (int _i = 0; _i < 2; ++_i) \
;         __builtin_amdgcn_global_load_lds((const unsigned*)((const char*)(gbase) + (voff)[_i]), (LAS unsigned*)(lds + (bufoff) + ldsw + _i * 8192), 16, 0, 0); } while (0)
; #define PG8_LDA(dst, b, h) do { _Pragma("unroll") for (int m = 0; m < 4; ++m) _Pragma("unroll") for (int k = 0; k < 2; ++k) dst[m][k] = *(const LAS bf16x8*)(lds + PG8_SA(b, h) + aoff + m * 2048 + k * 1024); } while (0)
; #define PG8_LDB(dst, b, h) do { _Pragma("unroll") for (int n = 0; n < 2; ++n) _Pragma("unroll") for (int k = 0; k < 2; ++k) dst[n][k] = *(const LAS bf16x8*)(lds + PG8_SB(b, h) + boff + n * 2048 + k * 1024); } while (0)
; #define PG8_MMA(ai, bj, At, Bt) do { __builtin_amdgcn_s_setprio(1); _Pragma("unroll") for (int m = 0; m < 4; ++m) _Pragma("unroll") for (int n = 0; n < 2; ++n) _Pragma("unroll") for (int k = 0; k < 2; ++k) \
;         acc[ai][bj][m][n] = __builtin_amdgcn_mfma_f32_16x16x32_bf16(Bt[n][k], At[m][k], acc[ai][bj][m][n], 0, 0, 0); __builtin_amdgcn_s_setprio(0); } while (0)
; #define PG8_WAIT_L(n) asm volatile("s_waitcnt lgkmcnt(" #n ")" ::: "memory")
; #define PG8_BAR __builtin_amdgcn_s_barrier()
; #define PG8_SCHED __builtin_amdgcn_sched_barrier(0)
; template <class Epi>
; __device__ __forceinline__ void gemm_phase(LAS unsigned char* lds, const Gemm g, const Epi& E) {
;     ...
;         for (int t = 0; t < nt; t += 2) {
;             const bool last = (t == nt - 2);
;             const char* a1 = cA + (size_t)(t + 1) * kstep;
;             const char* a2 = last ? nA : cA + (size_t)(t + 2) * kstep; const char* b2 = last ? nB : cB + (size_t)(t + 2) * kstep;
;             const char* a3 = a2 + kstep; const char* b3 = b2 + kstep;
;             PG8_LDB(B0, 0, 0); PG8_SCHED; PG8_LDA(At, 0, 0); PG8_STAGE(PG8_SA(1, 1), a1 + hstep, voffA);
;             PG8_WAIT_L(8); PG8_BAR; PG8_WAIT_L(0); PG8_MMA(0, 0, At, B0); PG8_BAR; PG8_SCHED;
;             PG8_LDB(B1, 0, 1); PG8_STAGE(PG8_SB(0, 0), b2, voffB);
;             PG8_BAR; PG8_WAIT_L(0); PG8_MMA(0, 1, At, B1); PG8_BAR;
;             PG8_LDA(At, 0, 1); PG8_STAGE(PG8_SA(0, 0), a2, voffA);
;             PG8_BAR; PG8_WAIT_L(0); PG8_MMA(1, 0, At, B0); PG8_BAR; PG8_SCHED;
;             PG8_STAGE(PG8_SB(0, 1), b2 + hstep, voffB);
.LBB0_211:
	s_add_u32 s28, s26, 0xfffc0080
	s_addc_u32 s29, s27, -1
	s_add_i32 s34, 0, 0x10000
	v_add_u32_e32 v150, s34, v159
	ds_read_b128 v[138:141], v150
	ds_read_b128 v[142:145], v150 offset:1024
	ds_read_b128 v[146:149], v150 offset:2048
	ds_read_b128 v[150:153], v150 offset:3072
	s_cmp_eq_u32 vcc_hi, 12
	s_cselect_b32 s37, s38, s29
	s_cselect_b32 s36, s39, s28
	s_cselect_b32 s29, s43, vcc_lo
	s_cselect_b32 s28, s49, s65
	v_lshl_add_u64 v[190:191], s[26:27], 0, v[134:135]
	s_add_i32 m0, s74, 0xc000
	ds_read_b128 v[154:157], v161
	ds_read_b128 v[162:165], v161 offset:1024
	ds_read_b128 v[166:169], v161 offset:2048
	ds_read_b128 v[170:173], v161 offset:3072
	ds_read_b128 v[174:177], v161 offset:4096
	ds_read_b128 v[178:181], v161 offset:5120
	ds_read_b128 v[182:185], v161 offset:6144
	ds_read_b128 v[186:189], v161 offset:7168
	global_load_lds_dwordx4 v[190:191], off
	s_add_i32 m0, s74, 0xe000
	v_lshl_add_u64 v[190:191], s[26:27], 0, v[136:137]
	global_load_lds_dwordx4 v[190:191], off
	s_waitcnt lgkmcnt(8)
	s_barrier
	s_waitcnt lgkmcnt(0)
	s_setprio 1
	v_mfma_f32_16x16x32_bf16 v[124:127], v[138:141], v[154:157], v[124:127]
	v_mfma_f32_16x16x32_bf16 v[120:123], v[146:149], v[154:157], v[120:123]
	v_mfma_f32_16x16x32_bf16 v[108:111], v[138:141], v[166:169], v[108:111]
	v_mfma_f32_16x16x32_bf16 v[104:107], v[146:149], v[166:169], v[104:107]
	v_mfma_f32_16x16x32_bf16 v[92:95], v[138:141], v[174:177], v[92:95]
	v_mfma_f32_16x16x32_bf16 v[88:91], v[146:149], v[174:177], v[88:91]
	v_mfma_f32_16x16x32_bf16 v[76:79], v[138:141], v[182:185], v[76:79]
	v_mfma_f32_16x16x32_bf16 v[72:75], v[146:149], v[182:185], v[72:75]
	v_mfma_f32_16x16x32_bf16 v[124:127], v[142:145], v[162:165], v[124:127]
	v_mfma_f32_16x16x32_bf16 v[120:123], v[150:153], v[162:165], v[120:123]
	v_mfma_f32_16x16x32_bf16 v[108:111], v[142:145], v[170:173], v[108:111]
	v_mfma_f32_16x16x32_bf16 v[104:107], v[150:153], v[170:173], v[104:107]
	v_mfma_f32_16x16x32_bf16 v[92:95], v[142:145], v[178:181], v[92:95]
	v_mfma_f32_16x16x32_bf16 v[88:91], v[150:153], v[178:181], v[88:91]
	v_mfma_f32_16x16x32_bf16 v[76:79], v[142:145], v[186:189], v[76:79]
	v_mfma_f32_16x16x32_bf16 v[72:75], v[150:153], v[186:189], v[72:75]
	s_setprio 0
	s_barrier
	s_add_i32 s46, 0, 0x14000
	s_add_i32 s34, s34, s71
	v_add_u32_e32 v202, s46, v159
	v_lshl_add_u64 v[206:207], s[28:29], 0, v[208:209]
	s_mov_b32 m0, s34
	ds_read_b128 v[190:193], v202
	ds_read_b128 v[194:197], v202 offset:1024
	ds_read_b128 v[198:201], v202 offset:2048
	ds_read_b128 v[202:205], v202 offset:3072
	global_load_lds_dwordx4 v[206:207], off
	s_add_i32 m0, s34, 0x2000
	v_lshl_add_u64 v[220:221], s[28:29], 0, v[132:133]
	global_load_lds_dwordx4 v[220:221], off
	s_barrier
	s_waitcnt lgkmcnt(0)
	s_setprio 1
	v_mfma_f32_16x16x32_bf16 v[116:119], v[190:193], v[154:157], v[116:119]
	v_mfma_f32_16x16x32_bf16 v[112:115], v[198:201], v[154:157], v[112:115]
	v_mfma_f32_16x16x32_bf16 v[100:103], v[190:193], v[166:169], v[100:103]
	v_mfma_f32_16x16x32_bf16 v[96:99], v[198:201], v[166:169], v[96:99]
	v_mfma_f32_16x16x32_bf16 v[84:87], v[190:193], v[174:177], v[84:87]
	v_mfma_f32_16x16x32_bf16 v[80:83], v[198:201], v[174:177], v[80:83]
	v_mfma_f32_16x16x32_bf16 v[68:71], v[190:193], v[182:185], v[68:71]
	v_mfma_f32_16x16x32_bf16 v[64:67], v[198:201], v[182:185], v[64:67]
	v_mfma_f32_16x16x32_bf16 v[116:119], v[194:197], v[162:165], v[116:119]
	v_mfma_f32_16x16x32_bf16 v[112:115], v[202:205], v[162:165], v[112:115]
	v_mfma_f32_16x16x32_bf16 v[100:103], v[194:197], v[170:173], v[100:103]
	v_mfma_f32_16x16x32_bf16 v[96:99], v[202:205], v[170:173], v[96:99]
	v_mfma_f32_16x16x32_bf16 v[84:87], v[194:197], v[178:181], v[84:87]
	v_mfma_f32_16x16x32_bf16 v[80:83], v[202:205], v[178:181], v[80:83]
	v_mfma_f32_16x16x32_bf16 v[68:71], v[194:197], v[186:189], v[68:71]
	v_mfma_f32_16x16x32_bf16 v[64:67], v[202:205], v[186:189], v[64:67]
	s_setprio 0
	s_mov_b32 m0, s74
	v_lshl_add_u64 v[228:229], s[36:37], 0, v[128:129]
	s_barrier
	ds_read_b128 v[154:157], v161 offset:16384
	ds_read_b128 v[162:165], v161 offset:17408
	ds_read_b128 v[166:169], v161 offset:18432
	ds_read_b128 v[170:173], v161 offset:19456
	ds_read_b128 v[174:177], v161 offset:20480
	ds_read_b128 v[178:181], v161 offset:21504
	ds_read_b128 v[182:185], v161 offset:22528
	ds_read_b128 v[186:189], v161 offset:23552
	global_load_lds_dwordx4 v[228:229], off
	s_mov_b32 m0, s76
	v_lshl_add_u64 v[230:231], s[36:37], 0, v[130:131]
	global_load_lds_dwordx4 v[230:231], off
	s_barrier
	s_waitcnt lgkmcnt(0)
	s_setprio 1
	v_mfma_f32_16x16x32_bf16 v[60:63], v[138:141], v[154:157], v[60:63]
	v_mfma_f32_16x16x32_bf16 v[56:59], v[146:149], v[154:157], v[56:59]
	v_mfma_f32_16x16x32_bf16 v[44:47], v[138:141], v[166:169], v[44:47]
	v_mfma_f32_16x16x32_bf16 v[40:43], v[146:149], v[166:169], v[40:43]
	v_mfma_f32_16x16x32_bf16 v[28:31], v[138:141], v[174:177], v[28:31]
	v_mfma_f32_16x16x32_bf16 v[24:27], v[146:149], v[174:177], v[24:27]
	v_mfma_f32_16x16x32_bf16 v[12:15], v[138:141], v[182:185], v[12:15]
	v_mfma_f32_16x16x32_bf16 v[8:11], v[146:149], v[182:185], v[8:11]
	v_mfma_f32_16x16x32_bf16 v[60:63], v[142:145], v[162:165], v[60:63]
	v_mfma_f32_16x16x32_bf16 v[56:59], v[150:153], v[162:165], v[56:59]
	v_mfma_f32_16x16x32_bf16 v[44:47], v[142:145], v[170:173], v[44:47]
	v_mfma_f32_16x16x32_bf16 v[40:43], v[150:153], v[170:173], v[40:43]
	v_mfma_f32_16x16x32_bf16 v[28:31], v[142:145], v[178:181], v[28:31]
	v_mfma_f32_16x16x32_bf16 v[24:27], v[150:153], v[178:181], v[24:27]
	v_mfma_f32_16x16x32_bf16 v[12:15], v[142:145], v[186:189], v[12:15]
	v_mfma_f32_16x16x32_bf16 v[8:11], v[150:153], v[186:189], v[8:11]
	s_setprio 0
	s_barrier
; #define PG8_STAGE(bufoff, gbase, voff) do { _Pragma("unroll") for (int _i = 0; _i < 2; ++_i) \
;         __builtin_amdgcn_global_load_lds((const unsigned*)((const char*)(gbase) + (voff)[_i]), (LAS unsigned*)(lds + (bufoff) + ldsw + _i * 8192), 16, 0, 0); } while (0)
; #define PG8_LDA(dst, b, h) do { _Pragma("unroll") for (int m = 0; m < 4; ++m) _Pragma("unroll") for (int k = 0; k < 2; ++k) dst[m][k] = *(const LAS bf16x8*)(lds + PG8_SA(b, h) + aoff + m * 2048 + k * 1024); } while (0)
; #define PG8_LDB(dst, b, h) do { _Pragma("unroll") for (int n = 0; n < 2; ++n) _Pragma("unroll") for (int k = 0; k < 2; ++k) dst[n][k] = *(const LAS bf16x8*)(lds + PG8_SB(b, h) + boff + n * 2048 + k * 1024); } while (0)
; #define PG8_MMA(ai, bj, At, Bt) do { __builtin_amdgcn_s_setprio(1); _Pragma("unroll") for (int m = 0; m < 4; ++m) _Pragma("unroll") for (int n = 0; n < 2; ++n) _Pragma("unroll") for (int k = 0; k < 2; ++k) \
;         acc[ai][bj][m][n] = __builtin_amdgcn_mfma_f32_16x16x32_bf16(Bt[n][k], At[m][k], acc[ai][bj][m][n], 0, 0, 0); __builtin_amdgcn_s_setprio(0); } while (0)
; #define PG8_WAIT_V(n) asm volatile("s_waitcnt vmcnt(" #n ")" ::: "memory")
; #define PG8_WAIT_L(n) asm volatile("s_waitcnt lgkmcnt(" #n ")" ::: "memory")
; #define PG8_BAR __builtin_amdgcn_s_barrier()
; #define PG8_SCHED __builtin_amdgcn_sched_barrier(0)
; template <class Epi>
; __device__ __forceinline__ void gemm_phase(LAS unsigned char* lds, const Gemm g, const Epi& E) {
;     ...
;             PG8_STAGE(PG8_SB(0, 1), b2 + hstep, voffB);
;             PG8_WAIT_V(6); PG8_BAR; PG8_MMA(1, 1, At, B1); PG8_BAR;
;             PG8_LDB(B0, 1, 0); PG8_SCHED; PG8_LDA(At, 1, 0); PG8_STAGE(PG8_SA(0, 1), a2 + hstep, voffA);
;             PG8_WAIT_L(8); PG8_BAR; PG8_WAIT_L(0); PG8_MMA(0, 0, At, B0); PG8_BAR; PG8_SCHED;
;             PG8_LDB(B1, 1, 1); PG8_STAGE(PG8_SB(1, 0), b3, voffB);
;             PG8_BAR; PG8_WAIT_L(0); PG8_MMA(0, 1, At, B1); PG8_BAR;
;             PG8_LDA(At, 1, 1); PG8_STAGE(PG8_SA(1, 0), a3, voffA);
;             PG8_BAR; PG8_WAIT_L(0); PG8_MMA(1, 0, At, B0); PG8_BAR; PG8_SCHED;
;             PG8_STAGE(PG8_SB(1, 1), b3 + hstep, voffB);
	s_add_u32 s34, s28, 0x40000
	s_addc_u32 s35, s29, 0
	s_add_i32 s46, s46, s71
	s_mov_b32 m0, s46
	v_lshl_add_u64 v[138:139], s[34:35], 0, v[208:209]
	global_load_lds_dwordx4 v[138:139], off
	s_add_i32 m0, s46, 0x2000
	v_lshl_add_u64 v[138:139], s[34:35], 0, v[132:133]
	global_load_lds_dwordx4 v[138:139], off
	s_waitcnt vmcnt(6)
	s_barrier
	s_setprio 1
	v_mfma_f32_16x16x32_bf16 v[52:55], v[190:193], v[154:157], v[52:55]
	v_mfma_f32_16x16x32_bf16 v[48:51], v[198:201], v[154:157], v[48:51]
	v_mfma_f32_16x16x32_bf16 v[36:39], v[190:193], v[166:169], v[36:39]
	v_mfma_f32_16x16x32_bf16 v[32:35], v[198:201], v[166:169], v[32:35]
	v_mfma_f32_16x16x32_bf16 v[20:23], v[190:193], v[174:177], v[20:23]
	v_mfma_f32_16x16x32_bf16 v[16:19], v[198:201], v[174:177], v[16:19]
	v_mfma_f32_16x16x32_bf16 v[4:7], v[190:193], v[182:185], v[4:7]
	v_mfma_f32_16x16x32_bf16 v[0:3], v[198:201], v[182:185], v[0:3]
	v_mfma_f32_16x16x32_bf16 v[52:55], v[194:197], v[162:165], v[52:55]
	v_mfma_f32_16x16x32_bf16 v[48:51], v[202:205], v[162:165], v[48:51]
	v_mfma_f32_16x16x32_bf16 v[36:39], v[194:197], v[170:173], v[36:39]
	v_mfma_f32_16x16x32_bf16 v[32:35], v[202:205], v[170:173], v[32:35]
	v_mfma_f32_16x16x32_bf16 v[20:23], v[194:197], v[178:181], v[20:23]
	v_mfma_f32_16x16x32_bf16 v[16:19], v[202:205], v[178:181], v[16:19]
	v_mfma_f32_16x16x32_bf16 v[4:7], v[194:197], v[186:189], v[4:7]
	v_mfma_f32_16x16x32_bf16 v[0:3], v[202:205], v[186:189], v[0:3]
	s_setprio 0
	s_add_i32 s46, 0, 0x18000
	v_add_u32_e32 v150, s46, v159
	s_barrier
	ds_read_b128 v[138:141], v150
	ds_read_b128 v[142:145], v150 offset:1024
	ds_read_b128 v[146:149], v150 offset:2048
	ds_read_b128 v[150:153], v150 offset:3072
	s_add_u32 s34, s36, 0x40000
	s_addc_u32 s35, s37, 0
	s_mov_b32 m0, s78
	v_lshl_add_u64 v[190:191], s[34:35], 0, v[128:129]
	ds_read_b128 v[154:157], v161 offset:32768
	ds_read_b128 v[162:165], v161 offset:33792
	ds_read_b128 v[166:169], v161 offset:34816
	ds_read_b128 v[170:173], v161 offset:35840
	ds_read_b128 v[174:177], v161 offset:36864
	ds_read_b128 v[178:181], v161 offset:37888
	ds_read_b128 v[182:185], v161 offset:38912
	ds_read_b128 v[186:189], v161 offset:39936
	global_load_lds_dwordx4 v[190:191], off
	s_mov_b32 m0, s79
	v_lshl_add_u64 v[190:191], s[34:35], 0, v[130:131]
	global_load_lds_dwordx4 v[190:191], off
	s_waitcnt lgkmcnt(8)
	s_barrier
	s_waitcnt lgkmcnt(0)
	s_setprio 1
	v_mfma_f32_16x16x32_bf16 v[124:127], v[138:141], v[154:157], v[124:127]
	v_mfma_f32_16x16x32_bf16 v[120:123], v[146:149], v[154:157], v[120:123]
	v_mfma_f32_16x16x32_bf16 v[108:111], v[138:141], v[166:169], v[108:111]
	v_mfma_f32_16x16x32_bf16 v[104:107], v[146:149], v[166:169], v[104:107]
	v_mfma_f32_16x16x32_bf16 v[92:95], v[138:141], v[174:177], v[92:95]
	v_mfma_f32_16x16x32_bf16 v[88:91], v[146:149], v[174:177], v[88:91]
	v_mfma_f32_16x16x32_bf16 v[76:79], v[138:141], v[182:185], v[76:79]
	v_mfma_f32_16x16x32_bf16 v[72:75], v[146:149], v[182:185], v[72:75]
	v_mfma_f32_16x16x32_bf16 v[124:127], v[142:145], v[162:165], v[124:127]
	v_mfma_f32_16x16x32_bf16 v[120:123], v[150:153], v[162:165], v[120:123]
	v_mfma_f32_16x16x32_bf16 v[108:111], v[142:145], v[170:173], v[108:111]
	v_mfma_f32_16x16x32_bf16 v[104:107], v[150:153], v[170:173], v[104:107]
	v_mfma_f32_16x16x32_bf16 v[92:95], v[142:145], v[178:181], v[92:95]
	v_mfma_f32_16x16x32_bf16 v[88:91], v[150:153], v[178:181], v[88:91]
	v_mfma_f32_16x16x32_bf16 v[76:79], v[142:145], v[186:189], v[76:79]
	v_mfma_f32_16x16x32_bf16 v[72:75], v[150:153], v[186:189], v[72:75]
	s_setprio 0
	s_barrier
	s_add_i32 s34, 0, 0x1c000
	s_add_i32 s35, s46, s71
	v_add_u32_e32 v202, s34, v159
	v_lshl_add_u64 v[206:207], v[206:207], 0, s[20:21]
	s_mov_b32 m0, s35
	ds_read_b128 v[190:193], v202
	ds_read_b128 v[194:197], v202 offset:1024
	ds_read_b128 v[198:201], v202 offset:2048
	ds_read_b128 v[202:205], v202 offset:3072
	global_load_lds_dwordx4 v[206:207], off
	s_add_i32 m0, s35, 0x2000
	v_lshl_add_u64 v[206:207], v[220:221], 0, s[20:21]
	global_load_lds_dwordx4 v[206:207], off
	s_barrier
	s_waitcnt lgkmcnt(0)
	s_setprio 1
	v_mfma_f32_16x16x32_bf16 v[116:119], v[190:193], v[154:157], v[116:119]
	v_mfma_f32_16x16x32_bf16 v[112:115], v[198:201], v[154:157], v[112:115]
	v_mfma_f32_16x16x32_bf16 v[100:103], v[190:193], v[166:169], v[100:103]
	v_mfma_f32_16x16x32_bf16 v[96:99], v[198:201], v[166:169], v[96:99]
	v_mfma_f32_16x16x32_bf16 v[84:87], v[190:193], v[174:177], v[84:87]
	v_mfma_f32_16x16x32_bf16 v[80:83], v[198:201], v[174:177], v[80:83]
	v_mfma_f32_16x16x32_bf16 v[68:71], v[190:193], v[182:185], v[68:71]
	v_mfma_f32_16x16x32_bf16 v[64:67], v[198:201], v[182:185], v[64:67]
	v_mfma_f32_16x16x32_bf16 v[116:119], v[194:197], v[162:165], v[116:119]
	v_mfma_f32_16x16x32_bf16 v[112:115], v[202:205], v[162:165], v[112:115]
	v_mfma_f32_16x16x32_bf16 v[100:103], v[194:197], v[170:173], v[100:103]
	v_mfma_f32_16x16x32_bf16 v[96:99], v[202:205], v[170:173], v[96:99]
	v_mfma_f32_16x16x32_bf16 v[84:87], v[194:197], v[178:181], v[84:87]
	v_mfma_f32_16x16x32_bf16 v[80:83], v[202:205], v[178:181], v[80:83]
	v_mfma_f32_16x16x32_bf16 v[68:71], v[194:197], v[186:189], v[68:71]
	v_mfma_f32_16x16x32_bf16 v[64:67], v[202:205], v[186:189], v[64:67]
	s_setprio 0
	s_mov_b32 m0, s82
	v_lshl_add_u64 v[206:207], v[228:229], 0, s[20:21]
	s_barrier
	ds_read_b128 v[154:157], v161 offset:49152
	ds_read_b128 v[162:165], v161 offset:50176
	ds_read_b128 v[166:169], v161 offset:51200
	ds_read_b128 v[170:173], v161 offset:52224
	ds_read_b128 v[174:177], v161 offset:53248
	ds_read_b128 v[178:181], v161 offset:54272
	ds_read_b128 v[182:185], v161 offset:55296
	ds_read_b128 v[186:189], v161 offset:56320
	global_load_lds_dwordx4 v[206:207], off
	s_mov_b32 m0, s83
	v_lshl_add_u64 v[206:207], v[230:231], 0, s[20:21]
	global_load_lds_dwordx4 v[206:207], off
	s_barrier
; __device__ __forceinline__ float bflo(unsigned w) { return __uint_as_float(w << 16); }
; __device__ __forceinline__ float bfhi(unsigned w) { return __uint_as_float(w & 0xffff0000u); }
; __device__ __forceinline__ u32x4 pack8u(f32x4 a, f32x4 b) { u32x4 w = {cvt_pk_bf16(a[0], a[1]), cvt_pk_bf16(a[2], a[3]), cvt_pk_bf16(b[0], b[1]), cvt_pk_bf16(b[2], b[3])}; return w; }
; #define PG8_STAGE(bufoff, gbase, voff) do { _Pragma("unroll") for (int _i = 0; _i < 2; ++_i) \
;         __builtin_amdgcn_global_load_lds((const unsigned*)((const char*)(gbase) + (voff)[_i]), (LAS unsigned*)(lds + (bufoff) + ldsw + _i * 8192), 16, 0, 0); } while (0)
; #define PG8_LDA(dst, b, h) do { _Pragma("unroll") for (int m = 0; m < 4; ++m) _Pragma("unroll") for (int k = 0; k < 2; ++k) dst[m][k] = *(const LAS bf16x8*)(lds + PG8_SA(b, h) + aoff + m * 2048 + k * 1024); } while (0)
; #define PG8_WAIT_V(n) asm volatile("s_waitcnt vmcnt(" #n ")" ::: "memory")
; template <class Epi>
; __device__ __forceinline__ void gemm_phase(LAS unsigned char* lds, const Gemm g, const Epi& E) {
;     ...
;             PG8_WAIT_V(6); PG8_BAR; PG8_MMA(1, 1, At, B1); PG8_BAR;
;             PG8_LDB(B0, 1, 0); PG8_SCHED; PG8_LDA(At, 1, 0); PG8_STAGE(PG8_SA(0, 1), a2 + hstep, voffA);
;             PG8_WAIT_L(8); PG8_BAR; PG8_WAIT_L(0); PG8_MMA(0, 0, At, B0); PG8_BAR; PG8_SCHED;
;             PG8_LDB(B1, 1, 1); PG8_STAGE(PG8_SB(1, 0), b3, voffB);
;             PG8_BAR; PG8_WAIT_L(0); PG8_MMA(0, 1, At, B1); PG8_BAR;
;             PG8_LDA(At, 1, 1); PG8_STAGE(PG8_SA(1, 0), a3, voffA);
;             PG8_BAR; PG8_WAIT_L(0); PG8_MMA(1, 0, At, B0); PG8_BAR; PG8_SCHED;
;             PG8_STAGE(PG8_SB(1, 1), b3 + hstep, voffB);
;             PG8_WAIT_V(6); PG8_BAR; PG8_MMA(1, 1, At, B1); PG8_BAR;
;     __device__ __forceinline__ void operator()(const AccT& acc, const Unit& u, int wr, int wc, int fr, int fq) const {
;     ...
;                     const int c8 = u.pn * 256 + bj * 128 + wc * 32 + fq * 8;
;                     const u32x4 gw = *(const u32x4*)(GATE + (size_t)row * 4096 + SECOND * 2048 + c8);
;                     const f32x4 g0 = {bflo(gw[0]), bfhi(gw[0]), bflo(gw[1]), bfhi(gw[1])}, g1 = {bflo(gw[2]), bfhi(gw[2]), bflo(gw[3]), bfhi(gw[3])};
;                     bf16_t* tp = (bf16_t*)TMP + (size_t)row * 2048 + c8;
;                     if (SECOND == 0) { *(u32x4*)tp = pack8u(g0 * acc[ai][bj][m][0], g1 * acc[ai][bj][m][1]); }
	s_waitcnt lgkmcnt(0)
	s_setprio 1
	v_mfma_f32_16x16x32_bf16 v[60:63], v[138:141], v[154:157], v[60:63]
	v_mfma_f32_16x16x32_bf16 v[56:59], v[146:149], v[154:157], v[56:59]
	v_mfma_f32_16x16x32_bf16 v[44:47], v[138:141], v[166:169], v[44:47]
	v_mfma_f32_16x16x32_bf16 v[40:43], v[146:149], v[166:169], v[40:43]
	v_mfma_f32_16x16x32_bf16 v[28:31], v[138:141], v[174:177], v[28:31]
	v_mfma_f32_16x16x32_bf16 v[24:27], v[146:149], v[174:177], v[24:27]
	v_mfma_f32_16x16x32_bf16 v[12:15], v[138:141], v[182:185], v[12:15]
	v_mfma_f32_16x16x32_bf16 v[8:11], v[146:149], v[182:185], v[8:11]
	v_mfma_f32_16x16x32_bf16 v[60:63], v[142:145], v[162:165], v[60:63]
	v_mfma_f32_16x16x32_bf16 v[56:59], v[150:153], v[162:165], v[56:59]
	v_mfma_f32_16x16x32_bf16 v[44:47], v[142:145], v[170:173], v[44:47]
	v_mfma_f32_16x16x32_bf16 v[40:43], v[150:153], v[170:173], v[40:43]
	v_mfma_f32_16x16x32_bf16 v[28:31], v[142:145], v[178:181], v[28:31]
	v_mfma_f32_16x16x32_bf16 v[24:27], v[150:153], v[178:181], v[24:27]
	v_mfma_f32_16x16x32_bf16 v[12:15], v[142:145], v[186:189], v[12:15]
	v_mfma_f32_16x16x32_bf16 v[8:11], v[150:153], v[186:189], v[8:11]
	s_setprio 0
	s_barrier
	s_add_u32 s28, s28, 0x40080
	s_addc_u32 s29, s29, 0
	s_add_i32 s34, s34, s71
	s_mov_b32 m0, s34
	v_lshl_add_u64 v[138:139], s[28:29], 0, v[208:209]
	global_load_lds_dwordx4 v[138:139], off
	s_add_i32 m0, s34, 0x2000
	v_lshl_add_u64 v[138:139], s[28:29], 0, v[132:133]
	global_load_lds_dwordx4 v[138:139], off
	s_waitcnt vmcnt(6)
	s_barrier
	s_setprio 1
	v_mfma_f32_16x16x32_bf16 v[52:55], v[190:193], v[154:157], v[52:55]
	v_mfma_f32_16x16x32_bf16 v[48:51], v[198:201], v[154:157], v[48:51]
	v_mfma_f32_16x16x32_bf16 v[36:39], v[190:193], v[166:169], v[36:39]
	v_mfma_f32_16x16x32_bf16 v[32:35], v[198:201], v[166:169], v[32:35]
	v_mfma_f32_16x16x32_bf16 v[20:23], v[190:193], v[174:177], v[20:23]
	v_mfma_f32_16x16x32_bf16 v[16:19], v[198:201], v[174:177], v[16:19]
	v_mfma_f32_16x16x32_bf16 v[4:7], v[190:193], v[182:185], v[4:7]
	v_mfma_f32_16x16x32_bf16 v[0:3], v[198:201], v[182:185], v[0:3]
	v_mfma_f32_16x16x32_bf16 v[52:55], v[194:197], v[162:165], v[52:55]
	v_mfma_f32_16x16x32_bf16 v[48:51], v[202:205], v[162:165], v[48:51]
	v_mfma_f32_16x16x32_bf16 v[36:39], v[194:197], v[170:173], v[36:39]
	v_mfma_f32_16x16x32_bf16 v[32:35], v[202:205], v[170:173], v[32:35]
	v_mfma_f32_16x16x32_bf16 v[20:23], v[194:197], v[178:181], v[20:23]
	v_mfma_f32_16x16x32_bf16 v[16:19], v[202:205], v[178:181], v[16:19]
	v_mfma_f32_16x16x32_bf16 v[4:7], v[194:197], v[186:189], v[4:7]
	v_mfma_f32_16x16x32_bf16 v[0:3], v[202:205], v[186:189], v[0:3]
	s_setprio 0
	s_add_i32 vcc_hi, vcc_hi, 2
	s_add_u32 s26, s26, 0x100
	s_addc_u32 s27, s27, 0
	s_add_u32 s65, s65, 0x100
	s_addc_u32 vcc_lo, vcc_lo, 0
	s_cmp_gt_u32 vcc_hi, 13
	s_barrier
	s_cbranch_scc0 .LBB0_211
	v_lshl_add_u32 v140, s42, 8, v158
	v_lshl_or_b32 v141, s96, 8, v160
	v_lshlrev_b32_e32 v141, 1, v141
	v_lshl_add_u32 v138, v140, 13, v141
	v_lshl_add_u32 v139, v140, 12, v141
	s_and_b64 vcc, exec, s[0:1]
	s_cbranch_vccnz .Lepo_second
	v_add_u32_e32 v140, 0x0, v138
	global_load_dwordx4 v[162:165], v140, s[44:45]
	v_add_u32_e32 v140, 0x0, v138
	global_load_dwordx4 v[166:169], v140, s[44:45] offset:256
	v_add_u32_e32 v140, 0x20000, v138
	global_load_dwordx4 v[170:173], v140, s[44:45]
	v_add_u32_e32 v140, 0x20000, v138
	global_load_dwordx4 v[174:177], v140, s[44:45] offset:256
	v_add_u32_e32 v140, 0x40000, v138
	global_load_dwordx4 v[178:181], v140, s[44:45]
	v_add_u32_e32 v140, 0x40000, v138
	global_load_dwordx4 v[182:185], v140, s[44:45] offset:256
	v_add_u32_e32 v140, 0x60000, v138
	global_load_dwordx4 v[186:189], v140, s[44:45]
	v_add_u32_e32 v140, 0x60000, v138
	global_load_dwordx4 v[190:193], v140, s[44:45] offset:256
	v_add_u32_e32 v140, 0x100000, v138
	global_load_dwordx4 v[194:197], v140, s[44:45]
	v_add_u32_e32 v140, 0x100000, v138
	global_load_dwordx4 v[198:201], v140, s[44:45] offset:256
	v_add_u32_e32 v140, 0x120000, v138
	global_load_dwordx4 v[202:205], v140, s[44:45]
	v_add_u32_e32 v140, 0x120000, v138
	global_load_dwordx4 v[228:231], v140, s[44:45] offset:256
	s_waitcnt vmcnt(11)
	v_lshlrev_b32_e32 v142, 16, v162
	v_and_b32_e32 v143, 0xffff0000, v162
	v_lshlrev_b32_e32 v144, 16, v163
	v_and_b32_e32 v145, 0xffff0000, v163
	v_lshlrev_b32_e32 v146, 16, v164
	v_and_b32_e32 v147, 0xffff0000, v164
	v_lshlrev_b32_e32 v148, 16, v165
	v_and_b32_e32 v149, 0xffff0000, v165
	v_pk_mul_f32 v[124:125], v[124:125], v[142:143]
	v_pk_mul_f32 v[126:127], v[126:127], v[144:145]
	v_pk_mul_f32 v[120:121], v[120:121], v[146:147]
	v_pk_mul_f32 v[122:123], v[122:123], v[148:149]
	v_cvt_pk_bf16_f32 v124, v124, v125
	v_cvt_pk_bf16_f32 v125, v126, v127
	v_cvt_pk_bf16_f32 v126, v120, v121
	v_cvt_pk_bf16_f32 v127, v122, v123
	v_add_u32_e32 v141, 0x0, v139
	global_store_dwordx4 v141, v[124:127], s[92:93]
	v_add_u32_e32 v140, 0x140000, v138
	global_load_dwordx4 v[162:165], v140, s[44:45]
	v_add_u32_e32 v140, 0x140000, v138
	global_load_dwordx4 v[120:123], v140, s[44:45] offset:256
	s_waitcnt vmcnt(13)
	v_lshlrev_b32_e32 v142, 16, v166
	v_and_b32_e32 v143, 0xffff0000, v166
	v_lshlrev_b32_e32 v144, 16, v167
	v_and_b32_e32 v145, 0xffff0000, v167
	v_lshlrev_b32_e32 v146, 16, v168
	v_and_b32_e32 v147, 0xffff0000, v168
	v_lshlrev_b32_e32 v148, 16, v169
	v_and_b32_e32 v149, 0xffff0000, v169
	v_pk_mul_f32 v[116:117], v[116:117], v[142:143]
	v_pk_mul_f32 v[118:119], v[118:119], v[144:145]
	v_pk_mul_f32 v[112:113], v[112:113], v[146:147]
	v_pk_mul_f32 v[114:115], v[114:115], v[148:149]
	v_cvt_pk_bf16_f32 v116, v116, v117
	v_cvt_pk_bf16_f32 v117, v118, v119
	v_cvt_pk_bf16_f32 v118, v112, v113
	v_cvt_pk_bf16_f32 v119, v114, v115
	v_add_u32_e32 v141, 0x0, v139
	global_store_dwordx4 v141, v[116:119], s[92:93] offset:256
	v_add_u32_e32 v140, 0x160000, v138
	global_load_dwordx4 v[166:169], v140, s[44:45]
	v_add_u32_e32 v140, 0x160000, v138
	global_load_dwordx4 v[112:115], v140, s[44:45] offset:256
	s_waitcnt vmcnt(15)
; __device__ __forceinline__ float bflo(unsigned w) { return __uint_as_float(w << 16); }
; __device__ __forceinline__ float bfhi(unsigned w) { return __uint_as_float(w & 0xffff0000u); }
; __device__ __forceinline__ u32x4 pack8u(f32x4 a, f32x4 b) { u32x4 w = {cvt_pk_bf16(a[0], a[1]), cvt_pk_bf16(a[2], a[3]), cvt_pk_bf16(b[0], b[1]), cvt_pk_bf16(b[2], b[3])}; return w; }
;     __device__ __forceinline__ void operator()(const AccT& acc, const Unit& u, int wr, int wc, int fr, int fq) const {
;     ...
;                     const int c8 = u.pn * 256 + bj * 128 + wc * 32 + fq * 8;
;                     const u32x4 gw = *(const u32x4*)(GATE + (size_t)row * 4096 + SECOND * 2048 + c8);
;                     const f32x4 g0 = {bflo(gw[0]), bfhi(gw[0]), bflo(gw[1]), bfhi(gw[1])}, g1 = {bflo(gw[2]), bfhi(gw[2]), bflo(gw[3]), bfhi(gw[3])};
;                     bf16_t* tp = (bf16_t*)TMP + (size_t)row * 2048 + c8;
;                     if (SECOND == 0) { *(u32x4*)tp = pack8u(g0 * acc[ai][bj][m][0], g1 * acc[ai][bj][m][1]); }
	v_lshlrev_b32_e32 v142, 16, v170
	v_and_b32_e32 v143, 0xffff0000, v170
	v_lshlrev_b32_e32 v144, 16, v171
	v_and_b32_e32 v145, 0xffff0000, v171
	v_lshlrev_b32_e32 v146, 16, v172
	v_and_b32_e32 v147, 0xffff0000, v172
	v_lshlrev_b32_e32 v148, 16, v173
	v_and_b32_e32 v149, 0xffff0000, v173
	v_pk_mul_f32 v[108:109], v[108:109], v[142:143]
	v_pk_mul_f32 v[110:111], v[110:111], v[144:145]
	v_pk_mul_f32 v[104:105], v[104:105], v[146:147]
	v_pk_mul_f32 v[106:107], v[106:107], v[148:149]
	v_cvt_pk_bf16_f32 v108, v108, v109
	v_cvt_pk_bf16_f32 v109, v110, v111
	v_cvt_pk_bf16_f32 v110, v104, v105
	v_cvt_pk_bf16_f32 v111, v106, v107
	v_add_u32_e32 v141, 0x10000, v139
	global_store_dwordx4 v141, v[108:111], s[92:93]
	s_waitcnt vmcnt(15)
	v_lshlrev_b32_e32 v142, 16, v174
	v_and_b32_e32 v143, 0xffff0000, v174
	v_lshlrev_b32_e32 v144, 16, v175
	v_and_b32_e32 v145, 0xffff0000, v175
	v_lshlrev_b32_e32 v146, 16, v176
	v_and_b32_e32 v147, 0xffff0000, v176
	v_lshlrev_b32_e32 v148, 16, v177
	v_and_b32_e32 v149, 0xffff0000, v177
	v_pk_mul_f32 v[100:101], v[100:101], v[142:143]
	v_pk_mul_f32 v[102:103], v[102:103], v[144:145]
	v_pk_mul_f32 v[96:97], v[96:97], v[146:147]
	v_pk_mul_f32 v[98:99], v[98:99], v[148:149]
	v_cvt_pk_bf16_f32 v100, v100, v101
	v_cvt_pk_bf16_f32 v101, v102, v103
	v_cvt_pk_bf16_f32 v102, v96, v97
	v_cvt_pk_bf16_f32 v103, v98, v99
	v_add_u32_e32 v141, 0x10000, v139
	global_store_dwordx4 v141, v[100:103], s[92:93] offset:256
	s_waitcnt vmcnt(15)
	v_lshlrev_b32_e32 v142, 16, v178
	v_and_b32_e32 v143, 0xffff0000, v178
	v_lshlrev_b32_e32 v144, 16, v179
	v_and_b32_e32 v145, 0xffff0000, v179
	v_lshlrev_b32_e32 v146, 16, v180
	v_and_b32_e32 v147, 0xffff0000, v180
	v_lshlrev_b32_e32 v148, 16, v181
	v_and_b32_e32 v149, 0xffff0000, v181
	v_pk_mul_f32 v[92:93], v[92:93], v[142:143]
	v_pk_mul_f32 v[94:95], v[94:95], v[144:145]
	v_pk_mul_f32 v[88:89], v[88:89], v[146:147]
	v_pk_mul_f32 v[90:91], v[90:91], v[148:149]
	v_cvt_pk_bf16_f32 v92, v92, v93
	v_cvt_pk_bf16_f32 v93, v94, v95
	v_cvt_pk_bf16_f32 v94, v88, v89
	v_cvt_pk_bf16_f32 v95, v90, v91
	v_add_u32_e32 v141, 0x20000, v139
	global_store_dwordx4 v141, v[92:95], s[92:93]
	s_waitcnt vmcnt(15)
	v_lshlrev_b32_e32 v142, 16, v182
	v_and_b32_e32 v143, 0xffff0000, v182
	v_lshlrev_b32_e32 v144, 16, v183
	v_and_b32_e32 v145, 0xffff0000, v183
	v_lshlrev_b32_e32 v146, 16, v184
	v_and_b32_e32 v147, 0xffff0000, v184
	v_lshlrev_b32_e32 v148, 16, v185
	v_and_b32_e32 v149, 0xffff0000, v185
	v_pk_mul_f32 v[84:85], v[84:85], v[142:143]
	v_pk_mul_f32 v[86:87], v[86:87], v[144:145]
	v_pk_mul_f32 v[80:81], v[80:81], v[146:147]
	v_pk_mul_f32 v[82:83], v[82:83], v[148:149]
	v_cvt_pk_bf16_f32 v84, v84, v85
	v_cvt_pk_bf16_f32 v85, v86, v87
	v_cvt_pk_bf16_f32 v86, v80, v81
	v_cvt_pk_bf16_f32 v87, v82, v83
	v_add_u32_e32 v141, 0x20000, v139
	global_store_dwordx4 v141, v[84:87], s[92:93] offset:256
	s_waitcnt vmcnt(15)
	v_lshlrev_b32_e32 v142, 16, v186
	v_and_b32_e32 v143, 0xffff0000, v186
	v_lshlrev_b32_e32 v144, 16, v187
	v_and_b32_e32 v145, 0xffff0000, v187
	v_lshlrev_b32_e32 v146, 16, v188
	v_and_b32_e32 v147, 0xffff0000, v188
	v_lshlrev_b32_e32 v148, 16, v189
	v_and_b32_e32 v149, 0xffff0000, v189
	v_pk_mul_f32 v[76:77], v[76:77], v[142:143]
	v_pk_mul_f32 v[78:79], v[78:79], v[144:145]
	v_pk_mul_f32 v[72:73], v[72:73], v[146:147]
	v_pk_mul_f32 v[74:75], v[74:75], v[148:149]
	v_cvt_pk_bf16_f32 v76, v76, v77
	v_cvt_pk_bf16_f32 v77, v78, v79
	v_cvt_pk_bf16_f32 v78, v72, v73
	v_cvt_pk_bf16_f32 v79, v74, v75
	v_add_u32_e32 v141, 0x30000, v139
	global_store_dwordx4 v141, v[76:79], s[92:93]
	s_waitcnt vmcnt(15)
	v_lshlrev_b32_e32 v142, 16, v190
	v_and_b32_e32 v143, 0xffff0000, v190
	v_lshlrev_b32_e32 v144, 16, v191
	v_and_b32_e32 v145, 0xffff0000, v191
	v_lshlrev_b32_e32 v146, 16, v192
	v_and_b32_e32 v147, 0xffff0000, v192
	v_lshlrev_b32_e32 v148, 16, v193
	v_and_b32_e32 v149, 0xffff0000, v193
	v_pk_mul_f32 v[68:69], v[68:69], v[142:143]
	v_pk_mul_f32 v[70:71], v[70:71], v[144:145]
	v_pk_mul_f32 v[64:65], v[64:65], v[146:147]
	v_pk_mul_f32 v[66:67], v[66:67], v[148:149]
	v_cvt_pk_bf16_f32 v68, v68, v69
	v_cvt_pk_bf16_f32 v69, v70, v71
	v_cvt_pk_bf16_f32 v70, v64, v65
	v_cvt_pk_bf16_f32 v71, v66, v67
	v_add_u32_e32 v141, 0x30000, v139
	global_store_dwordx4 v141, v[68:71], s[92:93] offset:256
	s_waitcnt vmcnt(15)
	v_lshlrev_b32_e32 v142, 16, v194
	v_and_b32_e32 v143, 0xffff0000, v194
	v_lshlrev_b32_e32 v144, 16, v195
	v_and_b32_e32 v145, 0xffff0000, v195
	v_lshlrev_b32_e32 v146, 16, v196
	v_and_b32_e32 v147, 0xffff0000, v196
	v_lshlrev_b32_e32 v148, 16, v197
	v_and_b32_e32 v149, 0xffff0000, v197
	v_pk_mul_f32 v[60:61], v[60:61], v[142:143]
	v_pk_mul_f32 v[62:63], v[62:63], v[144:145]
	v_pk_mul_f32 v[56:57], v[56:57], v[146:147]
	v_pk_mul_f32 v[58:59], v[58:59], v[148:149]
	v_cvt_pk_bf16_f32 v60, v60, v61
	v_cvt_pk_bf16_f32 v61, v62, v63
	v_cvt_pk_bf16_f32 v62, v56, v57
	v_cvt_pk_bf16_f32 v63, v58, v59
	v_add_u32_e32 v141, 0x80000, v139
	global_store_dwordx4 v141, v[60:63], s[92:93]
	s_waitcnt vmcnt(15)
; __device__ __forceinline__ float bflo(unsigned w) { return __uint_as_float(w << 16); }
; __device__ __forceinline__ float bfhi(unsigned w) { return __uint_as_float(w & 0xffff0000u); }
; __device__ __forceinline__ u32x4 pack8u(f32x4 a, f32x4 b) { u32x4 w = {cvt_pk_bf16(a[0], a[1]), cvt_pk_bf16(a[2], a[3]), cvt_pk_bf16(b[0], b[1]), cvt_pk_bf16(b[2], b[3])}; return w; }
; template <class Epi>
; __device__ __forceinline__ void gemm_phase(LAS unsigned char* lds, const Gemm g, const Epi& E) {
;     ...
;         E(acc, cur, wr, wc, fr, fq);
;         if (!has_next) break;
; #pragma unroll
;         for (int a = 0; a < 2; ++a)
; #pragma unroll
;             for (int b = 0; b < 2; ++b)
; #pragma unroll
;                 for (int m = 0; m < 4; ++m)
; #pragma unroll
;                     for (int n = 0; n < 2; ++n) acc[a][b][m][n] = (f32x4){0.f, 0.f, 0.f, 0.f};
;         cur = nxt; cA = nA; cB = nB; ++ui;
;     __device__ __forceinline__ void operator()(const AccT& acc, const Unit& u, int wr, int wc, int fr, int fq) const {
;     ...
;                     const int c8 = u.pn * 256 + bj * 128 + wc * 32 + fq * 8;
;                     const u32x4 gw = *(const u32x4*)(GATE + (size_t)row * 4096 + SECOND * 2048 + c8);
;                     const f32x4 g0 = {bflo(gw[0]), bfhi(gw[0]), bflo(gw[1]), bfhi(gw[1])}, g1 = {bflo(gw[2]), bfhi(gw[2]), bflo(gw[3]), bfhi(gw[3])};
;                     bf16_t* tp = (bf16_t*)TMP + (size_t)row * 2048 + c8;
;                     if (SECOND == 0) { *(u32x4*)tp = pack8u(g0 * acc[ai][bj][m][0], g1 * acc[ai][bj][m][1]); }
	v_lshlrev_b32_e32 v142, 16, v198
	v_and_b32_e32 v143, 0xffff0000, v198
	v_lshlrev_b32_e32 v144, 16, v199
	v_and_b32_e32 v145, 0xffff0000, v199
	v_lshlrev_b32_e32 v146, 16, v200
	v_and_b32_e32 v147, 0xffff0000, v200
	v_lshlrev_b32_e32 v148, 16, v201
	v_and_b32_e32 v149, 0xffff0000, v201
	v_pk_mul_f32 v[52:53], v[52:53], v[142:143]
	v_pk_mul_f32 v[54:55], v[54:55], v[144:145]
	v_pk_mul_f32 v[48:49], v[48:49], v[146:147]
	v_pk_mul_f32 v[50:51], v[50:51], v[148:149]
	v_cvt_pk_bf16_f32 v52, v52, v53
	v_cvt_pk_bf16_f32 v53, v54, v55
	v_cvt_pk_bf16_f32 v54, v48, v49
	v_cvt_pk_bf16_f32 v55, v50, v51
	v_add_u32_e32 v141, 0x80000, v139
	global_store_dwordx4 v141, v[52:55], s[92:93] offset:256
	s_waitcnt vmcnt(15)
	v_lshlrev_b32_e32 v142, 16, v202
	v_and_b32_e32 v143, 0xffff0000, v202
	v_lshlrev_b32_e32 v144, 16, v203
	v_and_b32_e32 v145, 0xffff0000, v203
	v_lshlrev_b32_e32 v146, 16, v204
	v_and_b32_e32 v147, 0xffff0000, v204
	v_lshlrev_b32_e32 v148, 16, v205
	v_and_b32_e32 v149, 0xffff0000, v205
	v_pk_mul_f32 v[44:45], v[44:45], v[142:143]
	v_pk_mul_f32 v[46:47], v[46:47], v[144:145]
	v_pk_mul_f32 v[40:41], v[40:41], v[146:147]
	v_pk_mul_f32 v[42:43], v[42:43], v[148:149]
	v_cvt_pk_bf16_f32 v44, v44, v45
	v_cvt_pk_bf16_f32 v45, v46, v47
	v_cvt_pk_bf16_f32 v46, v40, v41
	v_cvt_pk_bf16_f32 v47, v42, v43
	v_add_u32_e32 v141, 0x90000, v139
	global_store_dwordx4 v141, v[44:47], s[92:93]
	s_waitcnt vmcnt(15)
	v_lshlrev_b32_e32 v142, 16, v228
	v_and_b32_e32 v143, 0xffff0000, v228
	v_lshlrev_b32_e32 v144, 16, v229
	v_and_b32_e32 v145, 0xffff0000, v229
	v_lshlrev_b32_e32 v146, 16, v230
	v_and_b32_e32 v147, 0xffff0000, v230
	v_lshlrev_b32_e32 v148, 16, v231
	v_and_b32_e32 v149, 0xffff0000, v231
	v_pk_mul_f32 v[36:37], v[36:37], v[142:143]
	v_pk_mul_f32 v[38:39], v[38:39], v[144:145]
	v_pk_mul_f32 v[32:33], v[32:33], v[146:147]
	v_pk_mul_f32 v[34:35], v[34:35], v[148:149]
	v_cvt_pk_bf16_f32 v36, v36, v37
	v_cvt_pk_bf16_f32 v37, v38, v39
	v_cvt_pk_bf16_f32 v38, v32, v33
	v_cvt_pk_bf16_f32 v39, v34, v35
	v_add_u32_e32 v141, 0x90000, v139
	global_store_dwordx4 v141, v[36:39], s[92:93] offset:256
	s_waitcnt vmcnt(14)
	v_lshlrev_b32_e32 v142, 16, v162
	v_and_b32_e32 v143, 0xffff0000, v162
	v_lshlrev_b32_e32 v144, 16, v163
	v_and_b32_e32 v145, 0xffff0000, v163
	v_lshlrev_b32_e32 v146, 16, v164
	v_and_b32_e32 v147, 0xffff0000, v164
	v_lshlrev_b32_e32 v148, 16, v165
	v_and_b32_e32 v149, 0xffff0000, v165
	v_pk_mul_f32 v[28:29], v[28:29], v[142:143]
	v_pk_mul_f32 v[30:31], v[30:31], v[144:145]
	v_pk_mul_f32 v[24:25], v[24:25], v[146:147]
	v_pk_mul_f32 v[26:27], v[26:27], v[148:149]
	v_cvt_pk_bf16_f32 v28, v28, v29
	v_cvt_pk_bf16_f32 v29, v30, v31
	v_cvt_pk_bf16_f32 v30, v24, v25
	v_cvt_pk_bf16_f32 v31, v26, v27
	v_add_u32_e32 v141, 0xa0000, v139
	global_store_dwordx4 v141, v[28:31], s[92:93]
	s_waitcnt vmcnt(14)
	v_lshlrev_b32_e32 v142, 16, v120
	v_and_b32_e32 v143, 0xffff0000, v120
	v_lshlrev_b32_e32 v144, 16, v121
	v_and_b32_e32 v145, 0xffff0000, v121
	v_lshlrev_b32_e32 v146, 16, v122
	v_and_b32_e32 v147, 0xffff0000, v122
	v_lshlrev_b32_e32 v148, 16, v123
	v_and_b32_e32 v149, 0xffff0000, v123
	v_pk_mul_f32 v[20:21], v[20:21], v[142:143]
	v_pk_mul_f32 v[22:23], v[22:23], v[144:145]
	v_pk_mul_f32 v[16:17], v[16:17], v[146:147]
	v_pk_mul_f32 v[18:19], v[18:19], v[148:149]
	v_cvt_pk_bf16_f32 v20, v20, v21
	v_cvt_pk_bf16_f32 v21, v22, v23
	v_cvt_pk_bf16_f32 v22, v16, v17
	v_cvt_pk_bf16_f32 v23, v18, v19
	v_add_u32_e32 v141, 0xa0000, v139
	global_store_dwordx4 v141, v[20:23], s[92:93] offset:256
	s_waitcnt vmcnt(13)
	v_lshlrev_b32_e32 v142, 16, v166
	v_and_b32_e32 v143, 0xffff0000, v166
	v_lshlrev_b32_e32 v144, 16, v167
	v_and_b32_e32 v145, 0xffff0000, v167
	v_lshlrev_b32_e32 v146, 16, v168
	v_and_b32_e32 v147, 0xffff0000, v168
	v_lshlrev_b32_e32 v148, 16, v169
	v_and_b32_e32 v149, 0xffff0000, v169
	v_pk_mul_f32 v[12:13], v[12:13], v[142:143]
	v_pk_mul_f32 v[14:15], v[14:15], v[144:145]
	v_pk_mul_f32 v[8:9], v[8:9], v[146:147]
	v_pk_mul_f32 v[10:11], v[10:11], v[148:149]
	v_cvt_pk_bf16_f32 v12, v12, v13
	v_cvt_pk_bf16_f32 v13, v14, v15
	v_cvt_pk_bf16_f32 v14, v8, v9
	v_cvt_pk_bf16_f32 v15, v10, v11
	v_add_u32_e32 v141, 0xb0000, v139
	global_store_dwordx4 v141, v[12:15], s[92:93]
	s_waitcnt vmcnt(13)
	v_lshlrev_b32_e32 v142, 16, v112
	v_and_b32_e32 v143, 0xffff0000, v112
	v_lshlrev_b32_e32 v144, 16, v113
	v_and_b32_e32 v145, 0xffff0000, v113
	v_lshlrev_b32_e32 v146, 16, v114
	v_and_b32_e32 v147, 0xffff0000, v114
	v_lshlrev_b32_e32 v148, 16, v115
	v_and_b32_e32 v149, 0xffff0000, v115
	v_pk_mul_f32 v[4:5], v[4:5], v[142:143]
	v_pk_mul_f32 v[6:7], v[6:7], v[144:145]
	v_pk_mul_f32 v[0:1], v[0:1], v[146:147]
	v_pk_mul_f32 v[2:3], v[2:3], v[148:149]
	v_cvt_pk_bf16_f32 v4, v4, v5
	v_cvt_pk_bf16_f32 v5, v6, v7
	v_cvt_pk_bf16_f32 v6, v0, v1
	v_cvt_pk_bf16_f32 v7, v2, v3
	v_add_u32_e32 v141, 0xb0000, v139
	global_store_dwordx4 v141, v[4:7], s[92:93] offset:256
	s_mov_b64 s[26:27], -1
	s_mov_b64 s[42:43], exec
	s_mov_b64 vcc, 0
	s_branch .LBB0_203

; #define PG8_STAGE(bufoff, gbase, voff) do { _Pragma("unroll") for (int _i = 0; _i < 2; ++_i) \
;         __builtin_amdgcn_global_load_lds((const unsigned*)((const char*)(gbase) + (voff)[_i]), (LAS unsigned*)(lds + (bufoff) + ldsw + _i * 8192), 16, 0, 0); } while (0)
; #define PG8_LDA(dst, b, h) do { _Pragma("unroll") for (int m = 0; m < 4; ++m) _Pragma("unroll") for (int k = 0; k < 2; ++k) dst[m][k] = *(const LAS bf16x8*)(lds + PG8_SA(b, h) + aoff + m * 2048 + k * 1024); } while (0)
; #define PG8_LDB(dst, b, h) do { _Pragma("unroll") for (int n = 0; n < 2; ++n) _Pragma("unroll") for (int k = 0; k < 2; ++k) dst[n][k] = *(const LAS bf16x8*)(lds + PG8_SB(b, h) + boff + n * 2048 + k * 1024); } while (0)
; #define PG8_MMA(ai, bj, At, Bt) do { __builtin_amdgcn_s_setprio(1); _Pragma("unroll") for (int m = 0; m < 4; ++m) _Pragma("unroll") for (int n = 0; n < 2; ++n) _Pragma("unroll") for (int k = 0; k < 2; ++k) \
;         acc[ai][bj][m][n] = __builtin_amdgcn_mfma_f32_16x16x32_bf16(Bt[n][k], At[m][k], acc[ai][bj][m][n], 0, 0, 0); __builtin_amdgcn_s_setprio(0); } while (0)
; #define PG8_WAIT_L(n) asm volatile("s_waitcnt lgkmcnt(" #n ")" ::: "memory")
; #define PG8_BAR __builtin_amdgcn_s_barrier()
; #define PG8_SCHED __builtin_amdgcn_sched_barrier(0)
; template <class Epi>
; __device__ __forceinline__ void gemm_phase(LAS unsigned char* lds, const Gemm g, const Epi& E) {
;     ...
;             PG8_LDB(B0, 0, 0); PG8_SCHED; PG8_LDA(At, 0, 0); PG8_STAGE(PG8_SA(1, 1), a1 + hstep, voffA);
;             PG8_WAIT_L(8); PG8_BAR; PG8_WAIT_L(0); PG8_MMA(0, 0, At, B0); PG8_BAR; PG8_SCHED;
;             PG8_LDB(B1, 0, 1); PG8_STAGE(PG8_SB(0, 0), b2, voffB);
;             PG8_BAR; PG8_WAIT_L(0); PG8_MMA(0, 1, At, B1); PG8_BAR;
;             PG8_LDA(At, 0, 1); PG8_STAGE(PG8_SA(0, 0), a2, voffA);
;             PG8_BAR; PG8_WAIT_L(0); PG8_MMA(1, 0, At, B0); PG8_BAR; PG8_SCHED;
.LBB0_499:
	s_add_u32 s28, s26, 0xfffe0080
	s_addc_u32 s29, s27, -1
	s_add_i32 s34, 0, 0x10000
	v_add_u32_e32 v156, s34, v159
	ds_read_b128 v[144:147], v156
	ds_read_b128 v[148:151], v156 offset:1024
	ds_read_b128 v[152:155], v156 offset:2048
	ds_read_b128 v[162:165], v156 offset:3072
	s_cmp_eq_u32 vcc_lo, 4
	s_cselect_b32 s37, s1, s29
	s_cselect_b32 s36, s31, s28
	s_cselect_b32 s29, s42, s65
	s_cselect_b32 s28, s43, s45
	v_lshl_add_u64 v[156:157], s[26:27], 0, v[140:141]
	s_add_i32 m0, s95, 0xc000
	ds_read_b128 v[166:169], v161
	ds_read_b128 v[170:173], v161 offset:1024
	ds_read_b128 v[174:177], v161 offset:2048
	ds_read_b128 v[178:181], v161 offset:3072
	ds_read_b128 v[182:185], v161 offset:4096
	ds_read_b128 v[186:189], v161 offset:5120
	ds_read_b128 v[190:193], v161 offset:6144
	ds_read_b128 v[194:197], v161 offset:7168
	global_load_lds_dwordx4 v[156:157], off
	s_add_i32 m0, s95, 0xe000
	v_lshl_add_u64 v[156:157], s[26:27], 0, v[142:143]
	global_load_lds_dwordx4 v[156:157], off
	s_waitcnt lgkmcnt(8)
	s_barrier
	s_waitcnt lgkmcnt(0)
	s_setprio 1
	v_mfma_f32_16x16x32_bf16 v[124:127], v[144:147], v[166:169], v[124:127]
	v_mfma_f32_16x16x32_bf16 v[120:123], v[152:155], v[166:169], v[120:123]
	v_mfma_f32_16x16x32_bf16 v[108:111], v[144:147], v[174:177], v[108:111]
	v_mfma_f32_16x16x32_bf16 v[104:107], v[152:155], v[174:177], v[104:107]
	v_mfma_f32_16x16x32_bf16 v[92:95], v[144:147], v[182:185], v[92:95]
	v_mfma_f32_16x16x32_bf16 v[88:91], v[152:155], v[182:185], v[88:91]
	v_mfma_f32_16x16x32_bf16 v[76:79], v[144:147], v[190:193], v[76:79]
	v_mfma_f32_16x16x32_bf16 v[72:75], v[152:155], v[190:193], v[72:75]
	v_mfma_f32_16x16x32_bf16 v[124:127], v[148:151], v[170:173], v[124:127]
	v_mfma_f32_16x16x32_bf16 v[120:123], v[162:165], v[170:173], v[120:123]
	v_mfma_f32_16x16x32_bf16 v[108:111], v[148:151], v[178:181], v[108:111]
	v_mfma_f32_16x16x32_bf16 v[104:107], v[162:165], v[178:181], v[104:107]
	v_mfma_f32_16x16x32_bf16 v[92:95], v[148:151], v[186:189], v[92:95]
	v_mfma_f32_16x16x32_bf16 v[88:91], v[162:165], v[186:189], v[88:91]
	v_mfma_f32_16x16x32_bf16 v[76:79], v[148:151], v[194:197], v[76:79]
	v_mfma_f32_16x16x32_bf16 v[72:75], v[162:165], v[194:197], v[72:75]
	s_setprio 0
	s_barrier
	s_add_i32 vcc_hi, 0, 0x14000
	v_add_u32_e32 v156, vcc_hi, v159
	s_add_i32 s34, s34, s83
	ds_read_b128 v[198:201], v156
	ds_read_b128 v[202:205], v156 offset:1024
	ds_read_b128 v[238:241], v156 offset:2048
	ds_read_b128 v[242:245], v156 offset:3072
	v_lshl_add_u64 v[156:157], s[28:29], 0, v[130:131]
	s_mov_b32 m0, s34
	v_lshl_add_u64 v[206:207], s[28:29], 0, v[134:135]
	global_load_lds_dwordx4 v[156:157], off
	s_add_i32 m0, s34, 0x2000
	s_nop 0
	global_load_lds_dwordx4 v[206:207], off
	s_barrier
	s_waitcnt lgkmcnt(0)
	s_setprio 1
	v_mfma_f32_16x16x32_bf16 v[116:119], v[198:201], v[166:169], v[116:119]
	v_mfma_f32_16x16x32_bf16 v[112:115], v[238:241], v[166:169], v[112:115]
	v_mfma_f32_16x16x32_bf16 v[100:103], v[198:201], v[174:177], v[100:103]
	v_mfma_f32_16x16x32_bf16 v[96:99], v[238:241], v[174:177], v[96:99]
	v_mfma_f32_16x16x32_bf16 v[84:87], v[198:201], v[182:185], v[84:87]
	v_mfma_f32_16x16x32_bf16 v[80:83], v[238:241], v[182:185], v[80:83]
	v_mfma_f32_16x16x32_bf16 v[68:71], v[198:201], v[190:193], v[68:71]
	v_mfma_f32_16x16x32_bf16 v[64:67], v[238:241], v[190:193], v[64:67]
	v_mfma_f32_16x16x32_bf16 v[116:119], v[202:205], v[170:173], v[116:119]
	v_mfma_f32_16x16x32_bf16 v[112:115], v[242:245], v[170:173], v[112:115]
	v_mfma_f32_16x16x32_bf16 v[100:103], v[202:205], v[178:181], v[100:103]
	v_mfma_f32_16x16x32_bf16 v[96:99], v[242:245], v[178:181], v[96:99]
	v_mfma_f32_16x16x32_bf16 v[84:87], v[202:205], v[186:189], v[84:87]
	v_mfma_f32_16x16x32_bf16 v[80:83], v[242:245], v[186:189], v[80:83]
	v_mfma_f32_16x16x32_bf16 v[68:71], v[202:205], v[194:197], v[68:71]
	v_mfma_f32_16x16x32_bf16 v[64:67], v[242:245], v[194:197], v[64:67]
	s_setprio 0
	s_mov_b32 m0, s95
	v_lshl_add_u64 v[220:221], s[36:37], 0, v[128:129]
	s_barrier
	ds_read_b128 v[166:169], v161 offset:16384
	ds_read_b128 v[170:173], v161 offset:17408
	ds_read_b128 v[174:177], v161 offset:18432
	ds_read_b128 v[178:181], v161 offset:19456
	ds_read_b128 v[182:185], v161 offset:20480
	ds_read_b128 v[186:189], v161 offset:21504
	ds_read_b128 v[190:193], v161 offset:22528
	ds_read_b128 v[194:197], v161 offset:23552
	global_load_lds_dwordx4 v[220:221], off
	s_mov_b32 m0, s82
	v_lshl_add_u64 v[228:229], s[36:37], 0, v[132:133]
	global_load_lds_dwordx4 v[228:229], off
	s_barrier
	s_waitcnt lgkmcnt(0)
	s_setprio 1
	v_mfma_f32_16x16x32_bf16 v[60:63], v[144:147], v[166:169], v[60:63]
	v_mfma_f32_16x16x32_bf16 v[56:59], v[152:155], v[166:169], v[56:59]
	v_mfma_f32_16x16x32_bf16 v[44:47], v[144:147], v[174:177], v[44:47]
	v_mfma_f32_16x16x32_bf16 v[40:43], v[152:155], v[174:177], v[40:43]
	v_mfma_f32_16x16x32_bf16 v[28:31], v[144:147], v[182:185], v[28:31]
	v_mfma_f32_16x16x32_bf16 v[24:27], v[152:155], v[182:185], v[24:27]
	v_mfma_f32_16x16x32_bf16 v[12:15], v[144:147], v[190:193], v[12:15]
	v_mfma_f32_16x16x32_bf16 v[8:11], v[152:155], v[190:193], v[8:11]
	v_mfma_f32_16x16x32_bf16 v[60:63], v[148:151], v[170:173], v[60:63]
	v_mfma_f32_16x16x32_bf16 v[56:59], v[162:165], v[170:173], v[56:59]
	v_mfma_f32_16x16x32_bf16 v[44:47], v[148:151], v[178:181], v[44:47]
	v_mfma_f32_16x16x32_bf16 v[40:43], v[162:165], v[178:181], v[40:43]
	v_mfma_f32_16x16x32_bf16 v[28:31], v[148:151], v[186:189], v[28:31]
	v_mfma_f32_16x16x32_bf16 v[24:27], v[162:165], v[186:189], v[24:27]
	v_mfma_f32_16x16x32_bf16 v[12:15], v[148:151], v[194:197], v[12:15]
	v_mfma_f32_16x16x32_bf16 v[8:11], v[162:165], v[194:197], v[8:11]
	s_setprio 0
	s_barrier
; #define PG8_STAGE(bufoff, gbase, voff) do { _Pragma("unroll") for (int _i = 0; _i < 2; ++_i) \
;         __builtin_amdgcn_global_load_lds((const unsigned*)((const char*)(gbase) + (voff)[_i]), (LAS unsigned*)(lds + (bufoff) + ldsw + _i * 8192), 16, 0, 0); } while (0)
; #define PG8_LDA(dst, b, h) do { _Pragma("unroll") for (int m = 0; m < 4; ++m) _Pragma("unroll") for (int k = 0; k < 2; ++k) dst[m][k] = *(const LAS bf16x8*)(lds + PG8_SA(b, h) + aoff + m * 2048 + k * 1024); } while (0)
; #define PG8_LDB(dst, b, h) do { _Pragma("unroll") for (int n = 0; n < 2; ++n) _Pragma("unroll") for (int k = 0; k < 2; ++k) dst[n][k] = *(const LAS bf16x8*)(lds + PG8_SB(b, h) + boff + n * 2048 + k * 1024); } while (0)
; #define PG8_MMA(ai, bj, At, Bt) do { __builtin_amdgcn_s_setprio(1); _Pragma("unroll") for (int m = 0; m < 4; ++m) _Pragma("unroll") for (int n = 0; n < 2; ++n) _Pragma("unroll") for (int k = 0; k < 2; ++k) \
;         acc[ai][bj][m][n] = __builtin_amdgcn_mfma_f32_16x16x32_bf16(Bt[n][k], At[m][k], acc[ai][bj][m][n], 0, 0, 0); __builtin_amdgcn_s_setprio(0); } while (0)
; #define PG8_WAIT_V(n) asm volatile("s_waitcnt vmcnt(" #n ")" ::: "memory")
; #define PG8_WAIT_L(n) asm volatile("s_waitcnt lgkmcnt(" #n ")" ::: "memory")
; #define PG8_BAR __builtin_amdgcn_s_barrier()
; #define PG8_SCHED __builtin_amdgcn_sched_barrier(0)
; template <class Epi>
; __device__ __forceinline__ void gemm_phase(LAS unsigned char* lds, const Gemm g, const Epi& E) {
;     ...
;             PG8_BAR; PG8_WAIT_L(0); PG8_MMA(1, 0, At, B0); PG8_BAR; PG8_SCHED;
;             PG8_STAGE(PG8_SB(0, 1), b2 + hstep, voffB);
;             PG8_WAIT_V(6); PG8_BAR; PG8_MMA(1, 1, At, B1); PG8_BAR;
;             PG8_LDB(B0, 1, 0); PG8_SCHED; PG8_LDA(At, 1, 0); PG8_STAGE(PG8_SA(0, 1), a2 + hstep, voffA);
;             PG8_WAIT_L(8); PG8_BAR; PG8_WAIT_L(0); PG8_MMA(0, 0, At, B0); PG8_BAR; PG8_SCHED;
;             PG8_LDB(B1, 1, 1); PG8_STAGE(PG8_SB(1, 0), b3, voffB);
;             PG8_BAR; PG8_WAIT_L(0); PG8_MMA(0, 1, At, B1); PG8_BAR;
;             PG8_LDA(At, 1, 1); PG8_STAGE(PG8_SA(1, 0), a3, voffA);
	s_add_u32 s34, s28, 0x20000
	s_addc_u32 s35, s29, 0
	s_add_i32 vcc_hi, vcc_hi, s83
	s_mov_b32 m0, vcc_hi
	v_lshl_add_u64 v[144:145], s[34:35], 0, v[130:131]
	global_load_lds_dwordx4 v[144:145], off
	s_add_i32 m0, vcc_hi, 0x2000
	v_lshl_add_u64 v[144:145], s[34:35], 0, v[134:135]
	global_load_lds_dwordx4 v[144:145], off
	s_waitcnt vmcnt(6)
	s_barrier
	s_setprio 1
	v_mfma_f32_16x16x32_bf16 v[52:55], v[198:201], v[166:169], v[52:55]
	v_mfma_f32_16x16x32_bf16 v[48:51], v[238:241], v[166:169], v[48:51]
	v_mfma_f32_16x16x32_bf16 v[36:39], v[198:201], v[174:177], v[36:39]
	v_mfma_f32_16x16x32_bf16 v[32:35], v[238:241], v[174:177], v[32:35]
	v_mfma_f32_16x16x32_bf16 v[20:23], v[198:201], v[182:185], v[20:23]
	v_mfma_f32_16x16x32_bf16 v[16:19], v[238:241], v[182:185], v[16:19]
	v_mfma_f32_16x16x32_bf16 v[4:7], v[198:201], v[190:193], v[4:7]
	v_mfma_f32_16x16x32_bf16 v[0:3], v[238:241], v[190:193], v[0:3]
	v_mfma_f32_16x16x32_bf16 v[52:55], v[202:205], v[170:173], v[52:55]
	v_mfma_f32_16x16x32_bf16 v[48:51], v[242:245], v[170:173], v[48:51]
	v_mfma_f32_16x16x32_bf16 v[36:39], v[202:205], v[178:181], v[36:39]
	v_mfma_f32_16x16x32_bf16 v[32:35], v[242:245], v[178:181], v[32:35]
	v_mfma_f32_16x16x32_bf16 v[20:23], v[202:205], v[186:189], v[20:23]
	v_mfma_f32_16x16x32_bf16 v[16:19], v[242:245], v[186:189], v[16:19]
	v_mfma_f32_16x16x32_bf16 v[4:7], v[202:205], v[194:197], v[4:7]
	v_mfma_f32_16x16x32_bf16 v[0:3], v[242:245], v[194:197], v[0:3]
	s_setprio 0
	s_add_i32 vcc_hi, 0, 0x18000
	v_add_u32_e32 v162, vcc_hi, v159
	s_barrier
	ds_read_b128 v[144:147], v162
	ds_read_b128 v[148:151], v162 offset:1024
	ds_read_b128 v[152:155], v162 offset:2048
	ds_read_b128 v[162:165], v162 offset:3072
	s_add_u32 s34, s36, 0x20000
	s_addc_u32 s35, s37, 0
	s_mov_b32 m0, s78
	v_lshl_add_u64 v[198:199], s[34:35], 0, v[128:129]
	ds_read_b128 v[166:169], v161 offset:32768
	ds_read_b128 v[170:173], v161 offset:33792
	ds_read_b128 v[174:177], v161 offset:34816
	ds_read_b128 v[178:181], v161 offset:35840
	ds_read_b128 v[182:185], v161 offset:36864
	ds_read_b128 v[186:189], v161 offset:37888
	ds_read_b128 v[190:193], v161 offset:38912
	ds_read_b128 v[194:197], v161 offset:39936
	global_load_lds_dwordx4 v[198:199], off
	s_mov_b32 m0, s76
	v_lshl_add_u64 v[198:199], s[34:35], 0, v[132:133]
	global_load_lds_dwordx4 v[198:199], off
	s_waitcnt lgkmcnt(8)
	s_barrier
	s_waitcnt lgkmcnt(0)
	s_setprio 1
	v_mfma_f32_16x16x32_bf16 v[124:127], v[144:147], v[166:169], v[124:127]
	v_mfma_f32_16x16x32_bf16 v[120:123], v[152:155], v[166:169], v[120:123]
	v_mfma_f32_16x16x32_bf16 v[108:111], v[144:147], v[174:177], v[108:111]
	v_mfma_f32_16x16x32_bf16 v[104:107], v[152:155], v[174:177], v[104:107]
	v_mfma_f32_16x16x32_bf16 v[92:95], v[144:147], v[182:185], v[92:95]
	v_mfma_f32_16x16x32_bf16 v[88:91], v[152:155], v[182:185], v[88:91]
	v_mfma_f32_16x16x32_bf16 v[76:79], v[144:147], v[190:193], v[76:79]
	v_mfma_f32_16x16x32_bf16 v[72:75], v[152:155], v[190:193], v[72:75]
	v_mfma_f32_16x16x32_bf16 v[124:127], v[148:151], v[170:173], v[124:127]
	v_mfma_f32_16x16x32_bf16 v[120:123], v[162:165], v[170:173], v[120:123]
	v_mfma_f32_16x16x32_bf16 v[108:111], v[148:151], v[178:181], v[108:111]
	v_mfma_f32_16x16x32_bf16 v[104:107], v[162:165], v[178:181], v[104:107]
	v_mfma_f32_16x16x32_bf16 v[92:95], v[148:151], v[186:189], v[92:95]
	v_mfma_f32_16x16x32_bf16 v[88:91], v[162:165], v[186:189], v[88:91]
	v_mfma_f32_16x16x32_bf16 v[76:79], v[148:151], v[194:197], v[76:79]
	v_mfma_f32_16x16x32_bf16 v[72:75], v[162:165], v[194:197], v[72:75]
	s_setprio 0
	s_barrier
	s_add_i32 s34, 0, 0x1c000
	s_add_i32 s35, vcc_hi, s83
	v_add_u32_e32 v208, s34, v159
	v_lshl_add_u64 v[156:157], v[156:157], 0, s[20:21]
	s_mov_b32 m0, s35
	ds_read_b128 v[198:201], v208
	ds_read_b128 v[202:205], v208 offset:1024
	ds_read_b128 v[238:241], v208 offset:2048
	ds_read_b128 v[242:245], v208 offset:3072
	global_load_lds_dwordx4 v[156:157], off
	s_add_i32 m0, s35, 0x2000
	v_lshl_add_u64 v[156:157], v[206:207], 0, s[20:21]
	global_load_lds_dwordx4 v[156:157], off
	s_barrier
	s_waitcnt lgkmcnt(0)
	s_setprio 1
	v_mfma_f32_16x16x32_bf16 v[116:119], v[198:201], v[166:169], v[116:119]
	v_mfma_f32_16x16x32_bf16 v[112:115], v[238:241], v[166:169], v[112:115]
	v_mfma_f32_16x16x32_bf16 v[100:103], v[198:201], v[174:177], v[100:103]
	v_mfma_f32_16x16x32_bf16 v[96:99], v[238:241], v[174:177], v[96:99]
	v_mfma_f32_16x16x32_bf16 v[84:87], v[198:201], v[182:185], v[84:87]
	v_mfma_f32_16x16x32_bf16 v[80:83], v[238:241], v[182:185], v[80:83]
	v_mfma_f32_16x16x32_bf16 v[68:71], v[198:201], v[190:193], v[68:71]
	v_mfma_f32_16x16x32_bf16 v[64:67], v[238:241], v[190:193], v[64:67]
	v_mfma_f32_16x16x32_bf16 v[116:119], v[202:205], v[170:173], v[116:119]
	v_mfma_f32_16x16x32_bf16 v[112:115], v[242:245], v[170:173], v[112:115]
	v_mfma_f32_16x16x32_bf16 v[100:103], v[202:205], v[178:181], v[100:103]
	v_mfma_f32_16x16x32_bf16 v[96:99], v[242:245], v[178:181], v[96:99]
	v_mfma_f32_16x16x32_bf16 v[84:87], v[202:205], v[186:189], v[84:87]
	v_mfma_f32_16x16x32_bf16 v[80:83], v[242:245], v[186:189], v[80:83]
	v_mfma_f32_16x16x32_bf16 v[68:71], v[202:205], v[194:197], v[68:71]
	v_mfma_f32_16x16x32_bf16 v[64:67], v[242:245], v[194:197], v[64:67]
	s_setprio 0
	s_mov_b32 m0, s68
	v_lshl_add_u64 v[156:157], v[220:221], 0, s[20:21]
	s_barrier
	ds_read_b128 v[166:169], v161 offset:49152
	ds_read_b128 v[170:173], v161 offset:50176
	ds_read_b128 v[174:177], v161 offset:51200
	ds_read_b128 v[178:181], v161 offset:52224
	ds_read_b128 v[182:185], v161 offset:53248
	ds_read_b128 v[186:189], v161 offset:54272
	ds_read_b128 v[190:193], v161 offset:55296
	ds_read_b128 v[194:197], v161 offset:56320
	global_load_lds_dwordx4 v[156:157], off
	s_mov_b32 m0, s74
	v_lshl_add_u64 v[156:157], v[228:229], 0, s[20:21]
	global_load_lds_dwordx4 v[156:157], off
	s_barrier
; #define PG8_WAIT_V(n) asm volatile("s_waitcnt vmcnt(" #n ")" ::: "memory")
; template <class Epi>
; __device__ __forceinline__ void gemm_phase(LAS unsigned char* lds, const Gemm g, const Epi& E) {
;     ...
;             PG8_LDA(At, 1, 1); PG8_STAGE(PG8_SA(1, 0), a3, voffA);
;             PG8_BAR; PG8_WAIT_L(0); PG8_MMA(1, 0, At, B0); PG8_BAR; PG8_SCHED;
;             PG8_STAGE(PG8_SB(1, 1), b3 + hstep, voffB);
;             PG8_WAIT_V(6); PG8_BAR; PG8_MMA(1, 1, At, B1); PG8_BAR;
;     __device__ __forceinline__ void operator()(const AccT& acc, const Unit& u, int wr, int wc, int fr, int fq) const {
;     ...
;                 const int row = u.pm * 256 + ai * 128 + wr * 64 + m * 16 + fr; const int b = row / SEQ, t = row % SEQ;
;                 const f32x4 s0 = *(const f32x4*)(SSQ + (size_t)row * 16 + mode * 8), s1 = *(const f32x4*)(SSQ + (size_t)row * 16 + mode * 8 + 4);
;                 const float ssq = (s0[0] + s0[1]) + (s0[2] + s0[3]) + (s1[0] + s1[1]) + (s1[2] + s1[3]);
;                 float rs = rsqrtf(ssq * (1.0f / 512.0f) + EPS);
;                 if (mode == 0) {
;                     rs *= (0.07216878364870322f * 1.4426950408889634f);
; #pragma unroll
;                     for (int bj = 0; bj < 2; ++bj) {
;                         const int c8 = u.pn * 256 + bj * 128 + wc * 32 + fq * 8; const int head = c8 / DQK, d0 = c8 % DQK;
;                         bf16_t* qp = Q + ((size_t)(b * NH + head) * SEQ + t) * DQK;
;                         const f32x4 v0 = acc[ai][bj][m][0] * rs, v1 = acc[ai][bj][m][1] * rs;
;                         if (d0 < 128) { *(u32x4*)(qp + d0) = pack8u(v0, v1); }
;                         else { const int i0 = 4 * ((d0 - 128) >> 3);
;                             const f32x4 cs = *(const f32x4*)(COS + (size_t)row * 32 + i0), sn = *(const f32x4*)(SIN + (size_t)row * 32 + i0);
;                             const f32x4 o1 = v0 * cs - v1 * sn, o2 = v1 * cs + v0 * sn;
;                             *(u32x2*)(qp + 128 + i0) = pack4u(o1); *(u32x2*)(qp + 160 + i0) = pack4u(o2); }
;                     }
;                 } else {
;                     const size_t bh = (size_t)(b * NH + u.pn) * SEQ + t; const int d = wc * 32 + fq * 8;
;                     *(u32x4*)(Kb + bh * DQK + d) = pack8u(acc[ai][0][m][0] * rs, acc[ai][0][m][1] * rs);
;                     *(u32x4*)(Vb + bh * 128 + d) = pack8u(acc[ai][1][m][0] * rs, acc[ai][1][m][1] * rs);
	s_waitcnt lgkmcnt(0)
	s_setprio 1
	v_mfma_f32_16x16x32_bf16 v[60:63], v[144:147], v[166:169], v[60:63]
	v_mfma_f32_16x16x32_bf16 v[56:59], v[152:155], v[166:169], v[56:59]
	v_mfma_f32_16x16x32_bf16 v[44:47], v[144:147], v[174:177], v[44:47]
	v_mfma_f32_16x16x32_bf16 v[40:43], v[152:155], v[174:177], v[40:43]
	v_mfma_f32_16x16x32_bf16 v[28:31], v[144:147], v[182:185], v[28:31]
	v_mfma_f32_16x16x32_bf16 v[24:27], v[152:155], v[182:185], v[24:27]
	v_mfma_f32_16x16x32_bf16 v[12:15], v[144:147], v[190:193], v[12:15]
	v_mfma_f32_16x16x32_bf16 v[8:11], v[152:155], v[190:193], v[8:11]
	v_mfma_f32_16x16x32_bf16 v[60:63], v[148:151], v[170:173], v[60:63]
	v_mfma_f32_16x16x32_bf16 v[56:59], v[162:165], v[170:173], v[56:59]
	v_mfma_f32_16x16x32_bf16 v[44:47], v[148:151], v[178:181], v[44:47]
	v_mfma_f32_16x16x32_bf16 v[40:43], v[162:165], v[178:181], v[40:43]
	v_mfma_f32_16x16x32_bf16 v[28:31], v[148:151], v[186:189], v[28:31]
	v_mfma_f32_16x16x32_bf16 v[24:27], v[162:165], v[186:189], v[24:27]
	v_mfma_f32_16x16x32_bf16 v[12:15], v[148:151], v[194:197], v[12:15]
	v_mfma_f32_16x16x32_bf16 v[8:11], v[162:165], v[194:197], v[8:11]
	s_setprio 0
	s_barrier
	s_add_u32 s28, s28, 0x20080
	s_addc_u32 s29, s29, 0
	s_add_i32 s34, s34, s83
	s_mov_b32 m0, s34
	v_lshl_add_u64 v[144:145], s[28:29], 0, v[130:131]
	global_load_lds_dwordx4 v[144:145], off
	s_add_i32 m0, s34, 0x2000
	v_lshl_add_u64 v[144:145], s[28:29], 0, v[134:135]
	global_load_lds_dwordx4 v[144:145], off
	s_waitcnt vmcnt(6)
	s_barrier
	s_setprio 1
	v_mfma_f32_16x16x32_bf16 v[52:55], v[198:201], v[166:169], v[52:55]
	v_mfma_f32_16x16x32_bf16 v[48:51], v[238:241], v[166:169], v[48:51]
	v_mfma_f32_16x16x32_bf16 v[36:39], v[198:201], v[174:177], v[36:39]
	v_mfma_f32_16x16x32_bf16 v[32:35], v[238:241], v[174:177], v[32:35]
	v_mfma_f32_16x16x32_bf16 v[20:23], v[198:201], v[182:185], v[20:23]
	v_mfma_f32_16x16x32_bf16 v[16:19], v[238:241], v[182:185], v[16:19]
	v_mfma_f32_16x16x32_bf16 v[4:7], v[198:201], v[190:193], v[4:7]
	v_mfma_f32_16x16x32_bf16 v[0:3], v[238:241], v[190:193], v[0:3]
	v_mfma_f32_16x16x32_bf16 v[52:55], v[202:205], v[170:173], v[52:55]
	v_mfma_f32_16x16x32_bf16 v[48:51], v[242:245], v[170:173], v[48:51]
	v_mfma_f32_16x16x32_bf16 v[36:39], v[202:205], v[178:181], v[36:39]
	v_mfma_f32_16x16x32_bf16 v[32:35], v[242:245], v[178:181], v[32:35]
	v_mfma_f32_16x16x32_bf16 v[20:23], v[202:205], v[186:189], v[20:23]
	v_mfma_f32_16x16x32_bf16 v[16:19], v[242:245], v[186:189], v[16:19]
	v_mfma_f32_16x16x32_bf16 v[4:7], v[202:205], v[194:197], v[4:7]
	v_mfma_f32_16x16x32_bf16 v[0:3], v[242:245], v[194:197], v[0:3]
	s_setprio 0
	s_add_i32 vcc_lo, vcc_lo, 2
	s_add_u32 s26, s26, 0x100
	s_addc_u32 s27, s27, 0
	s_add_u32 s45, s45, 0x100
	s_addc_u32 s65, s65, 0
	s_cmp_gt_u32 vcc_lo, 5
	s_barrier
	s_cbranch_scc0 .LBB0_499
	v_lshl_add_u32 v144, s0, 8, v158
	v_lshlrev_b32_e32 v220, 6, v144
	v_add_u32_e32 v221, 0x2000, v220
	global_load_dwordx4 v[176:179], v220, s[48:49] offset:16
	global_load_dwordx4 v[180:183], v220, s[48:49]
	global_load_dwordx4 v[184:187], v220, s[48:49] offset:1040
	global_load_dwordx4 v[188:191], v220, s[48:49] offset:1024
	global_load_dwordx4 v[192:195], v220, s[48:49] offset:2064
	global_load_dwordx4 v[196:199], v220, s[48:49] offset:2048
	global_load_dwordx4 v[200:203], v220, s[48:49] offset:3088
	global_load_dwordx4 v[204:207], v220, s[48:49] offset:3072
	v_ashrrev_i32_e32 v145, 31, v144
	v_lshlrev_b64 v[150:151], 6, v[144:145]
	v_lshl_add_u64 v[154:155], s[48:49], 0, v[150:151]
	s_waitcnt vmcnt(6)
	v_mov_b32_e32 v150, v176
	v_mov_b32_e32 v151, v177
	v_mov_b32_e32 v152, v178
	v_mov_b32_e32 v153, v179
	s_nop 0
	v_mov_b32_e32 v154, v180
	v_mov_b32_e32 v155, v181
	v_mov_b32_e32 v156, v182
	v_mov_b32_e32 v157, v183
	global_load_dwordx4 v[176:179], v221, s[48:49] offset:16
	global_load_dwordx4 v[180:183], v221, s[48:49]
	v_lshrrev_b32_e32 v146, 21, v145
	v_add_u32_e32 v146, v144, v146
	v_ashrrev_i32_e32 v149, 11, v146
	v_mul_i32_i24_e32 v146, 0x800, v149
	v_sub_u32_e32 v146, v144, v146
	s_mov_b64 s[0:1], -1
	s_nop 0
	v_mov_b32_e32 v162, v155
	v_mov_b32_e32 v163, v156
	v_mov_b32_e32 v155, v157
	v_pk_add_f32 v[154:155], v[162:163], v[154:155]
	v_mov_b32_e32 v156, v152
	v_mov_b32_e32 v157, v150
	v_mov_b32_e32 v150, v153
	v_pk_add_f32 v[150:151], v[156:157], v[150:151]
	v_add_f32_e32 v147, v154, v155
	v_add_f32_e32 v147, v147, v151
	v_add_f32_e32 v147, v150, v147
	v_fmamk_f32 v147, v147, 0x3b000000, v223
	v_cmp_gt_f32_e32 vcc, s60, v147
	v_mul_f32_e32 v148, 0x4b800000, v147
	s_nop 0
	v_cndmask_b32_e32 v147, v147, v148, vcc
	v_rsq_f32_e32 v147, v147
	s_nop 0
	v_mul_f32_e32 v148, 0x45800000, v147
	v_cndmask_b32_e32 v148, v147, v148, vcc
	s_and_b64 vcc, exec, s[46:47]
	v_ashrrev_i32_e32 v147, 31, v146
	s_cbranch_vccz .LBB0_502
	v_lshl_add_u32 v150, v149, 3, s94
	v_ashrrev_i32_e32 v151, 31, v150
	v_lshlrev_b64 v[150:151], 11, v[150:151]
	v_lshl_add_u64 v[154:155], v[150:151], 0, v[146:147]
	v_pk_mul_f32 v[152:153], v[126:127], v[148:149] op_sel_hi:[1,0]
	v_pk_mul_f32 v[150:151], v[124:125], v[148:149] op_sel_hi:[1,0]
	v_pk_mul_f32 v[156:157], v[122:123], v[148:149] op_sel_hi:[1,0]
	v_pk_mul_f32 v[162:163], v[120:121], v[148:149] op_sel_hi:[1,0]
	v_cvt_pk_bf16_f32 v150, v150, v151
	v_cvt_pk_bf16_f32 v151, v152, v153
	v_cvt_pk_bf16_f32 v153, v156, v157
	v_mad_u64_u32 v[156:157], s[0:1], v154, s33, v[136:137]
	v_cvt_pk_bf16_f32 v152, v162, v163
	v_mad_i32_i24 v157, v155, s33, v157
	global_store_dwordx4 v[156:157], v[150:153], off
	v_pk_mul_f32 v[156:157], v[114:115], v[148:149] op_sel_hi:[1,0]
	v_pk_mul_f32 v[162:163], v[112:113], v[148:149] op_sel_hi:[1,0]
	v_pk_mul_f32 v[152:153], v[118:119], v[148:149] op_sel_hi:[1,0]
	v_pk_mul_f32 v[150:151], v[116:117], v[148:149] op_sel_hi:[1,0]
	v_lshlrev_b64 v[154:155], 8, v[154:155]
	v_cvt_pk_bf16_f32 v150, v150, v151
	v_cvt_pk_bf16_f32 v151, v152, v153
	v_cvt_pk_bf16_f32 v152, v162, v163
	v_cvt_pk_bf16_f32 v153, v156, v157
	v_lshl_add_u64 v[154:155], v[138:139], 0, v[154:155]
	global_store_dwordx4 v[154:155], v[150:153], off
	s_mov_b64 s[0:1], 0

; #define PG8_STAGE(bufoff, gbase, voff) do { _Pragma("unroll") for (int _i = 0; _i < 2; ++_i) \
;         __builtin_amdgcn_global_load_lds((const unsigned*)((const char*)(gbase) + (voff)[_i]), (LAS unsigned*)(lds + (bufoff) + ldsw + _i * 8192), 16, 0, 0); } while (0)
; #define PG8_LDA(dst, b, h) do { _Pragma("unroll") for (int m = 0; m < 4; ++m) _Pragma("unroll") for (int k = 0; k < 2; ++k) dst[m][k] = *(const LAS bf16x8*)(lds + PG8_SA(b, h) + aoff + m * 2048 + k * 1024); } while (0)
; #define PG8_LDB(dst, b, h) do { _Pragma("unroll") for (int n = 0; n < 2; ++n) _Pragma("unroll") for (int k = 0; k < 2; ++k) dst[n][k] = *(const LAS bf16x8*)(lds + PG8_SB(b, h) + boff + n * 2048 + k * 1024); } while (0)
; #define PG8_MMA(ai, bj, At, Bt) do { __builtin_amdgcn_s_setprio(1); _Pragma("unroll") for (int m = 0; m < 4; ++m) _Pragma("unroll") for (int n = 0; n < 2; ++n) _Pragma("unroll") for (int k = 0; k < 2; ++k) \
;         acc[ai][bj][m][n] = __builtin_amdgcn_mfma_f32_16x16x32_bf16(Bt[n][k], At[m][k], acc[ai][bj][m][n], 0, 0, 0); __builtin_amdgcn_s_setprio(0); } while (0)
; #define PG8_WAIT_L(n) asm volatile("s_waitcnt lgkmcnt(" #n ")" ::: "memory")
; #define PG8_BAR __builtin_amdgcn_s_barrier()
; #define PG8_SCHED __builtin_amdgcn_sched_barrier(0)
; template <class Epi>
; __device__ __forceinline__ void gemm_phase(LAS unsigned char* lds, const Gemm g, const Epi& E) {
;     ...
;             PG8_LDB(B0, 0, 0); PG8_SCHED; PG8_LDA(At, 0, 0); PG8_STAGE(PG8_SA(1, 1), a1 + hstep, voffA);
;             PG8_WAIT_L(8); PG8_BAR; PG8_WAIT_L(0); PG8_MMA(0, 0, At, B0); PG8_BAR; PG8_SCHED;
;             PG8_LDB(B1, 0, 1); PG8_STAGE(PG8_SB(0, 0), b2, voffB);
;             PG8_BAR; PG8_WAIT_L(0); PG8_MMA(0, 1, At, B1); PG8_BAR;
;             PG8_LDA(At, 0, 1); PG8_STAGE(PG8_SA(0, 0), a2, voffA);
;             PG8_BAR; PG8_WAIT_L(0); PG8_MMA(1, 0, At, B0); PG8_BAR; PG8_SCHED;
.LBB0_672:
	s_add_u32 s28, s26, 0xfff80080
	s_addc_u32 s29, s27, -1
	s_add_i32 s34, 0, 0x10000
	v_add_u32_e32 v160, s34, v163
	ds_read_b128 v[128:131], v160
	ds_read_b128 v[132:135], v160 offset:1024
	ds_read_b128 v[156:159], v160 offset:2048
	ds_read_b128 v[166:169], v160 offset:3072
	s_cmp_eq_u32 s39, 28
	s_cselect_b32 s37, s1, s29
	s_cselect_b32 s36, s2, s28
	s_cselect_b32 s29, s3, s38
	s_cselect_b32 s28, s30, s31
	v_lshl_add_u64 v[160:161], s[26:27], 0, v[152:153]
	s_add_i32 m0, s96, 0xc000
	ds_read_b128 v[170:173], v164
	ds_read_b128 v[174:177], v164 offset:1024
	ds_read_b128 v[178:181], v164 offset:2048
	ds_read_b128 v[182:185], v164 offset:3072
	ds_read_b128 v[186:189], v164 offset:4096
	ds_read_b128 v[190:193], v164 offset:5120
	ds_read_b128 v[194:197], v164 offset:6144
	ds_read_b128 v[198:201], v164 offset:7168
	global_load_lds_dwordx4 v[160:161], off
	s_add_i32 m0, s96, 0xe000
	v_lshl_add_u64 v[160:161], s[26:27], 0, v[154:155]
	global_load_lds_dwordx4 v[160:161], off
	s_waitcnt lgkmcnt(8)
	s_barrier
	s_waitcnt lgkmcnt(0)
	s_setprio 1
	v_mfma_f32_16x16x32_bf16 v[124:127], v[128:131], v[170:173], v[124:127]
	v_mfma_f32_16x16x32_bf16 v[120:123], v[156:159], v[170:173], v[120:123]
	v_mfma_f32_16x16x32_bf16 v[108:111], v[128:131], v[178:181], v[108:111]
	v_mfma_f32_16x16x32_bf16 v[104:107], v[156:159], v[178:181], v[104:107]
	v_mfma_f32_16x16x32_bf16 v[92:95], v[128:131], v[186:189], v[92:95]
	v_mfma_f32_16x16x32_bf16 v[88:91], v[156:159], v[186:189], v[88:91]
	v_mfma_f32_16x16x32_bf16 v[76:79], v[128:131], v[194:197], v[76:79]
	v_mfma_f32_16x16x32_bf16 v[72:75], v[156:159], v[194:197], v[72:75]
	v_mfma_f32_16x16x32_bf16 v[124:127], v[132:135], v[174:177], v[124:127]
	v_mfma_f32_16x16x32_bf16 v[120:123], v[166:169], v[174:177], v[120:123]
	v_mfma_f32_16x16x32_bf16 v[108:111], v[132:135], v[182:185], v[108:111]
	v_mfma_f32_16x16x32_bf16 v[104:107], v[166:169], v[182:185], v[104:107]
	v_mfma_f32_16x16x32_bf16 v[92:95], v[132:135], v[190:193], v[92:95]
	v_mfma_f32_16x16x32_bf16 v[88:91], v[166:169], v[190:193], v[88:91]
	v_mfma_f32_16x16x32_bf16 v[76:79], v[132:135], v[198:201], v[76:79]
	v_mfma_f32_16x16x32_bf16 v[72:75], v[166:169], v[198:201], v[72:75]
	s_setprio 0
	s_barrier
	s_add_i32 s35, 0, 0x14000
	v_add_u32_e32 v160, s35, v163
	s_add_i32 s34, s34, s71
	ds_read_b128 v[202:205], v160
	ds_read_b128 v[238:241], v160 offset:1024
	ds_read_b128 v[242:245], v160 offset:2048
	ds_read_b128 v[246:249], v160 offset:3072
	v_lshl_add_u64 v[160:161], s[28:29], 0, v[138:139]
	s_mov_b32 m0, s34
	v_lshl_add_u64 v[206:207], s[28:29], 0, v[142:143]
	global_load_lds_dwordx4 v[160:161], off
	s_add_i32 m0, s34, 0x2000
	s_nop 0
	global_load_lds_dwordx4 v[206:207], off
	s_barrier
	s_waitcnt lgkmcnt(0)
	s_setprio 1
	v_mfma_f32_16x16x32_bf16 v[116:119], v[202:205], v[170:173], v[116:119]
	v_mfma_f32_16x16x32_bf16 v[112:115], v[242:245], v[170:173], v[112:115]
	v_mfma_f32_16x16x32_bf16 v[100:103], v[202:205], v[178:181], v[100:103]
	v_mfma_f32_16x16x32_bf16 v[96:99], v[242:245], v[178:181], v[96:99]
	v_mfma_f32_16x16x32_bf16 v[84:87], v[202:205], v[186:189], v[84:87]
	v_mfma_f32_16x16x32_bf16 v[80:83], v[242:245], v[186:189], v[80:83]
	v_mfma_f32_16x16x32_bf16 v[68:71], v[202:205], v[194:197], v[68:71]
	v_mfma_f32_16x16x32_bf16 v[64:67], v[242:245], v[194:197], v[64:67]
	v_mfma_f32_16x16x32_bf16 v[116:119], v[238:241], v[174:177], v[116:119]
	v_mfma_f32_16x16x32_bf16 v[112:115], v[246:249], v[174:177], v[112:115]
	v_mfma_f32_16x16x32_bf16 v[100:103], v[238:241], v[182:185], v[100:103]
	v_mfma_f32_16x16x32_bf16 v[96:99], v[246:249], v[182:185], v[96:99]
	v_mfma_f32_16x16x32_bf16 v[84:87], v[238:241], v[190:193], v[84:87]
	v_mfma_f32_16x16x32_bf16 v[80:83], v[246:249], v[190:193], v[80:83]
	v_mfma_f32_16x16x32_bf16 v[68:71], v[238:241], v[198:201], v[68:71]
	v_mfma_f32_16x16x32_bf16 v[64:67], v[246:249], v[198:201], v[64:67]
	s_setprio 0
	s_mov_b32 m0, s96
	v_lshl_add_u64 v[220:221], s[36:37], 0, v[136:137]
	s_barrier
	ds_read_b128 v[170:173], v164 offset:16384
	ds_read_b128 v[174:177], v164 offset:17408
	ds_read_b128 v[178:181], v164 offset:18432
	ds_read_b128 v[182:185], v164 offset:19456
	ds_read_b128 v[186:189], v164 offset:20480
	ds_read_b128 v[190:193], v164 offset:21504
	ds_read_b128 v[194:197], v164 offset:22528
	ds_read_b128 v[198:201], v164 offset:23552
	global_load_lds_dwordx4 v[220:221], off
	s_mov_b32 m0, s97
	v_lshl_add_u64 v[228:229], s[36:37], 0, v[140:141]
	global_load_lds_dwordx4 v[228:229], off
	s_barrier
	s_waitcnt lgkmcnt(0)
	s_setprio 1
	v_mfma_f32_16x16x32_bf16 v[60:63], v[128:131], v[170:173], v[60:63]
	v_mfma_f32_16x16x32_bf16 v[56:59], v[156:159], v[170:173], v[56:59]
	v_mfma_f32_16x16x32_bf16 v[44:47], v[128:131], v[178:181], v[44:47]
	v_mfma_f32_16x16x32_bf16 v[40:43], v[156:159], v[178:181], v[40:43]
	v_mfma_f32_16x16x32_bf16 v[28:31], v[128:131], v[186:189], v[28:31]
	v_mfma_f32_16x16x32_bf16 v[24:27], v[156:159], v[186:189], v[24:27]
	v_mfma_f32_16x16x32_bf16 v[12:15], v[128:131], v[194:197], v[12:15]
	v_mfma_f32_16x16x32_bf16 v[8:11], v[156:159], v[194:197], v[8:11]
	v_mfma_f32_16x16x32_bf16 v[60:63], v[132:135], v[174:177], v[60:63]
	v_mfma_f32_16x16x32_bf16 v[56:59], v[166:169], v[174:177], v[56:59]
	v_mfma_f32_16x16x32_bf16 v[44:47], v[132:135], v[182:185], v[44:47]
	v_mfma_f32_16x16x32_bf16 v[40:43], v[166:169], v[182:185], v[40:43]
	v_mfma_f32_16x16x32_bf16 v[28:31], v[132:135], v[190:193], v[28:31]
	v_mfma_f32_16x16x32_bf16 v[24:27], v[166:169], v[190:193], v[24:27]
	v_mfma_f32_16x16x32_bf16 v[12:15], v[132:135], v[198:201], v[12:15]
	v_mfma_f32_16x16x32_bf16 v[8:11], v[166:169], v[198:201], v[8:11]
	s_setprio 0
	s_barrier
; #define PG8_STAGE(bufoff, gbase, voff) do { _Pragma("unroll") for (int _i = 0; _i < 2; ++_i) \
;         __builtin_amdgcn_global_load_lds((const unsigned*)((const char*)(gbase) + (voff)[_i]), (LAS unsigned*)(lds + (bufoff) + ldsw + _i * 8192), 16, 0, 0); } while (0)
; #define PG8_LDA(dst, b, h) do { _Pragma("unroll") for (int m = 0; m < 4; ++m) _Pragma("unroll") for (int k = 0; k < 2; ++k) dst[m][k] = *(const LAS bf16x8*)(lds + PG8_SA(b, h) + aoff + m * 2048 + k * 1024); } while (0)
; #define PG8_LDB(dst, b, h) do { _Pragma("unroll") for (int n = 0; n < 2; ++n) _Pragma("unroll") for (int k = 0; k < 2; ++k) dst[n][k] = *(const LAS bf16x8*)(lds + PG8_SB(b, h) + boff + n * 2048 + k * 1024); } while (0)
; #define PG8_MMA(ai, bj, At, Bt) do { __builtin_amdgcn_s_setprio(1); _Pragma("unroll") for (int m = 0; m < 4; ++m) _Pragma("unroll") for (int n = 0; n < 2; ++n) _Pragma("unroll") for (int k = 0; k < 2; ++k) \
;         acc[ai][bj][m][n] = __builtin_amdgcn_mfma_f32_16x16x32_bf16(Bt[n][k], At[m][k], acc[ai][bj][m][n], 0, 0, 0); __builtin_amdgcn_s_setprio(0); } while (0)
; #define PG8_WAIT_V(n) asm volatile("s_waitcnt vmcnt(" #n ")" ::: "memory")
; #define PG8_WAIT_L(n) asm volatile("s_waitcnt lgkmcnt(" #n ")" ::: "memory")
; #define PG8_BAR __builtin_amdgcn_s_barrier()
; #define PG8_SCHED __builtin_amdgcn_sched_barrier(0)
; template <class Epi>
; __device__ __forceinline__ void gemm_phase(LAS unsigned char* lds, const Gemm g, const Epi& E) {
;     ...
;             PG8_BAR; PG8_WAIT_L(0); PG8_MMA(1, 0, At, B0); PG8_BAR; PG8_SCHED;
;             PG8_STAGE(PG8_SB(0, 1), b2 + hstep, voffB);
;             PG8_WAIT_V(6); PG8_BAR; PG8_MMA(1, 1, At, B1); PG8_BAR;
;             PG8_LDB(B0, 1, 0); PG8_SCHED; PG8_LDA(At, 1, 0); PG8_STAGE(PG8_SA(0, 1), a2 + hstep, voffA);
;             PG8_WAIT_L(8); PG8_BAR; PG8_WAIT_L(0); PG8_MMA(0, 0, At, B0); PG8_BAR; PG8_SCHED;
;             PG8_LDB(B1, 1, 1); PG8_STAGE(PG8_SB(1, 0), b3, voffB);
	s_add_u32 s48, s28, 0x80000
	s_addc_u32 s49, s29, 0
	s_add_i32 s34, s35, s71
	s_mov_b32 m0, s34
	v_lshl_add_u64 v[128:129], s[48:49], 0, v[138:139]
	global_load_lds_dwordx4 v[128:129], off
	s_add_i32 m0, s34, 0x2000
	v_lshl_add_u64 v[128:129], s[48:49], 0, v[142:143]
	global_load_lds_dwordx4 v[128:129], off
	s_waitcnt vmcnt(6)
	s_barrier
	s_setprio 1
	v_mfma_f32_16x16x32_bf16 v[52:55], v[202:205], v[170:173], v[52:55]
	v_mfma_f32_16x16x32_bf16 v[48:51], v[242:245], v[170:173], v[48:51]
	v_mfma_f32_16x16x32_bf16 v[36:39], v[202:205], v[178:181], v[36:39]
	v_mfma_f32_16x16x32_bf16 v[32:35], v[242:245], v[178:181], v[32:35]
	v_mfma_f32_16x16x32_bf16 v[20:23], v[202:205], v[186:189], v[20:23]
	v_mfma_f32_16x16x32_bf16 v[16:19], v[242:245], v[186:189], v[16:19]
	v_mfma_f32_16x16x32_bf16 v[4:7], v[202:205], v[194:197], v[4:7]
	v_mfma_f32_16x16x32_bf16 v[0:3], v[242:245], v[194:197], v[0:3]
	v_mfma_f32_16x16x32_bf16 v[52:55], v[238:241], v[174:177], v[52:55]
	v_mfma_f32_16x16x32_bf16 v[48:51], v[246:249], v[174:177], v[48:51]
	v_mfma_f32_16x16x32_bf16 v[36:39], v[238:241], v[182:185], v[36:39]
	v_mfma_f32_16x16x32_bf16 v[32:35], v[246:249], v[182:185], v[32:35]
	v_mfma_f32_16x16x32_bf16 v[20:23], v[238:241], v[190:193], v[20:23]
	v_mfma_f32_16x16x32_bf16 v[16:19], v[246:249], v[190:193], v[16:19]
	v_mfma_f32_16x16x32_bf16 v[4:7], v[238:241], v[198:201], v[4:7]
	v_mfma_f32_16x16x32_bf16 v[0:3], v[246:249], v[198:201], v[0:3]
	s_setprio 0
	s_add_i32 s34, 0, 0x18000
	v_add_u32_e32 v165, s34, v163
	s_barrier
	ds_read_b128 v[128:131], v165
	ds_read_b128 v[132:135], v165 offset:1024
	ds_read_b128 v[156:159], v165 offset:2048
	ds_read_b128 v[166:169], v165 offset:3072
	s_add_u32 s36, s36, 0x80000
	s_addc_u32 s37, s37, 0
	s_mov_b32 m0, s70
	v_lshl_add_u64 v[202:203], s[36:37], 0, v[136:137]
	ds_read_b128 v[170:173], v164 offset:32768
	ds_read_b128 v[174:177], v164 offset:33792
	ds_read_b128 v[178:181], v164 offset:34816
	ds_read_b128 v[182:185], v164 offset:35840
	ds_read_b128 v[186:189], v164 offset:36864
	ds_read_b128 v[190:193], v164 offset:37888
	ds_read_b128 v[194:197], v164 offset:38912
	ds_read_b128 v[198:201], v164 offset:39936
	global_load_lds_dwordx4 v[202:203], off
	s_mov_b32 m0, s69
	v_lshl_add_u64 v[202:203], s[36:37], 0, v[140:141]
	global_load_lds_dwordx4 v[202:203], off
	s_waitcnt lgkmcnt(8)
	s_barrier
	s_waitcnt lgkmcnt(0)
	s_setprio 1
	v_mfma_f32_16x16x32_bf16 v[124:127], v[128:131], v[170:173], v[124:127]
	v_mfma_f32_16x16x32_bf16 v[120:123], v[156:159], v[170:173], v[120:123]
	v_mfma_f32_16x16x32_bf16 v[108:111], v[128:131], v[178:181], v[108:111]
	v_mfma_f32_16x16x32_bf16 v[104:107], v[156:159], v[178:181], v[104:107]
	v_mfma_f32_16x16x32_bf16 v[92:95], v[128:131], v[186:189], v[92:95]
	v_mfma_f32_16x16x32_bf16 v[88:91], v[156:159], v[186:189], v[88:91]
	v_mfma_f32_16x16x32_bf16 v[76:79], v[128:131], v[194:197], v[76:79]
	v_mfma_f32_16x16x32_bf16 v[72:75], v[156:159], v[194:197], v[72:75]
	v_mfma_f32_16x16x32_bf16 v[124:127], v[132:135], v[174:177], v[124:127]
	v_mfma_f32_16x16x32_bf16 v[120:123], v[166:169], v[174:177], v[120:123]
	v_mfma_f32_16x16x32_bf16 v[108:111], v[132:135], v[182:185], v[108:111]
	v_mfma_f32_16x16x32_bf16 v[104:107], v[166:169], v[182:185], v[104:107]
	v_mfma_f32_16x16x32_bf16 v[92:95], v[132:135], v[190:193], v[92:95]
	v_mfma_f32_16x16x32_bf16 v[88:91], v[166:169], v[190:193], v[88:91]
	v_mfma_f32_16x16x32_bf16 v[76:79], v[132:135], v[198:201], v[76:79]
	v_mfma_f32_16x16x32_bf16 v[72:75], v[166:169], v[198:201], v[72:75]
	s_setprio 0
	s_barrier
	s_add_i32 s35, 0, 0x1c000
	s_add_i32 s34, s34, s71
	v_add_u32_e32 v165, s35, v163
	v_lshl_add_u64 v[160:161], v[160:161], 0, s[20:21]
	s_mov_b32 m0, s34
	ds_read_b128 v[202:205], v165
	ds_read_b128 v[238:241], v165 offset:1024
	ds_read_b128 v[242:245], v165 offset:2048
	ds_read_b128 v[246:249], v165 offset:3072
	global_load_lds_dwordx4 v[160:161], off
	s_add_i32 m0, s34, 0x2000
	v_lshl_add_u64 v[160:161], v[206:207], 0, s[20:21]
	global_load_lds_dwordx4 v[160:161], off
	s_barrier
; __device__ __forceinline__ u32x2 pack4u(f32x4 a) { u32x2 w = {cvt_pk_bf16(a[0], a[1]), cvt_pk_bf16(a[2], a[3])}; return w; }
; #define PG8_STAGE(bufoff, gbase, voff) do { _Pragma("unroll") for (int _i = 0; _i < 2; ++_i) \
;         __builtin_amdgcn_global_load_lds((const unsigned*)((const char*)(gbase) + (voff)[_i]), (LAS unsigned*)(lds + (bufoff) + ldsw + _i * 8192), 16, 0, 0); } while (0)
; #define PG8_WAIT_V(n) asm volatile("s_waitcnt vmcnt(" #n ")" ::: "memory")
; #define PG8_BAR __builtin_amdgcn_s_barrier()
; template <class Epi>
; __device__ __forceinline__ void gemm_phase(LAS unsigned char* lds, const Gemm g, const Epi& E) {
;     ...
;             PG8_LDB(B1, 1, 1); PG8_STAGE(PG8_SB(1, 0), b3, voffB);
;             PG8_BAR; PG8_WAIT_L(0); PG8_MMA(0, 1, At, B1); PG8_BAR;
;             PG8_LDA(At, 1, 1); PG8_STAGE(PG8_SA(1, 0), a3, voffA);
;             PG8_BAR; PG8_WAIT_L(0); PG8_MMA(1, 0, At, B0); PG8_BAR; PG8_SCHED;
;             PG8_STAGE(PG8_SB(1, 1), b3 + hstep, voffB);
;             PG8_WAIT_V(6); PG8_BAR; PG8_MMA(1, 1, At, B1); PG8_BAR;
;     __device__ __forceinline__ void operator()(const AccT& acc, const Unit& u, int wr, int wc, int fr, int fq) const {
;     ...
;         } else {
;             const int g8 = wc * 4 + fq;
; #pragma unroll
;             for (int ai = 0; ai < 2; ++ai)
; #pragma unroll
;                 for (int m = 0; m < 4; ++m) {
;                     const int row = u.pm * 256 + ai * 128 + wr * 64 + m * 16 + fr;
;                     const f32x4 v0 = acc[ai][0][m][0], v1 = acc[ai][0][m][1];
;                     if (g8 < 8) {
;                         const int i0 = 4 * g8;
;                         const f32x4 cs = *(const f32x4*)(COS + (size_t)row * 32 + i0), sn = *(const f32x4*)(SIN + (size_t)row * 32 + i0);
;                         const f32x4 o1 = v0 * cs - v1 * sn, o2 = v1 * cs + v0 * sn;
;                         const u32x2 w1 = pack4u(o1), w2 = pack4u(o2);
;                         const int b = row / SEQ, t = row % SEQ;
;                         bf16_t* kp = Kb + ((size_t)(b * NH) * SEQ + t) * DQK + 128 + i0;
; #pragma unroll
;                         for (int h = 0; h < NH; ++h) { *(u32x2*)(kp + (size_t)h * SEQ * DQK) = w1; *(u32x2*)(kp + (size_t)h * SEQ * DQK + 32) = w2; }
;                     } else if (g8 < 10) { float* bp = BA + (size_t)row * 16 + (g8 - 8) * 8; *(f32x4*)bp = v0; *(f32x4*)(bp + 4) = v1; }
	s_waitcnt lgkmcnt(0)
	s_setprio 1
	v_mfma_f32_16x16x32_bf16 v[116:119], v[202:205], v[170:173], v[116:119]
	v_mfma_f32_16x16x32_bf16 v[112:115], v[242:245], v[170:173], v[112:115]
	v_mfma_f32_16x16x32_bf16 v[100:103], v[202:205], v[178:181], v[100:103]
	v_mfma_f32_16x16x32_bf16 v[96:99], v[242:245], v[178:181], v[96:99]
	v_mfma_f32_16x16x32_bf16 v[84:87], v[202:205], v[186:189], v[84:87]
	v_mfma_f32_16x16x32_bf16 v[80:83], v[242:245], v[186:189], v[80:83]
	v_mfma_f32_16x16x32_bf16 v[68:71], v[202:205], v[194:197], v[68:71]
	v_mfma_f32_16x16x32_bf16 v[64:67], v[242:245], v[194:197], v[64:67]
	v_mfma_f32_16x16x32_bf16 v[116:119], v[238:241], v[174:177], v[116:119]
	v_mfma_f32_16x16x32_bf16 v[112:115], v[246:249], v[174:177], v[112:115]
	v_mfma_f32_16x16x32_bf16 v[100:103], v[238:241], v[182:185], v[100:103]
	v_mfma_f32_16x16x32_bf16 v[96:99], v[246:249], v[182:185], v[96:99]
	v_mfma_f32_16x16x32_bf16 v[84:87], v[238:241], v[190:193], v[84:87]
	v_mfma_f32_16x16x32_bf16 v[80:83], v[246:249], v[190:193], v[80:83]
	v_mfma_f32_16x16x32_bf16 v[68:71], v[238:241], v[198:201], v[68:71]
	v_mfma_f32_16x16x32_bf16 v[64:67], v[246:249], v[198:201], v[64:67]
	s_setprio 0
	s_mov_b32 m0, s68
	v_lshl_add_u64 v[160:161], v[220:221], 0, s[20:21]
	s_barrier
	ds_read_b128 v[170:173], v164 offset:49152
	ds_read_b128 v[174:177], v164 offset:50176
	ds_read_b128 v[178:181], v164 offset:51200
	ds_read_b128 v[182:185], v164 offset:52224
	ds_read_b128 v[186:189], v164 offset:53248
	ds_read_b128 v[190:193], v164 offset:54272
	ds_read_b128 v[194:197], v164 offset:55296
	ds_read_b128 v[198:201], v164 offset:56320
	global_load_lds_dwordx4 v[160:161], off
	s_mov_b32 m0, s83
	v_lshl_add_u64 v[160:161], v[228:229], 0, s[20:21]
	global_load_lds_dwordx4 v[160:161], off
	s_barrier
	s_waitcnt lgkmcnt(0)
	s_setprio 1
	v_mfma_f32_16x16x32_bf16 v[60:63], v[128:131], v[170:173], v[60:63]
	v_mfma_f32_16x16x32_bf16 v[56:59], v[156:159], v[170:173], v[56:59]
	v_mfma_f32_16x16x32_bf16 v[44:47], v[128:131], v[178:181], v[44:47]
	v_mfma_f32_16x16x32_bf16 v[40:43], v[156:159], v[178:181], v[40:43]
	v_mfma_f32_16x16x32_bf16 v[28:31], v[128:131], v[186:189], v[28:31]
	v_mfma_f32_16x16x32_bf16 v[24:27], v[156:159], v[186:189], v[24:27]
	v_mfma_f32_16x16x32_bf16 v[12:15], v[128:131], v[194:197], v[12:15]
	v_mfma_f32_16x16x32_bf16 v[8:11], v[156:159], v[194:197], v[8:11]
	v_mfma_f32_16x16x32_bf16 v[60:63], v[132:135], v[174:177], v[60:63]
	v_mfma_f32_16x16x32_bf16 v[56:59], v[166:169], v[174:177], v[56:59]
	v_mfma_f32_16x16x32_bf16 v[44:47], v[132:135], v[182:185], v[44:47]
	v_mfma_f32_16x16x32_bf16 v[40:43], v[166:169], v[182:185], v[40:43]
	v_mfma_f32_16x16x32_bf16 v[28:31], v[132:135], v[190:193], v[28:31]
	v_mfma_f32_16x16x32_bf16 v[24:27], v[166:169], v[190:193], v[24:27]
	v_mfma_f32_16x16x32_bf16 v[12:15], v[132:135], v[198:201], v[12:15]
	v_mfma_f32_16x16x32_bf16 v[8:11], v[166:169], v[198:201], v[8:11]
	s_setprio 0
	s_barrier
	s_add_u32 s28, s28, 0x80080
	s_addc_u32 s29, s29, 0
	s_add_i32 s34, s35, s71
	s_mov_b32 m0, s34
	v_lshl_add_u64 v[128:129], s[28:29], 0, v[138:139]
	global_load_lds_dwordx4 v[128:129], off
	s_add_i32 m0, s34, 0x2000
	v_lshl_add_u64 v[128:129], s[28:29], 0, v[142:143]
	global_load_lds_dwordx4 v[128:129], off
	s_waitcnt vmcnt(6)
	s_barrier
	s_setprio 1
	v_mfma_f32_16x16x32_bf16 v[52:55], v[202:205], v[170:173], v[52:55]
	v_mfma_f32_16x16x32_bf16 v[48:51], v[242:245], v[170:173], v[48:51]
	v_mfma_f32_16x16x32_bf16 v[36:39], v[202:205], v[178:181], v[36:39]
	v_mfma_f32_16x16x32_bf16 v[32:35], v[242:245], v[178:181], v[32:35]
	v_mfma_f32_16x16x32_bf16 v[20:23], v[202:205], v[186:189], v[20:23]
	v_mfma_f32_16x16x32_bf16 v[16:19], v[242:245], v[186:189], v[16:19]
	v_mfma_f32_16x16x32_bf16 v[4:7], v[202:205], v[194:197], v[4:7]
	v_mfma_f32_16x16x32_bf16 v[0:3], v[242:245], v[194:197], v[0:3]
	v_mfma_f32_16x16x32_bf16 v[52:55], v[238:241], v[174:177], v[52:55]
	v_mfma_f32_16x16x32_bf16 v[48:51], v[246:249], v[174:177], v[48:51]
	v_mfma_f32_16x16x32_bf16 v[36:39], v[238:241], v[182:185], v[36:39]
	v_mfma_f32_16x16x32_bf16 v[32:35], v[246:249], v[182:185], v[32:35]
	v_mfma_f32_16x16x32_bf16 v[20:23], v[238:241], v[190:193], v[20:23]
	v_mfma_f32_16x16x32_bf16 v[16:19], v[246:249], v[190:193], v[16:19]
	v_mfma_f32_16x16x32_bf16 v[4:7], v[238:241], v[198:201], v[4:7]
	v_mfma_f32_16x16x32_bf16 v[0:3], v[246:249], v[198:201], v[0:3]
	s_setprio 0
	s_add_i32 s39, s39, 2
	s_add_u32 s26, s26, 0x100
	s_addc_u32 s27, s27, 0
	s_add_u32 s31, s31, 0x100
	s_addc_u32 s38, s38, 0
	s_cmp_gt_u32 s39, 29
	s_barrier
	s_cbranch_scc0 .LBB0_672
	s_mov_b64 s[26:27], -1
	s_cmp_gt_i32 s64, 35
	v_lshl_add_u32 v156, s46, 8, v162
	s_movk_i32 s95, 0x1ff
	s_cbranch_scc0 .LBB0_723
	s_and_b64 vcc, exec, s[52:53]
	s_cbranch_vccz .LBB0_678
	s_and_saveexec_b64 s[26:27], s[54:55]
	s_cbranch_execz .LBB0_677
	v_ashrrev_i32_e32 v157, 31, v156
	v_lshlrev_b64 v[128:129], 6, v[156:157]
	v_lshl_add_u64 v[128:129], v[144:145], 0, v[128:129]
	global_store_dwordx4 v[128:129], v[124:127], off offset:-256
	global_store_dwordx4 v[128:129], v[120:123], off offset:-240

; #define PG8_STAGE(bufoff, gbase, voff) do { _Pragma("unroll") for (int _i = 0; _i < 2; ++_i) \
;         __builtin_amdgcn_global_load_lds((const unsigned*)((const char*)(gbase) + (voff)[_i]), (LAS unsigned*)(lds + (bufoff) + ldsw + _i * 8192), 16, 0, 0); } while (0)
; #define PG8_LDA(dst, b, h) do { _Pragma("unroll") for (int m = 0; m < 4; ++m) _Pragma("unroll") for (int k = 0; k < 2; ++k) dst[m][k] = *(const LAS bf16x8*)(lds + PG8_SA(b, h) + aoff + m * 2048 + k * 1024); } while (0)
; #define PG8_LDB(dst, b, h) do { _Pragma("unroll") for (int n = 0; n < 2; ++n) _Pragma("unroll") for (int k = 0; k < 2; ++k) dst[n][k] = *(const LAS bf16x8*)(lds + PG8_SB(b, h) + boff + n * 2048 + k * 1024); } while (0)
; #define PG8_MMA(ai, bj, At, Bt) do { __builtin_amdgcn_s_setprio(1); _Pragma("unroll") for (int m = 0; m < 4; ++m) _Pragma("unroll") for (int n = 0; n < 2; ++n) _Pragma("unroll") for (int k = 0; k < 2; ++k) \
;         acc[ai][bj][m][n] = __builtin_amdgcn_mfma_f32_16x16x32_bf16(Bt[n][k], At[m][k], acc[ai][bj][m][n], 0, 0, 0); __builtin_amdgcn_s_setprio(0); } while (0)
; #define PG8_WAIT_L(n) asm volatile("s_waitcnt lgkmcnt(" #n ")" ::: "memory")
; #define PG8_BAR __builtin_amdgcn_s_barrier()
; #define PG8_SCHED __builtin_amdgcn_sched_barrier(0)
; template <class Epi>
; __device__ __forceinline__ void gemm_phase(LAS unsigned char* lds, const Gemm g, const Epi& E) {
;     ...
;             PG8_LDB(B0, 0, 0); PG8_SCHED; PG8_LDA(At, 0, 0); PG8_STAGE(PG8_SA(1, 1), a1 + hstep, voffA);
;             PG8_WAIT_L(8); PG8_BAR; PG8_WAIT_L(0); PG8_MMA(0, 0, At, B0); PG8_BAR; PG8_SCHED;
;             PG8_LDB(B1, 0, 1); PG8_STAGE(PG8_SB(0, 0), b2, voffB);
;             PG8_BAR; PG8_WAIT_L(0); PG8_MMA(0, 1, At, B1); PG8_BAR;
;             PG8_LDA(At, 0, 1); PG8_STAGE(PG8_SA(0, 0), a2, voffA);
;             PG8_BAR; PG8_WAIT_L(0); PG8_MMA(1, 0, At, B0); PG8_BAR; PG8_SCHED;
.LBB0_873:
	s_add_u32 s28, s26, 0x100
	s_addc_u32 s29, s27, 0
	s_add_i32 s34, 0, 0x10000
	v_add_u32_e32 v140, s34, v160
	ds_read_b128 v[128:131], v140
	ds_read_b128 v[132:135], v140 offset:1024
	ds_read_b128 v[136:139], v140 offset:2048
	ds_read_b128 v[140:143], v140 offset:3072
	s_cmpk_eq_i32 s82, 0x54
	s_cselect_b32 s39, s1, s29
	s_cselect_b32 s38, s0, s28
	s_cselect_b32 s37, s43, s79
	s_cselect_b32 s36, s42, s78
	v_lshl_add_u64 v[192:193], s[26:27], 0, v[152:153]
	s_add_i32 m0, s44, 0xc000
	ds_read_b128 v[156:159], v161
	ds_read_b128 v[164:167], v161 offset:1024
	ds_read_b128 v[168:171], v161 offset:2048
	ds_read_b128 v[172:175], v161 offset:3072
	ds_read_b128 v[176:179], v161 offset:4096
	ds_read_b128 v[180:183], v161 offset:5120
	ds_read_b128 v[184:187], v161 offset:6144
	ds_read_b128 v[188:191], v161 offset:7168
	global_load_lds_dwordx4 v[192:193], off
	s_add_i32 m0, s44, 0xe000
	v_lshl_add_u64 v[192:193], s[26:27], 0, v[154:155]
	global_load_lds_dwordx4 v[192:193], off
	s_waitcnt lgkmcnt(8)
	s_barrier
	s_waitcnt lgkmcnt(0)
	s_setprio 1
	v_mfma_f32_16x16x32_bf16 v[124:127], v[128:131], v[156:159], v[124:127]
	v_mfma_f32_16x16x32_bf16 v[120:123], v[136:139], v[156:159], v[120:123]
	v_mfma_f32_16x16x32_bf16 v[108:111], v[128:131], v[168:171], v[108:111]
	v_mfma_f32_16x16x32_bf16 v[104:107], v[136:139], v[168:171], v[104:107]
	v_mfma_f32_16x16x32_bf16 v[92:95], v[128:131], v[176:179], v[92:95]
	v_mfma_f32_16x16x32_bf16 v[88:91], v[136:139], v[176:179], v[88:91]
	v_mfma_f32_16x16x32_bf16 v[76:79], v[128:131], v[184:187], v[76:79]
	v_mfma_f32_16x16x32_bf16 v[72:75], v[136:139], v[184:187], v[72:75]
	v_mfma_f32_16x16x32_bf16 v[124:127], v[132:135], v[164:167], v[124:127]
	v_mfma_f32_16x16x32_bf16 v[120:123], v[140:143], v[164:167], v[120:123]
	v_mfma_f32_16x16x32_bf16 v[108:111], v[132:135], v[172:175], v[108:111]
	v_mfma_f32_16x16x32_bf16 v[104:107], v[140:143], v[172:175], v[104:107]
	v_mfma_f32_16x16x32_bf16 v[92:95], v[132:135], v[180:183], v[92:95]
	v_mfma_f32_16x16x32_bf16 v[88:91], v[140:143], v[180:183], v[88:91]
	v_mfma_f32_16x16x32_bf16 v[76:79], v[132:135], v[188:191], v[76:79]
	v_mfma_f32_16x16x32_bf16 v[72:75], v[140:143], v[188:191], v[72:75]
	s_setprio 0
	s_barrier
	s_add_i32 s35, 0, 0x14000
	s_add_i32 s26, s34, s31
	v_add_u32_e32 v163, s35, v160
	v_lshl_add_u64 v[220:221], s[36:37], 0, v[208:209]
	s_mov_b32 m0, s26
	ds_read_b128 v[192:195], v163
	ds_read_b128 v[196:199], v163 offset:1024
	ds_read_b128 v[200:203], v163 offset:2048
	ds_read_b128 v[204:207], v163 offset:3072
	global_load_lds_dwordx4 v[220:221], off
	s_add_i32 m0, s26, 0x2000
	v_lshl_add_u64 v[228:229], s[36:37], 0, v[148:149]
	global_load_lds_dwordx4 v[228:229], off
	s_barrier
	s_waitcnt lgkmcnt(0)
	s_setprio 1
	v_mfma_f32_16x16x32_bf16 v[116:119], v[192:195], v[156:159], v[116:119]
	v_mfma_f32_16x16x32_bf16 v[112:115], v[200:203], v[156:159], v[112:115]
	v_mfma_f32_16x16x32_bf16 v[100:103], v[192:195], v[168:171], v[100:103]
	v_mfma_f32_16x16x32_bf16 v[96:99], v[200:203], v[168:171], v[96:99]
	v_mfma_f32_16x16x32_bf16 v[84:87], v[192:195], v[176:179], v[84:87]
	v_mfma_f32_16x16x32_bf16 v[80:83], v[200:203], v[176:179], v[80:83]
	v_mfma_f32_16x16x32_bf16 v[68:71], v[192:195], v[184:187], v[68:71]
	v_mfma_f32_16x16x32_bf16 v[64:67], v[200:203], v[184:187], v[64:67]
	v_mfma_f32_16x16x32_bf16 v[116:119], v[196:199], v[164:167], v[116:119]
	v_mfma_f32_16x16x32_bf16 v[112:115], v[204:207], v[164:167], v[112:115]
	v_mfma_f32_16x16x32_bf16 v[100:103], v[196:199], v[172:175], v[100:103]
	v_mfma_f32_16x16x32_bf16 v[96:99], v[204:207], v[172:175], v[96:99]
	v_mfma_f32_16x16x32_bf16 v[84:87], v[196:199], v[180:183], v[84:87]
	v_mfma_f32_16x16x32_bf16 v[80:83], v[204:207], v[180:183], v[80:83]
	v_mfma_f32_16x16x32_bf16 v[68:71], v[196:199], v[188:191], v[68:71]
	v_mfma_f32_16x16x32_bf16 v[64:67], v[204:207], v[188:191], v[64:67]
	s_setprio 0
	s_mov_b32 m0, s44
	v_lshl_add_u64 v[230:231], s[38:39], 0, v[144:145]
	s_barrier
	ds_read_b128 v[156:159], v161 offset:16384
	ds_read_b128 v[164:167], v161 offset:17408
	ds_read_b128 v[168:171], v161 offset:18432
	ds_read_b128 v[172:175], v161 offset:19456
	ds_read_b128 v[176:179], v161 offset:20480
	ds_read_b128 v[180:183], v161 offset:21504
	ds_read_b128 v[184:187], v161 offset:22528
	ds_read_b128 v[188:191], v161 offset:23552
	global_load_lds_dwordx4 v[230:231], off
	s_mov_b32 m0, s45
	v_lshl_add_u64 v[232:233], s[38:39], 0, v[146:147]
	global_load_lds_dwordx4 v[232:233], off
	s_barrier
	s_waitcnt lgkmcnt(0)
	s_setprio 1
	v_mfma_f32_16x16x32_bf16 v[60:63], v[128:131], v[156:159], v[60:63]
	v_mfma_f32_16x16x32_bf16 v[56:59], v[136:139], v[156:159], v[56:59]
	v_mfma_f32_16x16x32_bf16 v[44:47], v[128:131], v[168:171], v[44:47]
	v_mfma_f32_16x16x32_bf16 v[40:43], v[136:139], v[168:171], v[40:43]
	v_mfma_f32_16x16x32_bf16 v[28:31], v[128:131], v[176:179], v[28:31]
	v_mfma_f32_16x16x32_bf16 v[24:27], v[136:139], v[176:179], v[24:27]
	v_mfma_f32_16x16x32_bf16 v[12:15], v[128:131], v[184:187], v[12:15]
	v_mfma_f32_16x16x32_bf16 v[8:11], v[136:139], v[184:187], v[8:11]
	v_mfma_f32_16x16x32_bf16 v[60:63], v[132:135], v[164:167], v[60:63]
	v_mfma_f32_16x16x32_bf16 v[56:59], v[140:143], v[164:167], v[56:59]
	v_mfma_f32_16x16x32_bf16 v[44:47], v[132:135], v[172:175], v[44:47]
	v_mfma_f32_16x16x32_bf16 v[40:43], v[140:143], v[172:175], v[40:43]
	v_mfma_f32_16x16x32_bf16 v[28:31], v[132:135], v[180:183], v[28:31]
	v_mfma_f32_16x16x32_bf16 v[24:27], v[140:143], v[180:183], v[24:27]
	v_mfma_f32_16x16x32_bf16 v[12:15], v[132:135], v[188:191], v[12:15]
	v_mfma_f32_16x16x32_bf16 v[8:11], v[140:143], v[188:191], v[8:11]
	s_setprio 0
	s_barrier
; #define PG8_STAGE(bufoff, gbase, voff) do { _Pragma("unroll") for (int _i = 0; _i < 2; ++_i) \
;         __builtin_amdgcn_global_load_lds((const unsigned*)((const char*)(gbase) + (voff)[_i]), (LAS unsigned*)(lds + (bufoff) + ldsw + _i * 8192), 16, 0, 0); } while (0)
; #define PG8_LDA(dst, b, h) do { _Pragma("unroll") for (int m = 0; m < 4; ++m) _Pragma("unroll") for (int k = 0; k < 2; ++k) dst[m][k] = *(const LAS bf16x8*)(lds + PG8_SA(b, h) + aoff + m * 2048 + k * 1024); } while (0)
; #define PG8_LDB(dst, b, h) do { _Pragma("unroll") for (int n = 0; n < 2; ++n) _Pragma("unroll") for (int k = 0; k < 2; ++k) dst[n][k] = *(const LAS bf16x8*)(lds + PG8_SB(b, h) + boff + n * 2048 + k * 1024); } while (0)
; #define PG8_MMA(ai, bj, At, Bt) do { __builtin_amdgcn_s_setprio(1); _Pragma("unroll") for (int m = 0; m < 4; ++m) _Pragma("unroll") for (int n = 0; n < 2; ++n) _Pragma("unroll") for (int k = 0; k < 2; ++k) \
;         acc[ai][bj][m][n] = __builtin_amdgcn_mfma_f32_16x16x32_bf16(Bt[n][k], At[m][k], acc[ai][bj][m][n], 0, 0, 0); __builtin_amdgcn_s_setprio(0); } while (0)
; #define PG8_WAIT_V(n) asm volatile("s_waitcnt vmcnt(" #n ")" ::: "memory")
; #define PG8_WAIT_L(n) asm volatile("s_waitcnt lgkmcnt(" #n ")" ::: "memory")
; #define PG8_BAR __builtin_amdgcn_s_barrier()
; #define PG8_SCHED __builtin_amdgcn_sched_barrier(0)
; template <class Epi>
; __device__ __forceinline__ void gemm_phase(LAS unsigned char* lds, const Gemm g, const Epi& E) {
;     ...
;             PG8_BAR; PG8_WAIT_L(0); PG8_MMA(1, 0, At, B0); PG8_BAR; PG8_SCHED;
;             PG8_STAGE(PG8_SB(0, 1), b2 + hstep, voffB);
;             PG8_WAIT_V(6); PG8_BAR; PG8_MMA(1, 1, At, B1); PG8_BAR;
;             PG8_LDB(B0, 1, 0); PG8_SCHED; PG8_LDA(At, 1, 0); PG8_STAGE(PG8_SA(0, 1), a2 + hstep, voffA);
;             PG8_WAIT_L(8); PG8_BAR; PG8_WAIT_L(0); PG8_MMA(0, 0, At, B0); PG8_BAR; PG8_SCHED;
;             PG8_LDB(B1, 1, 1); PG8_STAGE(PG8_SB(1, 0), b3, voffB);
;             PG8_BAR; PG8_WAIT_L(0); PG8_MMA(0, 1, At, B1); PG8_BAR;
;             PG8_LDA(At, 1, 1); PG8_STAGE(PG8_SA(1, 0), a3, voffA);
	s_add_u32 s26, s36, 0x160000
	s_addc_u32 s27, s37, 0
	s_add_i32 s34, s35, s31
	s_mov_b32 m0, s34
	v_lshl_add_u64 v[128:129], s[26:27], 0, v[208:209]
	global_load_lds_dwordx4 v[128:129], off
	s_add_i32 m0, s34, 0x2000
	v_lshl_add_u64 v[128:129], s[26:27], 0, v[148:149]
	global_load_lds_dwordx4 v[128:129], off
	s_waitcnt vmcnt(6)
	s_barrier
	s_setprio 1
	v_mfma_f32_16x16x32_bf16 v[52:55], v[192:195], v[156:159], v[52:55]
	v_mfma_f32_16x16x32_bf16 v[48:51], v[200:203], v[156:159], v[48:51]
	v_mfma_f32_16x16x32_bf16 v[36:39], v[192:195], v[168:171], v[36:39]
	v_mfma_f32_16x16x32_bf16 v[32:35], v[200:203], v[168:171], v[32:35]
	v_mfma_f32_16x16x32_bf16 v[20:23], v[192:195], v[176:179], v[20:23]
	v_mfma_f32_16x16x32_bf16 v[16:19], v[200:203], v[176:179], v[16:19]
	v_mfma_f32_16x16x32_bf16 v[4:7], v[192:195], v[184:187], v[4:7]
	v_mfma_f32_16x16x32_bf16 v[0:3], v[200:203], v[184:187], v[0:3]
	v_mfma_f32_16x16x32_bf16 v[52:55], v[196:199], v[164:167], v[52:55]
	v_mfma_f32_16x16x32_bf16 v[48:51], v[204:207], v[164:167], v[48:51]
	v_mfma_f32_16x16x32_bf16 v[36:39], v[196:199], v[172:175], v[36:39]
	v_mfma_f32_16x16x32_bf16 v[32:35], v[204:207], v[172:175], v[32:35]
	v_mfma_f32_16x16x32_bf16 v[20:23], v[196:199], v[180:183], v[20:23]
	v_mfma_f32_16x16x32_bf16 v[16:19], v[204:207], v[180:183], v[16:19]
	v_mfma_f32_16x16x32_bf16 v[4:7], v[196:199], v[188:191], v[4:7]
	v_mfma_f32_16x16x32_bf16 v[0:3], v[204:207], v[188:191], v[0:3]
	s_setprio 0
	s_add_i32 s34, 0, 0x18000
	v_add_u32_e32 v140, s34, v160
	s_barrier
	ds_read_b128 v[128:131], v140
	ds_read_b128 v[132:135], v140 offset:1024
	ds_read_b128 v[136:139], v140 offset:2048
	ds_read_b128 v[140:143], v140 offset:3072
	s_add_u32 s26, s38, 0x160000
	s_addc_u32 s27, s39, 0
	s_mov_b32 m0, s46
	v_lshl_add_u64 v[192:193], s[26:27], 0, v[144:145]
	ds_read_b128 v[156:159], v161 offset:32768
	ds_read_b128 v[164:167], v161 offset:33792
	ds_read_b128 v[168:171], v161 offset:34816
	ds_read_b128 v[172:175], v161 offset:35840
	ds_read_b128 v[176:179], v161 offset:36864
	ds_read_b128 v[180:183], v161 offset:37888
	ds_read_b128 v[184:187], v161 offset:38912
	ds_read_b128 v[188:191], v161 offset:39936
	global_load_lds_dwordx4 v[192:193], off
	s_mov_b32 m0, s47
	v_lshl_add_u64 v[192:193], s[26:27], 0, v[146:147]
	global_load_lds_dwordx4 v[192:193], off
	s_waitcnt lgkmcnt(8)
	s_barrier
	s_waitcnt lgkmcnt(0)
	s_setprio 1
	v_mfma_f32_16x16x32_bf16 v[124:127], v[128:131], v[156:159], v[124:127]
	v_mfma_f32_16x16x32_bf16 v[120:123], v[136:139], v[156:159], v[120:123]
	v_mfma_f32_16x16x32_bf16 v[108:111], v[128:131], v[168:171], v[108:111]
	v_mfma_f32_16x16x32_bf16 v[104:107], v[136:139], v[168:171], v[104:107]
	v_mfma_f32_16x16x32_bf16 v[92:95], v[128:131], v[176:179], v[92:95]
	v_mfma_f32_16x16x32_bf16 v[88:91], v[136:139], v[176:179], v[88:91]
	v_mfma_f32_16x16x32_bf16 v[76:79], v[128:131], v[184:187], v[76:79]
	v_mfma_f32_16x16x32_bf16 v[72:75], v[136:139], v[184:187], v[72:75]
	v_mfma_f32_16x16x32_bf16 v[124:127], v[132:135], v[164:167], v[124:127]
	v_mfma_f32_16x16x32_bf16 v[120:123], v[140:143], v[164:167], v[120:123]
	v_mfma_f32_16x16x32_bf16 v[108:111], v[132:135], v[172:175], v[108:111]
	v_mfma_f32_16x16x32_bf16 v[104:107], v[140:143], v[172:175], v[104:107]
	v_mfma_f32_16x16x32_bf16 v[92:95], v[132:135], v[180:183], v[92:95]
	v_mfma_f32_16x16x32_bf16 v[88:91], v[140:143], v[180:183], v[88:91]
	v_mfma_f32_16x16x32_bf16 v[76:79], v[132:135], v[188:191], v[76:79]
	v_mfma_f32_16x16x32_bf16 v[72:75], v[140:143], v[188:191], v[72:75]
	s_setprio 0
	s_barrier
	s_add_i32 s35, 0, 0x1c000
	s_add_i32 s26, s34, s31
	v_add_u32_e32 v163, s35, v160
	v_lshl_add_u64 v[220:221], v[220:221], 0, s[20:21]
	s_mov_b32 m0, s26
	ds_read_b128 v[192:195], v163
	ds_read_b128 v[196:199], v163 offset:1024
	ds_read_b128 v[200:203], v163 offset:2048
	ds_read_b128 v[204:207], v163 offset:3072
	global_load_lds_dwordx4 v[220:221], off
	s_add_i32 m0, s26, 0x2000
	v_lshl_add_u64 v[220:221], v[228:229], 0, s[20:21]
	global_load_lds_dwordx4 v[220:221], off
	s_barrier
	s_waitcnt lgkmcnt(0)
	s_setprio 1
	v_mfma_f32_16x16x32_bf16 v[116:119], v[192:195], v[156:159], v[116:119]
	v_mfma_f32_16x16x32_bf16 v[112:115], v[200:203], v[156:159], v[112:115]
	v_mfma_f32_16x16x32_bf16 v[100:103], v[192:195], v[168:171], v[100:103]
	v_mfma_f32_16x16x32_bf16 v[96:99], v[200:203], v[168:171], v[96:99]
	v_mfma_f32_16x16x32_bf16 v[84:87], v[192:195], v[176:179], v[84:87]
	v_mfma_f32_16x16x32_bf16 v[80:83], v[200:203], v[176:179], v[80:83]
	v_mfma_f32_16x16x32_bf16 v[68:71], v[192:195], v[184:187], v[68:71]
	v_mfma_f32_16x16x32_bf16 v[64:67], v[200:203], v[184:187], v[64:67]
	v_mfma_f32_16x16x32_bf16 v[116:119], v[196:199], v[164:167], v[116:119]
	v_mfma_f32_16x16x32_bf16 v[112:115], v[204:207], v[164:167], v[112:115]
	v_mfma_f32_16x16x32_bf16 v[100:103], v[196:199], v[172:175], v[100:103]
	v_mfma_f32_16x16x32_bf16 v[96:99], v[204:207], v[172:175], v[96:99]
	v_mfma_f32_16x16x32_bf16 v[84:87], v[196:199], v[180:183], v[84:87]
	v_mfma_f32_16x16x32_bf16 v[80:83], v[204:207], v[180:183], v[80:83]
	v_mfma_f32_16x16x32_bf16 v[68:71], v[196:199], v[188:191], v[68:71]
	v_mfma_f32_16x16x32_bf16 v[64:67], v[204:207], v[188:191], v[64:67]
	s_setprio 0
	s_mov_b32 m0, s64
	v_lshl_add_u64 v[220:221], v[230:231], 0, s[20:21]
	s_barrier
	ds_read_b128 v[156:159], v161 offset:49152
	ds_read_b128 v[164:167], v161 offset:50176
	ds_read_b128 v[168:171], v161 offset:51200
	ds_read_b128 v[172:175], v161 offset:52224
	ds_read_b128 v[176:179], v161 offset:53248
	ds_read_b128 v[180:183], v161 offset:54272
	ds_read_b128 v[184:187], v161 offset:55296
	ds_read_b128 v[188:191], v161 offset:56320
	global_load_lds_dwordx4 v[220:221], off
	s_mov_b32 m0, s65
	v_lshl_add_u64 v[220:221], v[232:233], 0, s[20:21]
	global_load_lds_dwordx4 v[220:221], off
	s_barrier
; __device__ __forceinline__ float bflo(unsigned w) { return __uint_as_float(w << 16); }
; __device__ __forceinline__ float bfhi(unsigned w) { return __uint_as_float(w & 0xffff0000u); }
; __device__ __forceinline__ u32x4 pack8u(f32x4 a, f32x4 b) { u32x4 w = {cvt_pk_bf16(a[0], a[1]), cvt_pk_bf16(a[2], a[3]), cvt_pk_bf16(b[0], b[1]), cvt_pk_bf16(b[2], b[3])}; return w; }
; #define PG8_STAGE(bufoff, gbase, voff) do { _Pragma("unroll") for (int _i = 0; _i < 2; ++_i) \
;         __builtin_amdgcn_global_load_lds((const unsigned*)((const char*)(gbase) + (voff)[_i]), (LAS unsigned*)(lds + (bufoff) + ldsw + _i * 8192), 16, 0, 0); } while (0)
; #define PG8_WAIT_V(n) asm volatile("s_waitcnt vmcnt(" #n ")" ::: "memory")
; template <class Epi>
; __device__ __forceinline__ void gemm_phase(LAS unsigned char* lds, const Gemm g, const Epi& E) {
;     ...
;             PG8_LDA(At, 1, 1); PG8_STAGE(PG8_SA(1, 0), a3, voffA);
;             PG8_BAR; PG8_WAIT_L(0); PG8_MMA(1, 0, At, B0); PG8_BAR; PG8_SCHED;
;             PG8_STAGE(PG8_SB(1, 1), b3 + hstep, voffB);
;             PG8_WAIT_V(6); PG8_BAR; PG8_MMA(1, 1, At, B1); PG8_BAR;
;     __device__ __forceinline__ void operator()(const AccT& acc, const Unit& u, int wr, int wc, int fr, int fq) const {
;         const int b = (u.pm * 256) / SEQ;
;         f32x4 gt[2][2];
; #pragma unroll
;         for (int bj = 0; bj < 2; ++bj)
; #pragma unroll
;             for (int n = 0; n < 2; ++n) gt[bj][n] = *(const f32x4*)(GT + (size_t)b * 6 * D + u.pn * 256 + bj * 128 + wc * 32 + fq * 8 + 4 * n);
; #pragma unroll
;         for (int ai = 0; ai < 2; ++ai)
; #pragma unroll
;             for (int m = 0; m < 4; ++m) {
;                 const int row = u.pm * 256 + ai * 128 + wr * 64 + m * 16 + fr;
; #pragma unroll
;                 for (int bj = 0; bj < 2; ++bj) {
;                     const size_t off = (size_t)row * D + u.pn * 256 + bj * 128 + wc * 32 + fq * 8;
;                     f32x4 x0, x1;
;                     if (XINF) { x0 = *(const f32x4*)(XINF + off); x1 = *(const f32x4*)(XINF + off + 4); }
;                     else { const u32x4 w = *(const u32x4*)(XIN16 + off); x0 = (f32x4){bflo(w[0]), bfhi(w[0]), bflo(w[1]), bfhi(w[1])}; x1 = (f32x4){bflo(w[2]), bfhi(w[2]), bflo(w[3]), bfhi(w[3])}; }
;                     *(u32x4*)(XOUT + off) = pack8u(x0 + gt[bj][0] * acc[ai][bj][m][0], x1 + gt[bj][1] * acc[ai][bj][m][1]);
	s_waitcnt lgkmcnt(0)
	s_setprio 1
	v_mfma_f32_16x16x32_bf16 v[60:63], v[128:131], v[156:159], v[60:63]
	v_mfma_f32_16x16x32_bf16 v[56:59], v[136:139], v[156:159], v[56:59]
	v_mfma_f32_16x16x32_bf16 v[44:47], v[128:131], v[168:171], v[44:47]
	v_mfma_f32_16x16x32_bf16 v[40:43], v[136:139], v[168:171], v[40:43]
	v_mfma_f32_16x16x32_bf16 v[28:31], v[128:131], v[176:179], v[28:31]
	v_mfma_f32_16x16x32_bf16 v[24:27], v[136:139], v[176:179], v[24:27]
	v_mfma_f32_16x16x32_bf16 v[12:15], v[128:131], v[184:187], v[12:15]
	v_mfma_f32_16x16x32_bf16 v[8:11], v[136:139], v[184:187], v[8:11]
	v_mfma_f32_16x16x32_bf16 v[60:63], v[132:135], v[164:167], v[60:63]
	v_mfma_f32_16x16x32_bf16 v[56:59], v[140:143], v[164:167], v[56:59]
	v_mfma_f32_16x16x32_bf16 v[44:47], v[132:135], v[172:175], v[44:47]
	v_mfma_f32_16x16x32_bf16 v[40:43], v[140:143], v[172:175], v[40:43]
	v_mfma_f32_16x16x32_bf16 v[28:31], v[132:135], v[180:183], v[28:31]
	v_mfma_f32_16x16x32_bf16 v[24:27], v[140:143], v[180:183], v[24:27]
	v_mfma_f32_16x16x32_bf16 v[12:15], v[132:135], v[188:191], v[12:15]
	v_mfma_f32_16x16x32_bf16 v[8:11], v[140:143], v[188:191], v[8:11]
	s_setprio 0
	s_barrier
	s_add_u32 s26, s36, 0x160080
	s_addc_u32 s27, s37, 0
	s_add_i32 s34, s35, s31
	s_mov_b32 m0, s34
	v_lshl_add_u64 v[128:129], s[26:27], 0, v[208:209]
	global_load_lds_dwordx4 v[128:129], off
	s_add_i32 m0, s34, 0x2000
	v_lshl_add_u64 v[128:129], s[26:27], 0, v[148:149]
	global_load_lds_dwordx4 v[128:129], off
	s_waitcnt vmcnt(6)
	s_barrier
	s_setprio 1
	v_mfma_f32_16x16x32_bf16 v[52:55], v[192:195], v[156:159], v[52:55]
	v_mfma_f32_16x16x32_bf16 v[48:51], v[200:203], v[156:159], v[48:51]
	v_mfma_f32_16x16x32_bf16 v[36:39], v[192:195], v[168:171], v[36:39]
	v_mfma_f32_16x16x32_bf16 v[32:35], v[200:203], v[168:171], v[32:35]
	v_mfma_f32_16x16x32_bf16 v[20:23], v[192:195], v[176:179], v[20:23]
	v_mfma_f32_16x16x32_bf16 v[16:19], v[200:203], v[176:179], v[16:19]
	v_mfma_f32_16x16x32_bf16 v[4:7], v[192:195], v[184:187], v[4:7]
	v_mfma_f32_16x16x32_bf16 v[0:3], v[200:203], v[184:187], v[0:3]
	v_mfma_f32_16x16x32_bf16 v[52:55], v[196:199], v[164:167], v[52:55]
	v_mfma_f32_16x16x32_bf16 v[48:51], v[204:207], v[164:167], v[48:51]
	v_mfma_f32_16x16x32_bf16 v[36:39], v[196:199], v[172:175], v[36:39]
	v_mfma_f32_16x16x32_bf16 v[32:35], v[204:207], v[172:175], v[32:35]
	v_mfma_f32_16x16x32_bf16 v[20:23], v[196:199], v[180:183], v[20:23]
	v_mfma_f32_16x16x32_bf16 v[16:19], v[204:207], v[180:183], v[16:19]
	v_mfma_f32_16x16x32_bf16 v[4:7], v[196:199], v[188:191], v[4:7]
	v_mfma_f32_16x16x32_bf16 v[0:3], v[204:207], v[188:191], v[0:3]
	s_setprio 0
	s_add_i32 s82, s82, 2
	s_add_u32 s78, s78, 0x100
	s_addc_u32 s79, s79, 0
	s_cmpk_gt_u32 s82, 0x55
	s_mov_b64 s[26:27], s[28:29]
	s_barrier
	s_cbranch_scc0 .LBB0_873
	s_ashr_i32 s26, s74, 31
	s_lshr_b32 s26, s26, 29
	s_add_i32 s26, s74, s26
	s_ashr_i32 s26, s26, 3
	s_mul_i32 s26, s26, 6
	s_ashr_i32 s27, s26, 31
	s_lshl_b64 s[26:27], s[26:27], 13
	s_add_u32 s28, s48, s26
	s_addc_u32 s29, s49, s27
	s_lshl_b32 s26, s76, 8
	s_ashr_i32 s27, s26, 31
	v_lshl_add_u32 v157, s74, 8, v151
	v_or_b32_e32 v158, s26, v150
	s_lshl_b64 s[26:27], s[26:27], 2
	s_add_u32 s26, s28, s26
	s_addc_u32 s27, s29, s27
	s_add_u32 s26, s26, s69
	s_addc_u32 s27, s27, 0
	global_load_dwordx4 v[140:143], v162, s[26:27]
	global_load_dwordx4 v[136:139], v162, s[26:27] offset:16
	global_load_dwordx4 v[132:135], v162, s[26:27] offset:512
	global_load_dwordx4 v[128:131], v162, s[26:27] offset:528
	v_lshlrev_b32_e32 v156, 1, v158
	v_lshl_add_u32 v156, v157, 12, v156
	v_add_u32_e32 v157, 0x0, v156
	global_load_dwordx4 v[164:167], v157, s[96:97] offset:0
	v_add_u32_e32 v157, 0x0, v156
	global_load_dwordx4 v[168:171], v157, s[96:97] offset:256
	v_add_u32_e32 v157, 0x10000, v156
	global_load_dwordx4 v[172:175], v157, s[96:97] offset:0
	v_add_u32_e32 v157, 0x10000, v156
	global_load_dwordx4 v[184:187], v157, s[96:97] offset:256
	v_add_u32_e32 v157, 0x20000, v156
	global_load_dwordx4 v[188:191], v157, s[96:97] offset:0
	v_add_u32_e32 v157, 0x20000, v156
	global_load_dwordx4 v[192:195], v157, s[96:97] offset:256
	v_add_u32_e32 v157, 0x30000, v156
	global_load_dwordx4 v[196:199], v157, s[96:97] offset:0
	v_add_u32_e32 v157, 0x30000, v156
	global_load_dwordx4 v[200:203], v157, s[96:97] offset:256
	v_add_u32_e32 v157, 0x80000, v156
	global_load_dwordx4 v[204:207], v157, s[96:97] offset:0
	v_add_u32_e32 v157, 0x80000, v156
	global_load_dwordx4 v[228:231], v157, s[96:97] offset:256
	s_waitcnt vmcnt(9)
	v_lshlrev_b32_e32 v176, 16, v164
	v_and_b32_e32 v177, 0xffff0000, v164
	v_lshlrev_b32_e32 v178, 16, v165
	v_and_b32_e32 v179, 0xffff0000, v165
	v_lshlrev_b32_e32 v180, 16, v166
	v_and_b32_e32 v181, 0xffff0000, v166
	v_lshlrev_b32_e32 v182, 16, v167
	v_and_b32_e32 v183, 0xffff0000, v167
	v_pk_fma_f32 v[124:125], v[124:125], v[140:141], v[176:177]
	v_pk_fma_f32 v[126:127], v[126:127], v[142:143], v[178:179]
	v_pk_fma_f32 v[120:121], v[120:121], v[136:137], v[180:181]
	v_pk_fma_f32 v[122:123], v[122:123], v[138:139], v[182:183]
	v_cvt_pk_bf16_f32 v124, v124, v125
	v_cvt_pk_bf16_f32 v125, v126, v127
	v_cvt_pk_bf16_f32 v126, v120, v121
	v_cvt_pk_bf16_f32 v127, v122, v123
	v_add_u32_e32 v158, 0x0, v156
	global_store_dwordx4 v158, v[124:127], s[96:97] offset:0
	v_add_u32_e32 v157, 0x90000, v156
	global_load_dwordx4 v[164:167], v157, s[96:97] offset:0
	v_add_u32_e32 v157, 0x90000, v156
	global_load_dwordx4 v[120:123], v157, s[96:97] offset:256
	s_waitcnt vmcnt(11)
; __device__ __forceinline__ float bflo(unsigned w) { return __uint_as_float(w << 16); }
; __device__ __forceinline__ float bfhi(unsigned w) { return __uint_as_float(w & 0xffff0000u); }
; __device__ __forceinline__ u32x4 pack8u(f32x4 a, f32x4 b) { u32x4 w = {cvt_pk_bf16(a[0], a[1]), cvt_pk_bf16(a[2], a[3]), cvt_pk_bf16(b[0], b[1]), cvt_pk_bf16(b[2], b[3])}; return w; }
;     __device__ __forceinline__ void operator()(const AccT& acc, const Unit& u, int wr, int wc, int fr, int fq) const {
;     ...
;                 for (int bj = 0; bj < 2; ++bj) {
;                     const size_t off = (size_t)row * D + u.pn * 256 + bj * 128 + wc * 32 + fq * 8;
;                     f32x4 x0, x1;
;                     if (XINF) { x0 = *(const f32x4*)(XINF + off); x1 = *(const f32x4*)(XINF + off + 4); }
;                     else { const u32x4 w = *(const u32x4*)(XIN16 + off); x0 = (f32x4){bflo(w[0]), bfhi(w[0]), bflo(w[1]), bfhi(w[1])}; x1 = (f32x4){bflo(w[2]), bfhi(w[2]), bflo(w[3]), bfhi(w[3])}; }
;                     *(u32x4*)(XOUT + off) = pack8u(x0 + gt[bj][0] * acc[ai][bj][m][0], x1 + gt[bj][1] * acc[ai][bj][m][1]);
	v_lshlrev_b32_e32 v176, 16, v168
	v_and_b32_e32 v177, 0xffff0000, v168
	v_lshlrev_b32_e32 v178, 16, v169
	v_and_b32_e32 v179, 0xffff0000, v169
	v_lshlrev_b32_e32 v180, 16, v170
	v_and_b32_e32 v181, 0xffff0000, v170
	v_lshlrev_b32_e32 v182, 16, v171
	v_and_b32_e32 v183, 0xffff0000, v171
	v_pk_fma_f32 v[116:117], v[116:117], v[132:133], v[176:177]
	v_pk_fma_f32 v[118:119], v[118:119], v[134:135], v[178:179]
	v_pk_fma_f32 v[112:113], v[112:113], v[128:129], v[180:181]
	v_pk_fma_f32 v[114:115], v[114:115], v[130:131], v[182:183]
	v_cvt_pk_bf16_f32 v116, v116, v117
	v_cvt_pk_bf16_f32 v117, v118, v119
	v_cvt_pk_bf16_f32 v118, v112, v113
	v_cvt_pk_bf16_f32 v119, v114, v115
	v_add_u32_e32 v158, 0x0, v156
	global_store_dwordx4 v158, v[116:119], s[96:97] offset:256
	v_add_u32_e32 v157, 0xa0000, v156
	global_load_dwordx4 v[168:171], v157, s[96:97] offset:0
	v_add_u32_e32 v157, 0xa0000, v156
	global_load_dwordx4 v[112:115], v157, s[96:97] offset:256
	s_waitcnt vmcnt(13)
	v_lshlrev_b32_e32 v176, 16, v172
	v_and_b32_e32 v177, 0xffff0000, v172
	v_lshlrev_b32_e32 v178, 16, v173
	v_and_b32_e32 v179, 0xffff0000, v173
	v_lshlrev_b32_e32 v180, 16, v174
	v_and_b32_e32 v181, 0xffff0000, v174
	v_lshlrev_b32_e32 v182, 16, v175
	v_and_b32_e32 v183, 0xffff0000, v175
	v_pk_fma_f32 v[108:109], v[108:109], v[140:141], v[176:177]
	v_pk_fma_f32 v[110:111], v[110:111], v[142:143], v[178:179]
	v_pk_fma_f32 v[104:105], v[104:105], v[136:137], v[180:181]
	v_pk_fma_f32 v[106:107], v[106:107], v[138:139], v[182:183]
	v_cvt_pk_bf16_f32 v108, v108, v109
	v_cvt_pk_bf16_f32 v109, v110, v111
	v_cvt_pk_bf16_f32 v110, v104, v105
	v_cvt_pk_bf16_f32 v111, v106, v107
	v_add_u32_e32 v158, 0x10000, v156
	global_store_dwordx4 v158, v[108:111], s[96:97] offset:0
	v_add_u32_e32 v157, 0xb0000, v156
	global_load_dwordx4 v[172:175], v157, s[96:97] offset:0
	v_add_u32_e32 v157, 0xb0000, v156
	global_load_dwordx4 v[104:107], v157, s[96:97] offset:256
	s_waitcnt vmcnt(15)
	v_lshlrev_b32_e32 v176, 16, v184
	v_and_b32_e32 v177, 0xffff0000, v184
	v_lshlrev_b32_e32 v178, 16, v185
	v_and_b32_e32 v179, 0xffff0000, v185
	v_lshlrev_b32_e32 v180, 16, v186
	v_and_b32_e32 v181, 0xffff0000, v186
	v_lshlrev_b32_e32 v182, 16, v187
	v_and_b32_e32 v183, 0xffff0000, v187
	v_pk_fma_f32 v[100:101], v[100:101], v[132:133], v[176:177]
	v_pk_fma_f32 v[102:103], v[102:103], v[134:135], v[178:179]
	v_pk_fma_f32 v[96:97], v[96:97], v[128:129], v[180:181]
	v_pk_fma_f32 v[98:99], v[98:99], v[130:131], v[182:183]
	v_cvt_pk_bf16_f32 v100, v100, v101
	v_cvt_pk_bf16_f32 v101, v102, v103
	v_cvt_pk_bf16_f32 v102, v96, v97
	v_cvt_pk_bf16_f32 v103, v98, v99
	v_add_u32_e32 v158, 0x10000, v156
	global_store_dwordx4 v158, v[100:103], s[96:97] offset:256
	s_waitcnt vmcnt(15)
	v_lshlrev_b32_e32 v176, 16, v188
	v_and_b32_e32 v177, 0xffff0000, v188
	v_lshlrev_b32_e32 v178, 16, v189
	v_and_b32_e32 v179, 0xffff0000, v189
	v_lshlrev_b32_e32 v180, 16, v190
	v_and_b32_e32 v181, 0xffff0000, v190
	v_lshlrev_b32_e32 v182, 16, v191
	v_and_b32_e32 v183, 0xffff0000, v191
	v_pk_fma_f32 v[92:93], v[92:93], v[140:141], v[176:177]
	v_pk_fma_f32 v[94:95], v[94:95], v[142:143], v[178:179]
	v_pk_fma_f32 v[88:89], v[88:89], v[136:137], v[180:181]
	v_pk_fma_f32 v[90:91], v[90:91], v[138:139], v[182:183]
	v_cvt_pk_bf16_f32 v92, v92, v93
	v_cvt_pk_bf16_f32 v93, v94, v95
	v_cvt_pk_bf16_f32 v94, v88, v89
	v_cvt_pk_bf16_f32 v95, v90, v91
	v_add_u32_e32 v158, 0x20000, v156
	global_store_dwordx4 v158, v[92:95], s[96:97] offset:0
	s_waitcnt vmcnt(15)
	v_lshlrev_b32_e32 v176, 16, v192
	v_and_b32_e32 v177, 0xffff0000, v192
	v_lshlrev_b32_e32 v178, 16, v193
	v_and_b32_e32 v179, 0xffff0000, v193
	v_lshlrev_b32_e32 v180, 16, v194
	v_and_b32_e32 v181, 0xffff0000, v194
	v_lshlrev_b32_e32 v182, 16, v195
	v_and_b32_e32 v183, 0xffff0000, v195
	v_pk_fma_f32 v[84:85], v[84:85], v[132:133], v[176:177]
	v_pk_fma_f32 v[86:87], v[86:87], v[134:135], v[178:179]
	v_pk_fma_f32 v[80:81], v[80:81], v[128:129], v[180:181]
	v_pk_fma_f32 v[82:83], v[82:83], v[130:131], v[182:183]
	v_cvt_pk_bf16_f32 v84, v84, v85
	v_cvt_pk_bf16_f32 v85, v86, v87
	v_cvt_pk_bf16_f32 v86, v80, v81
	v_cvt_pk_bf16_f32 v87, v82, v83
	v_add_u32_e32 v158, 0x20000, v156
	global_store_dwordx4 v158, v[84:87], s[96:97] offset:256
	s_waitcnt vmcnt(15)
	v_lshlrev_b32_e32 v176, 16, v196
	v_and_b32_e32 v177, 0xffff0000, v196
	v_lshlrev_b32_e32 v178, 16, v197
	v_and_b32_e32 v179, 0xffff0000, v197
	v_lshlrev_b32_e32 v180, 16, v198
	v_and_b32_e32 v181, 0xffff0000, v198
	v_lshlrev_b32_e32 v182, 16, v199
	v_and_b32_e32 v183, 0xffff0000, v199
	v_pk_fma_f32 v[76:77], v[76:77], v[140:141], v[176:177]
	v_pk_fma_f32 v[78:79], v[78:79], v[142:143], v[178:179]
	v_pk_fma_f32 v[72:73], v[72:73], v[136:137], v[180:181]
	v_pk_fma_f32 v[74:75], v[74:75], v[138:139], v[182:183]
	v_cvt_pk_bf16_f32 v76, v76, v77
	v_cvt_pk_bf16_f32 v77, v78, v79
	v_cvt_pk_bf16_f32 v78, v72, v73
	v_cvt_pk_bf16_f32 v79, v74, v75
	v_add_u32_e32 v158, 0x30000, v156
	global_store_dwordx4 v158, v[76:79], s[96:97] offset:0
	s_waitcnt vmcnt(15)
	v_lshlrev_b32_e32 v176, 16, v200
	v_and_b32_e32 v177, 0xffff0000, v200
	v_lshlrev_b32_e32 v178, 16, v201
	v_and_b32_e32 v179, 0xffff0000, v201
	v_lshlrev_b32_e32 v180, 16, v202
	v_and_b32_e32 v181, 0xffff0000, v202
	v_lshlrev_b32_e32 v182, 16, v203
	v_and_b32_e32 v183, 0xffff0000, v203
	v_pk_fma_f32 v[68:69], v[68:69], v[132:133], v[176:177]
	v_pk_fma_f32 v[70:71], v[70:71], v[134:135], v[178:179]
	v_pk_fma_f32 v[64:65], v[64:65], v[128:129], v[180:181]
	v_pk_fma_f32 v[66:67], v[66:67], v[130:131], v[182:183]
	v_cvt_pk_bf16_f32 v68, v68, v69
	v_cvt_pk_bf16_f32 v69, v70, v71
	v_cvt_pk_bf16_f32 v70, v64, v65
	v_cvt_pk_bf16_f32 v71, v66, v67
	v_add_u32_e32 v158, 0x30000, v156
	global_store_dwordx4 v158, v[68:71], s[96:97] offset:256
	s_waitcnt vmcnt(15)
; __device__ __forceinline__ float bflo(unsigned w) { return __uint_as_float(w << 16); }
; __device__ __forceinline__ float bfhi(unsigned w) { return __uint_as_float(w & 0xffff0000u); }
; __device__ __forceinline__ u32x4 pack8u(f32x4 a, f32x4 b) { u32x4 w = {cvt_pk_bf16(a[0], a[1]), cvt_pk_bf16(a[2], a[3]), cvt_pk_bf16(b[0], b[1]), cvt_pk_bf16(b[2], b[3])}; return w; }
; #define PG8_WAIT_V(n) asm volatile("s_waitcnt vmcnt(" #n ")" ::: "memory")
; #define PG8_BAR __builtin_amdgcn_s_barrier()
; template <class Epi>
; __device__ __forceinline__ void gemm_phase(LAS unsigned char* lds, const Gemm g, const Epi& E) {
;     ...
;         E(acc, cur, wr, wc, fr, fq);
;         if (!has_next) break;
; #pragma unroll
;         for (int a = 0; a < 2; ++a)
; #pragma unroll
;             for (int b = 0; b < 2; ++b)
; #pragma unroll
;                 for (int m = 0; m < 4; ++m)
; #pragma unroll
;                     for (int n = 0; n < 2; ++n) acc[a][b][m][n] = (f32x4){0.f, 0.f, 0.f, 0.f};
;         cur = nxt; cA = nA; cB = nB; ++ui;
;     }
;     PG8_WAIT_V(0);
;     if (wr == 0) PG8_BAR;
;     PG8_BAR;
;     __device__ __forceinline__ void operator()(const AccT& acc, const Unit& u, int wr, int wc, int fr, int fq) const {
;     ...
;                 for (int bj = 0; bj < 2; ++bj) {
;                     const size_t off = (size_t)row * D + u.pn * 256 + bj * 128 + wc * 32 + fq * 8;
;                     f32x4 x0, x1;
;                     if (XINF) { x0 = *(const f32x4*)(XINF + off); x1 = *(const f32x4*)(XINF + off + 4); }
;                     else { const u32x4 w = *(const u32x4*)(XIN16 + off); x0 = (f32x4){bflo(w[0]), bfhi(w[0]), bflo(w[1]), bfhi(w[1])}; x1 = (f32x4){bflo(w[2]), bfhi(w[2]), bflo(w[3]), bfhi(w[3])}; }
;                     *(u32x4*)(XOUT + off) = pack8u(x0 + gt[bj][0] * acc[ai][bj][m][0], x1 + gt[bj][1] * acc[ai][bj][m][1]);
	v_lshlrev_b32_e32 v176, 16, v204
	v_and_b32_e32 v177, 0xffff0000, v204
	v_lshlrev_b32_e32 v178, 16, v205
	v_and_b32_e32 v179, 0xffff0000, v205
	v_lshlrev_b32_e32 v180, 16, v206
	v_and_b32_e32 v181, 0xffff0000, v206
	v_lshlrev_b32_e32 v182, 16, v207
	v_and_b32_e32 v183, 0xffff0000, v207
	v_pk_fma_f32 v[60:61], v[60:61], v[140:141], v[176:177]
	v_pk_fma_f32 v[62:63], v[62:63], v[142:143], v[178:179]
	v_pk_fma_f32 v[56:57], v[56:57], v[136:137], v[180:181]
	v_pk_fma_f32 v[58:59], v[58:59], v[138:139], v[182:183]
	v_cvt_pk_bf16_f32 v60, v60, v61
	v_cvt_pk_bf16_f32 v61, v62, v63
	v_cvt_pk_bf16_f32 v62, v56, v57
	v_cvt_pk_bf16_f32 v63, v58, v59
	v_add_u32_e32 v158, 0x80000, v156
	global_store_dwordx4 v158, v[60:63], s[96:97] offset:0
	s_waitcnt vmcnt(15)
	v_lshlrev_b32_e32 v176, 16, v228
	v_and_b32_e32 v177, 0xffff0000, v228
	v_lshlrev_b32_e32 v178, 16, v229
	v_and_b32_e32 v179, 0xffff0000, v229
	v_lshlrev_b32_e32 v180, 16, v230
	v_and_b32_e32 v181, 0xffff0000, v230
	v_lshlrev_b32_e32 v182, 16, v231
	v_and_b32_e32 v183, 0xffff0000, v231
	v_pk_fma_f32 v[52:53], v[52:53], v[132:133], v[176:177]
	v_pk_fma_f32 v[54:55], v[54:55], v[134:135], v[178:179]
	v_pk_fma_f32 v[48:49], v[48:49], v[128:129], v[180:181]
	v_pk_fma_f32 v[50:51], v[50:51], v[130:131], v[182:183]
	v_cvt_pk_bf16_f32 v52, v52, v53
	v_cvt_pk_bf16_f32 v53, v54, v55
	v_cvt_pk_bf16_f32 v54, v48, v49
	v_cvt_pk_bf16_f32 v55, v50, v51
	v_add_u32_e32 v158, 0x80000, v156
	global_store_dwordx4 v158, v[52:55], s[96:97] offset:256
	s_waitcnt vmcnt(14)
	v_lshlrev_b32_e32 v176, 16, v164
	v_and_b32_e32 v177, 0xffff0000, v164
	v_lshlrev_b32_e32 v178, 16, v165
	v_and_b32_e32 v179, 0xffff0000, v165
	v_lshlrev_b32_e32 v180, 16, v166
	v_and_b32_e32 v181, 0xffff0000, v166
	v_lshlrev_b32_e32 v182, 16, v167
	v_and_b32_e32 v183, 0xffff0000, v167
	v_pk_fma_f32 v[44:45], v[44:45], v[140:141], v[176:177]
	v_pk_fma_f32 v[46:47], v[46:47], v[142:143], v[178:179]
	v_pk_fma_f32 v[40:41], v[40:41], v[136:137], v[180:181]
	v_pk_fma_f32 v[42:43], v[42:43], v[138:139], v[182:183]
	v_cvt_pk_bf16_f32 v44, v44, v45
	v_cvt_pk_bf16_f32 v45, v46, v47
	v_cvt_pk_bf16_f32 v46, v40, v41
	v_cvt_pk_bf16_f32 v47, v42, v43
	v_add_u32_e32 v158, 0x90000, v156
	global_store_dwordx4 v158, v[44:47], s[96:97] offset:0
	s_waitcnt vmcnt(14)
	v_lshlrev_b32_e32 v176, 16, v120
	v_and_b32_e32 v177, 0xffff0000, v120
	v_lshlrev_b32_e32 v178, 16, v121
	v_and_b32_e32 v179, 0xffff0000, v121
	v_lshlrev_b32_e32 v180, 16, v122
	v_and_b32_e32 v181, 0xffff0000, v122
	v_lshlrev_b32_e32 v182, 16, v123
	v_and_b32_e32 v183, 0xffff0000, v123
	v_pk_fma_f32 v[36:37], v[36:37], v[132:133], v[176:177]
	v_pk_fma_f32 v[38:39], v[38:39], v[134:135], v[178:179]
	v_pk_fma_f32 v[32:33], v[32:33], v[128:129], v[180:181]
	v_pk_fma_f32 v[34:35], v[34:35], v[130:131], v[182:183]
	v_cvt_pk_bf16_f32 v36, v36, v37
	v_cvt_pk_bf16_f32 v37, v38, v39
	v_cvt_pk_bf16_f32 v38, v32, v33
	v_cvt_pk_bf16_f32 v39, v34, v35
	v_add_u32_e32 v158, 0x90000, v156
	global_store_dwordx4 v158, v[36:39], s[96:97] offset:256
	s_waitcnt vmcnt(13)
	v_lshlrev_b32_e32 v176, 16, v168
	v_and_b32_e32 v177, 0xffff0000, v168
	v_lshlrev_b32_e32 v178, 16, v169
	v_and_b32_e32 v179, 0xffff0000, v169
	v_lshlrev_b32_e32 v180, 16, v170
	v_and_b32_e32 v181, 0xffff0000, v170
	v_lshlrev_b32_e32 v182, 16, v171
	v_and_b32_e32 v183, 0xffff0000, v171
	v_pk_fma_f32 v[28:29], v[28:29], v[140:141], v[176:177]
	v_pk_fma_f32 v[30:31], v[30:31], v[142:143], v[178:179]
	v_pk_fma_f32 v[24:25], v[24:25], v[136:137], v[180:181]
	v_pk_fma_f32 v[26:27], v[26:27], v[138:139], v[182:183]
	v_cvt_pk_bf16_f32 v28, v28, v29
	v_cvt_pk_bf16_f32 v29, v30, v31
	v_cvt_pk_bf16_f32 v30, v24, v25
	v_cvt_pk_bf16_f32 v31, v26, v27
	v_add_u32_e32 v158, 0xa0000, v156
	global_store_dwordx4 v158, v[28:31], s[96:97] offset:0
	s_waitcnt vmcnt(13)
	v_lshlrev_b32_e32 v176, 16, v112
	v_and_b32_e32 v177, 0xffff0000, v112
	v_lshlrev_b32_e32 v178, 16, v113
	v_and_b32_e32 v179, 0xffff0000, v113
	v_lshlrev_b32_e32 v180, 16, v114
	v_and_b32_e32 v181, 0xffff0000, v114
	v_lshlrev_b32_e32 v182, 16, v115
	v_and_b32_e32 v183, 0xffff0000, v115
	v_pk_fma_f32 v[20:21], v[20:21], v[132:133], v[176:177]
	v_pk_fma_f32 v[22:23], v[22:23], v[134:135], v[178:179]
	v_pk_fma_f32 v[16:17], v[16:17], v[128:129], v[180:181]
	v_pk_fma_f32 v[18:19], v[18:19], v[130:131], v[182:183]
	v_cvt_pk_bf16_f32 v20, v20, v21
	v_cvt_pk_bf16_f32 v21, v22, v23
	v_cvt_pk_bf16_f32 v22, v16, v17
	v_cvt_pk_bf16_f32 v23, v18, v19
	v_add_u32_e32 v158, 0xa0000, v156
	global_store_dwordx4 v158, v[20:23], s[96:97] offset:256
	s_waitcnt vmcnt(12)
	v_lshlrev_b32_e32 v176, 16, v172
	v_and_b32_e32 v177, 0xffff0000, v172
	v_lshlrev_b32_e32 v178, 16, v173
	v_and_b32_e32 v179, 0xffff0000, v173
	v_lshlrev_b32_e32 v180, 16, v174
	v_and_b32_e32 v181, 0xffff0000, v174
	v_lshlrev_b32_e32 v182, 16, v175
	v_and_b32_e32 v183, 0xffff0000, v175
	v_pk_fma_f32 v[12:13], v[12:13], v[140:141], v[176:177]
	v_pk_fma_f32 v[14:15], v[14:15], v[142:143], v[178:179]
	v_pk_fma_f32 v[8:9], v[8:9], v[136:137], v[180:181]
	v_pk_fma_f32 v[10:11], v[10:11], v[138:139], v[182:183]
	v_cvt_pk_bf16_f32 v12, v12, v13
	v_cvt_pk_bf16_f32 v13, v14, v15
	v_cvt_pk_bf16_f32 v14, v8, v9
	v_cvt_pk_bf16_f32 v15, v10, v11
	v_add_u32_e32 v158, 0xb0000, v156
	global_store_dwordx4 v158, v[12:15], s[96:97] offset:0
	s_waitcnt vmcnt(12)
	v_lshlrev_b32_e32 v176, 16, v104
	v_and_b32_e32 v177, 0xffff0000, v104
	v_lshlrev_b32_e32 v178, 16, v105
	v_and_b32_e32 v179, 0xffff0000, v105
	v_lshlrev_b32_e32 v180, 16, v106
	v_and_b32_e32 v181, 0xffff0000, v106
	v_lshlrev_b32_e32 v182, 16, v107
	v_and_b32_e32 v183, 0xffff0000, v107
	v_pk_fma_f32 v[4:5], v[4:5], v[132:133], v[176:177]
	v_pk_fma_f32 v[6:7], v[6:7], v[134:135], v[178:179]
	v_pk_fma_f32 v[0:1], v[0:1], v[128:129], v[180:181]
	v_pk_fma_f32 v[2:3], v[2:3], v[130:131], v[182:183]
	v_cvt_pk_bf16_f32 v4, v4, v5
	v_cvt_pk_bf16_f32 v5, v6, v7
	v_cvt_pk_bf16_f32 v6, v0, v1
	v_cvt_pk_bf16_f32 v7, v2, v3
	v_add_u32_e32 v158, 0xb0000, v156
	global_store_dwordx4 v158, v[4:7], s[96:97] offset:256
	s_mov_b64 s[28:29], s[42:43]
	s_mov_b64 s[26:27], s[0:1]
	s_mov_b32 s74, s71
	s_mov_b32 s76, s70
	s_and_b64 vcc, exec, s[40:41]
	v_readlane_b32 s82, v255, 24
	v_readlane_b32 s83, v255, 25
	s_cbranch_vccz .LBB0_862
	s_waitcnt vmcnt(0)
	s_cmpk_gt_u32 s3, 0xff
	s_cbranch_scc1 .LBB0_877
	s_barrier
